# hand-written EpiAB (gate loads of a half tile in flight), layer-0 XN stores dropped
# speedup vs baseline: 1.0452x; 1.0058x over previous
; __device__ __forceinline__ unsigned cvt_pk_bf16(float lo, float hi) { unsigned r; asm volatile("v_cvt_pk_bf16_f32 %0, %1, %2" : "=v"(r) : "v"(lo), "v"(hi)); return r; }
; __device__ __forceinline__ float bflo(unsigned w) { return __uint_as_float(w << 16); }
; __device__ __forceinline__ float bfhi(unsigned w) { return __uint_as_float(w & 0xffff0000u); }
; __device__ __forceinline__ void norm_phase(KP p, bool first, int nslab) {
;     ...
;         f32x4 v[4]; float s = 0.f;
;         if (first) { const f32x4* xr = (const f32x4*)src_row(p, m) + lane;
; #pragma unroll
;             for (int j = 0; j < 4; ++j) v[j] = __builtin_nontemporal_load(xr + 64 * j); }
;         else { const u32x2* xr = (const u32x2*)(X + (size_t)m * D) + lane;
; #pragma unroll
;             for (int j = 0; j < 4; ++j) { const u32x2 w = __builtin_nontemporal_load(xr + 64 * j); v[j] = (f32x4){bflo(w.x), bfhi(w.x), bflo(w.y), bfhi(w.y)}; } }
;         const bool fold = (!first) && m >= 64 * 256;
;         if (fold) { const f32x4* sl = (const f32x4*)(p->ws + WS_SLAB) + (size_t)(m - 64 * 256) * (D / 4) + lane;
;             for (int q = 0; q < nslab; ++q) {
; #pragma unroll
;                 for (int j = 0; j < 4; ++j) v[j] += sl[(size_t)q * 256 * (D / 4) + 64 * j]; } }
;         if (first || fold) { u32x2* xo = (u32x2*)(X + (size_t)m * D) + lane;
; #pragma unroll
;             for (int j = 0; j < 4; ++j) { u32x2 w; w.x = cvt_pk_bf16(v[j][0], v[j][1]); w.y = cvt_pk_bf16(v[j][2], v[j][3]); xo[64 * j] = w; } }
; #pragma unroll
;         for (int j = 0; j < 4; ++j) s += (v[j][0] * v[j][0] + v[j][1] * v[j][1]) + (v[j][2] * v[j][2] + v[j][3] * v[j][3]);
;         const float rinv = rsqrtf(wave_sum(s) * (1.f / D) + EPS);
;         u32x2* o8 = (u32x2*)(XN + (size_t)m * D) + lane;
; #pragma unroll
;         for (int j = 0; j < 4; ++j) { u32x2 w; w.x = cvt_pk_bf16(v[j][0] * rinv, v[j][1] * rinv); w.y = cvt_pk_bf16(v[j][2] * rinv, v[j][3] * rinv); o8[64 * j] = w; }
.LBB0_60:
	s_waitcnt vmcnt(3)
	v_mov_b32_e32 v18, v16
	v_mov_b32_e32 v19, v14
	v_mov_b32_e32 v20, v17
	v_mov_b32_e32 v21, v15
	s_waitcnt vmcnt(2)
	v_mov_b32_e32 v22, v8
	v_mov_b32_e32 v23, v6
	v_pk_mul_f32 v[18:19], v[18:19], v[18:19]
	v_mov_b32_e32 v24, v9
	v_mov_b32_e32 v25, v7
	v_pk_fma_f32 v[18:19], v[20:21], v[20:21], v[18:19]
	v_pk_mul_f32 v[20:21], v[22:23], v[22:23]
	v_pk_add_f32 v[18:19], v[18:19], v[18:19] op_sel_hi:[0,1]
	v_pk_fma_f32 v[20:21], v[24:25], v[24:25], v[20:21]
	s_waitcnt vmcnt(1)
	v_mul_f32_e32 v18, v10, v10
	v_pk_add_f32 v[20:21], v[20:21], v[20:21] op_sel_hi:[0,1]
	v_mul_f32_e32 v25, v12, v12
	v_mul_f32_e32 v27, v13, v13
	s_waitcnt vmcnt(0)
	v_mov_b32_e32 v26, v5
	v_mov_b32_e32 v24, v5
	v_pk_fma_f32 v[22:23], v[10:11], v[10:11], v[18:19] op_sel_hi:[1,1,0]
	v_mul_f32_e32 v18, v2, v2
	v_mul_f32_e32 v20, v3, v3
	v_pk_add_f32 v[24:25], v[26:27], v[24:25]
	v_mul_f32_e32 v22, v4, v4
	v_pk_add_f32 v[18:19], v[20:21], v[18:19]
	v_mul_f32_e32 v20, v5, v5
	v_mov_b32_e32 v21, v25
	v_pk_add_f32 v[20:21], v[20:21], v[22:23]
	s_add_i32 s34, s34, 1
	v_pk_add_f32 v[18:19], v[20:21], v[18:19]
	v_xor_b32_e32 v20, 1, v207
	v_add_f32_e32 v18, v18, v19
	v_and_b32_e32 v19, 64, v207
	v_add_u32_e32 v19, 64, v19
	v_cmp_lt_i32_e32 vcc, v20, v19
	s_addk_i32 s24, 0x100
	s_add_i32 s25, s25, s19
	v_cndmask_b32_e32 v20, v207, v20, vcc
	v_lshlrev_b32_e32 v20, 2, v20
	ds_bpermute_b32 v20, v20, v18
	s_cmpk_eq_i32 s24, 0x900
	s_waitcnt lgkmcnt(0)
	v_add_f32_e32 v18, v18, v20
	v_xor_b32_e32 v20, 2, v207
	v_cmp_lt_i32_e32 vcc, v20, v19
	s_nop 1
	v_cndmask_b32_e32 v20, v207, v20, vcc
	v_lshlrev_b32_e32 v20, 2, v20
	ds_bpermute_b32 v20, v20, v18
	s_waitcnt lgkmcnt(0)
	v_add_f32_e32 v18, v18, v20
	v_xor_b32_e32 v20, 4, v207
	v_cmp_lt_i32_e32 vcc, v20, v19
	s_nop 1
	v_cndmask_b32_e32 v20, v207, v20, vcc
	v_lshlrev_b32_e32 v20, 2, v20
	ds_bpermute_b32 v20, v20, v18
	s_waitcnt lgkmcnt(0)
	v_add_f32_e32 v18, v18, v20
	v_xor_b32_e32 v20, 8, v207
	v_cmp_lt_i32_e32 vcc, v20, v19
	s_nop 1
	v_cndmask_b32_e32 v20, v207, v20, vcc
	v_lshlrev_b32_e32 v20, 2, v20
	ds_bpermute_b32 v20, v20, v18
	s_waitcnt lgkmcnt(0)
	v_add_f32_e32 v18, v18, v20
	v_xor_b32_e32 v20, 16, v207
	v_cmp_lt_i32_e32 vcc, v20, v19
	s_nop 1
	v_cndmask_b32_e32 v20, v207, v20, vcc
	v_lshlrev_b32_e32 v20, 2, v20
	ds_bpermute_b32 v20, v20, v18
	s_waitcnt lgkmcnt(0)
	v_add_f32_e32 v18, v18, v20
	v_xor_b32_e32 v20, 32, v207
	v_cmp_lt_i32_e32 vcc, v20, v19
	s_nop 1
	v_cndmask_b32_e32 v19, v207, v20, vcc
	v_lshlrev_b32_e32 v19, 2, v19
	ds_bpermute_b32 v19, v19, v18
	s_waitcnt lgkmcnt(0)
	v_add_f32_e32 v18, v18, v19
	v_fmamk_f32 v18, v18, 0x3a800000, v213
	v_mul_f32_e32 v19, 0x4b800000, v18
	v_cmp_gt_f32_e32 vcc, s43, v18
	s_nop 1
	v_cndmask_b32_e32 v18, v18, v19, vcc
	v_rsq_f32_e32 v18, v18
	s_nop 0
	v_mul_f32_e32 v19, 0x45800000, v18
	v_cndmask_b32_e32 v20, v18, v19, vcc
	v_readfirstlane_b32 s44, v110
	v_readfirstlane_b32 s45, v111
	s_mul_hi_u32 s16, s60, 0x800000
	v_mov_b32_e32 v30, s16
	v_add_u32_e32 v30, 0x4620000, v30
	s_nop 2
	global_store_dword v30, v20, s[44:45]
	v_mul_f32_e32 v14, v14, v20
	v_mul_f32_e32 v15, v15, v20
	v_lshl_add_u64 v[18:19], v[110:111], 0, s[60:61]
	v_cvt_pk_bf16_f32 v14, v14, v15
	v_mul_f32_e32 v15, v16, v20
	v_mul_f32_e32 v6, v6, v20
	v_mul_f32_e32 v7, v7, v20
	v_mul_f32_e32 v16, v17, v20
	v_cvt_pk_bf16_f32 v15, v15, v16
	v_cvt_pk_bf16_f32 v6, v6, v7
	v_mul_f32_e32 v7, v8, v20
	v_mul_f32_e32 v8, v9, v20
	v_cvt_pk_bf16_f32 v7, v7, v8
	v_mul_f32_e32 v6, v10, v20
	v_mul_f32_e32 v7, v11, v20
	v_cvt_pk_bf16_f32 v6, v6, v7
	v_mul_f32_e32 v7, v12, v20
	v_mul_f32_e32 v2, v2, v20
	v_mul_f32_e32 v3, v3, v20
	v_mul_f32_e32 v8, v13, v20
	v_cvt_pk_bf16_f32 v7, v7, v8
	v_cvt_pk_bf16_f32 v2, v2, v3
	v_mul_f32_e32 v3, v4, v20
	s_cselect_b64 s[60:61], -1, 0
	v_mul_f32_e32 v4, v5, v20
	v_cvt_pk_bf16_f32 v3, v3, v4

; __device__ __forceinline__ u32x4 pack8(const float (&f)[8]) { u32x4 o; o.x = cvt_pk_bf16(f[0], f[1]); o.y = cvt_pk_bf16(f[2], f[3]); o.z = cvt_pk_bf16(f[4], f[5]); o.w = cvt_pk_bf16(f[6], f[7]); return o; }
; __device__ __forceinline__ float sigmoidf_(float x) { return __builtin_amdgcn_rcpf(1.0f + __expf(-x)); }
;     __device__ __forceinline__ void operator()(const f32x4 (&acc)[2][2][4][2], const Unit& u, int wr, int wc, int fr, int fq) const {
;         const int row0 = u.pm * BM + wr * 64 + fr, col0 = u.pn * BM + wc * 32 + 8 * fq;
;         const bool split = u.nkt != ntFull;
;         const int goff = (split && u.z == 0) ? C_MA : C_MB;
;         float* S0 = SLAB + (size_t)((u.kt0 >> 2) * 2 + u.z) * 256 * D;
; #pragma unroll
;         for (int ai = 0; ai < 2; ++ai)
; #pragma unroll
;             for (int m = 0; m < 4; ++m) { const size_t r = (size_t)(row0 + ai * HALF + m * 16); bf16_t* prow = P + r * DP;
;                 float* srow = S0 + (size_t)(wr * 64 + fr + ai * HALF + m * 16) * D;
; #pragma unroll
;                 for (int bj = 0; bj < 2; ++bj) { const int c = col0 + bj * HALF;
;                     const u32x4 gw = *(const u32x4*)(prow + goff + c); float g[8]; unpack8(gw, g);
;                     const f32x4 v0 = acc[ai][bj][m][0], v1 = acc[ai][bj][m][1];
;                     float o[8];
; #pragma unroll
;                     for (int e = 0; e < 4; ++e) { o[e] = sigmoidf_(g[e]) * v0[e]; o[4 + e] = sigmoidf_(g[4 + e]) * v1[e]; }
;                     if (split) store8f(srow + c, o); else *(u32x4*)(prow + C_MIX + c) = pack8(o); }
;                 asm volatile("" ::: "memory"); }
.LBB0_513:
	s_or_b32 s5, s16, s4
	s_cmp_eq_u32 s16, 0
	s_cselect_b64 s[54:55], -1, 0
	s_cmp_lg_u32 s5, 0
	s_cselect_b64 s[24:25], -1, 0
	s_cmp_eq_u32 s19, 16
	s_cselect_b64 s[68:69], -1, 0
	s_cmp_lg_u32 s19, 16
	s_cselect_b64 s[70:71], -1, 0
	s_or_b64 s[64:65], s[24:25], s[70:71]
	s_lshl_b32 s15, s18, 8
	s_mov_b64 s[72:73], -1
	s_and_b64 vcc, exec, s[64:65]
	s_cbranch_vccz .Lab_mid
	v_add_u32_e32 v0, s15, v148
	v_mul_lo_u32 v0, v0, s33
	v_lshl_or_b32 v3, s66, 8, v149
	v_lshl_add_u32 v0, v3, 1, v0
	s_and_b64 vcc, exec, s[70:71]
	s_cbranch_vccnz .Lab_split
	s_add_u32 s68, s8, 0x2000
	s_addc_u32 s69, s9, 0
	s_add_u32 s72, s8, 0x1000
	s_addc_u32 s73, s9, 0
	global_load_dwordx4 v[180:183], v0, s[68:69]
	global_load_dwordx4 v[184:187], v0, s[68:69] offset:256
	s_add_u32 s68, s68, 0x28000
	s_addc_u32 s69, s69, 0
	global_load_dwordx4 v[188:191], v0, s[68:69]
	global_load_dwordx4 v[192:195], v0, s[68:69] offset:256
	s_add_u32 s68, s68, 0x28000
	s_addc_u32 s69, s69, 0
	global_load_dwordx4 v[196:199], v0, s[68:69]
	global_load_dwordx4 v[200:203], v0, s[68:69] offset:256
	s_add_u32 s68, s68, 0x28000
	s_addc_u32 s69, s69, 0
	global_load_dwordx4 v[224:227], v0, s[68:69]
	global_load_dwordx4 v[228:231], v0, s[68:69] offset:256
	s_add_u32 s68, s68, 0xc8000
	s_addc_u32 s69, s69, 0
	global_load_dwordx4 v[232:235], v0, s[68:69]
	global_load_dwordx4 v[236:239], v0, s[68:69] offset:256
	s_add_u32 s68, s68, 0x28000
	s_addc_u32 s69, s69, 0
	global_load_dwordx4 v[240:243], v0, s[68:69]
	global_load_dwordx4 v[244:247], v0, s[68:69] offset:256
	s_add_u32 s68, s68, 0x28000
	s_addc_u32 s69, s69, 0
	global_load_dwordx4 v[248:251], v0, s[68:69]
	global_load_dwordx4 v[132:135], v0, s[68:69] offset:256
	s_add_u32 s68, s68, 0x28000
	s_addc_u32 s69, s69, 0
	global_load_dwordx4 v[136:139], v0, s[68:69]
	global_load_dwordx4 v[170:173], v0, s[68:69] offset:256
	s_waitcnt vmcnt(15)
	v_lshlrev_b32_e32 v174, 16, v180
	v_lshlrev_b32_e32 v175, 16, v181
	v_lshlrev_b32_e32 v176, 16, v182
	v_lshlrev_b32_e32 v177, 16, v183
	v_and_b32_e32 v180, 0xffff0000, v180
	v_and_b32_e32 v181, 0xffff0000, v181
	v_and_b32_e32 v182, 0xffff0000, v182
	v_and_b32_e32 v183, 0xffff0000, v183
	v_mul_f32_e32 v174, 0xbfb8aa3b, v174
	v_mul_f32_e32 v180, 0xbfb8aa3b, v180
	v_mul_f32_e32 v175, 0xbfb8aa3b, v175
	v_mul_f32_e32 v181, 0xbfb8aa3b, v181
	v_mul_f32_e32 v176, 0xbfb8aa3b, v176
	v_mul_f32_e32 v182, 0xbfb8aa3b, v182
	v_mul_f32_e32 v177, 0xbfb8aa3b, v177
	v_mul_f32_e32 v183, 0xbfb8aa3b, v183
	v_exp_f32_e32 v174, v174
	v_exp_f32_e32 v180, v180
	v_exp_f32_e32 v175, v175
	v_exp_f32_e32 v181, v181
	v_exp_f32_e32 v176, v176
	v_exp_f32_e32 v182, v182
	v_exp_f32_e32 v177, v177
	v_exp_f32_e32 v183, v183
	v_add_f32_e32 v174, 1.0, v174
	v_add_f32_e32 v180, 1.0, v180
	v_add_f32_e32 v175, 1.0, v175
	v_add_f32_e32 v181, 1.0, v181
	v_add_f32_e32 v176, 1.0, v176
	v_add_f32_e32 v182, 1.0, v182
	v_add_f32_e32 v177, 1.0, v177
	v_add_f32_e32 v183, 1.0, v183
	v_rcp_f32_e32 v174, v174
	v_rcp_f32_e32 v180, v180
	v_rcp_f32_e32 v175, v175
	v_rcp_f32_e32 v181, v181
	v_rcp_f32_e32 v176, v176
	v_rcp_f32_e32 v182, v182
	v_rcp_f32_e32 v177, v177
	v_rcp_f32_e32 v183, v183
	v_mul_f32_e32 v128, v174, v128
	v_mul_f32_e32 v129, v180, v129
	v_mul_f32_e32 v130, v175, v130
	v_mul_f32_e32 v131, v181, v131
	v_mul_f32_e32 v124, v176, v124
	v_mul_f32_e32 v125, v182, v125
	v_mul_f32_e32 v126, v177, v126
	v_mul_f32_e32 v127, v183, v127
	v_cvt_pk_bf16_f32 v180, v128, v129
	v_cvt_pk_bf16_f32 v181, v130, v131
	v_cvt_pk_bf16_f32 v182, v124, v125
	v_cvt_pk_bf16_f32 v183, v126, v127
	global_store_dwordx4 v0, v[180:183], s[72:73]
	s_waitcnt vmcnt(15)
	v_lshlrev_b32_e32 v174, 16, v184
	v_lshlrev_b32_e32 v175, 16, v185
	v_lshlrev_b32_e32 v176, 16, v186
	v_lshlrev_b32_e32 v177, 16, v187
	v_and_b32_e32 v184, 0xffff0000, v184
	v_and_b32_e32 v185, 0xffff0000, v185
	v_and_b32_e32 v186, 0xffff0000, v186
	v_and_b32_e32 v187, 0xffff0000, v187
	v_mul_f32_e32 v174, 0xbfb8aa3b, v174
	v_mul_f32_e32 v184, 0xbfb8aa3b, v184
	v_mul_f32_e32 v175, 0xbfb8aa3b, v175
	v_mul_f32_e32 v185, 0xbfb8aa3b, v185
	v_mul_f32_e32 v176, 0xbfb8aa3b, v176
	v_mul_f32_e32 v186, 0xbfb8aa3b, v186
	v_mul_f32_e32 v177, 0xbfb8aa3b, v177
	v_mul_f32_e32 v187, 0xbfb8aa3b, v187
	v_exp_f32_e32 v174, v174
	v_exp_f32_e32 v184, v184
	v_exp_f32_e32 v175, v175
	v_exp_f32_e32 v185, v185
	v_exp_f32_e32 v176, v176
	v_exp_f32_e32 v186, v186
	v_exp_f32_e32 v177, v177
	v_exp_f32_e32 v187, v187
	v_add_f32_e32 v174, 1.0, v174
	v_add_f32_e32 v184, 1.0, v184
	v_add_f32_e32 v175, 1.0, v175
	v_add_f32_e32 v185, 1.0, v185
	v_add_f32_e32 v176, 1.0, v176
	v_add_f32_e32 v186, 1.0, v186
	v_add_f32_e32 v177, 1.0, v177
	v_add_f32_e32 v187, 1.0, v187
	v_rcp_f32_e32 v174, v174
	v_rcp_f32_e32 v184, v184
	v_rcp_f32_e32 v175, v175
	v_rcp_f32_e32 v185, v185
	v_rcp_f32_e32 v176, v176
	v_rcp_f32_e32 v186, v186
	v_rcp_f32_e32 v177, v177
	v_rcp_f32_e32 v187, v187
	v_mul_f32_e32 v96, v174, v96
	v_mul_f32_e32 v97, v184, v97
	v_mul_f32_e32 v98, v175, v98
	v_mul_f32_e32 v99, v185, v99
	v_mul_f32_e32 v92, v176, v92
	v_mul_f32_e32 v93, v186, v93
	v_mul_f32_e32 v94, v177, v94
	v_mul_f32_e32 v95, v187, v95
	v_cvt_pk_bf16_f32 v184, v96, v97
	v_cvt_pk_bf16_f32 v185, v98, v99
	v_cvt_pk_bf16_f32 v186, v92, v93
	v_cvt_pk_bf16_f32 v187, v94, v95
	global_store_dwordx4 v0, v[184:187], s[72:73] offset:256
	s_add_u32 s72, s72, 0x28000
	s_addc_u32 s73, s73, 0
	s_waitcnt vmcnt(15)
; __device__ __forceinline__ u32x4 pack8(const float (&f)[8]) { u32x4 o; o.x = cvt_pk_bf16(f[0], f[1]); o.y = cvt_pk_bf16(f[2], f[3]); o.z = cvt_pk_bf16(f[4], f[5]); o.w = cvt_pk_bf16(f[6], f[7]); return o; }
; __device__ __forceinline__ float sigmoidf_(float x) { return __builtin_amdgcn_rcpf(1.0f + __expf(-x)); }
;     __device__ __forceinline__ void operator()(const f32x4 (&acc)[2][2][4][2], const Unit& u, int wr, int wc, int fr, int fq) const {
;         const int row0 = u.pm * BM + wr * 64 + fr, col0 = u.pn * BM + wc * 32 + 8 * fq;
;         const bool split = u.nkt != ntFull;
;         const int goff = (split && u.z == 0) ? C_MA : C_MB;
;         float* S0 = SLAB + (size_t)((u.kt0 >> 2) * 2 + u.z) * 256 * D;
; #pragma unroll
;         for (int ai = 0; ai < 2; ++ai)
; #pragma unroll
;             for (int m = 0; m < 4; ++m) { const size_t r = (size_t)(row0 + ai * HALF + m * 16); bf16_t* prow = P + r * DP;
;                 float* srow = S0 + (size_t)(wr * 64 + fr + ai * HALF + m * 16) * D;
; #pragma unroll
;                 for (int bj = 0; bj < 2; ++bj) { const int c = col0 + bj * HALF;
;                     const u32x4 gw = *(const u32x4*)(prow + goff + c); float g[8]; unpack8(gw, g);
;                     const f32x4 v0 = acc[ai][bj][m][0], v1 = acc[ai][bj][m][1];
;                     float o[8];
; #pragma unroll
;                     for (int e = 0; e < 4; ++e) { o[e] = sigmoidf_(g[e]) * v0[e]; o[4 + e] = sigmoidf_(g[4 + e]) * v1[e]; }
;                     if (split) store8f(srow + c, o); else *(u32x4*)(prow + C_MIX + c) = pack8(o); }
;                 asm volatile("" ::: "memory"); }
	v_lshlrev_b32_e32 v174, 16, v188
	v_lshlrev_b32_e32 v175, 16, v189
	v_lshlrev_b32_e32 v176, 16, v190
	v_lshlrev_b32_e32 v177, 16, v191
	v_and_b32_e32 v188, 0xffff0000, v188
	v_and_b32_e32 v189, 0xffff0000, v189
	v_and_b32_e32 v190, 0xffff0000, v190
	v_and_b32_e32 v191, 0xffff0000, v191
	v_mul_f32_e32 v174, 0xbfb8aa3b, v174
	v_mul_f32_e32 v188, 0xbfb8aa3b, v188
	v_mul_f32_e32 v175, 0xbfb8aa3b, v175
	v_mul_f32_e32 v189, 0xbfb8aa3b, v189
	v_mul_f32_e32 v176, 0xbfb8aa3b, v176
	v_mul_f32_e32 v190, 0xbfb8aa3b, v190
	v_mul_f32_e32 v177, 0xbfb8aa3b, v177
	v_mul_f32_e32 v191, 0xbfb8aa3b, v191
	v_exp_f32_e32 v174, v174
	v_exp_f32_e32 v188, v188
	v_exp_f32_e32 v175, v175
	v_exp_f32_e32 v189, v189
	v_exp_f32_e32 v176, v176
	v_exp_f32_e32 v190, v190
	v_exp_f32_e32 v177, v177
	v_exp_f32_e32 v191, v191
	v_add_f32_e32 v174, 1.0, v174
	v_add_f32_e32 v188, 1.0, v188
	v_add_f32_e32 v175, 1.0, v175
	v_add_f32_e32 v189, 1.0, v189
	v_add_f32_e32 v176, 1.0, v176
	v_add_f32_e32 v190, 1.0, v190
	v_add_f32_e32 v177, 1.0, v177
	v_add_f32_e32 v191, 1.0, v191
	v_rcp_f32_e32 v174, v174
	v_rcp_f32_e32 v188, v188
	v_rcp_f32_e32 v175, v175
	v_rcp_f32_e32 v189, v189
	v_rcp_f32_e32 v176, v176
	v_rcp_f32_e32 v190, v190
	v_rcp_f32_e32 v177, v177
	v_rcp_f32_e32 v191, v191
	v_mul_f32_e32 v120, v174, v120
	v_mul_f32_e32 v121, v188, v121
	v_mul_f32_e32 v122, v175, v122
	v_mul_f32_e32 v123, v189, v123
	v_mul_f32_e32 v116, v176, v116
	v_mul_f32_e32 v117, v190, v117
	v_mul_f32_e32 v118, v177, v118
	v_mul_f32_e32 v119, v191, v119
	v_cvt_pk_bf16_f32 v188, v120, v121
	v_cvt_pk_bf16_f32 v189, v122, v123
	v_cvt_pk_bf16_f32 v190, v116, v117
	v_cvt_pk_bf16_f32 v191, v118, v119
	global_store_dwordx4 v0, v[188:191], s[72:73]
	s_waitcnt vmcnt(15)
	v_lshlrev_b32_e32 v174, 16, v192
	v_lshlrev_b32_e32 v175, 16, v193
	v_lshlrev_b32_e32 v176, 16, v194
	v_lshlrev_b32_e32 v177, 16, v195
	v_and_b32_e32 v192, 0xffff0000, v192
	v_and_b32_e32 v193, 0xffff0000, v193
	v_and_b32_e32 v194, 0xffff0000, v194
	v_and_b32_e32 v195, 0xffff0000, v195
	v_mul_f32_e32 v174, 0xbfb8aa3b, v174
	v_mul_f32_e32 v192, 0xbfb8aa3b, v192
	v_mul_f32_e32 v175, 0xbfb8aa3b, v175
	v_mul_f32_e32 v193, 0xbfb8aa3b, v193
	v_mul_f32_e32 v176, 0xbfb8aa3b, v176
	v_mul_f32_e32 v194, 0xbfb8aa3b, v194
	v_mul_f32_e32 v177, 0xbfb8aa3b, v177
	v_mul_f32_e32 v195, 0xbfb8aa3b, v195
	v_exp_f32_e32 v174, v174
	v_exp_f32_e32 v192, v192
	v_exp_f32_e32 v175, v175
	v_exp_f32_e32 v193, v193
	v_exp_f32_e32 v176, v176
	v_exp_f32_e32 v194, v194
	v_exp_f32_e32 v177, v177
	v_exp_f32_e32 v195, v195
	v_add_f32_e32 v174, 1.0, v174
	v_add_f32_e32 v192, 1.0, v192
	v_add_f32_e32 v175, 1.0, v175
	v_add_f32_e32 v193, 1.0, v193
	v_add_f32_e32 v176, 1.0, v176
	v_add_f32_e32 v194, 1.0, v194
	v_add_f32_e32 v177, 1.0, v177
	v_add_f32_e32 v195, 1.0, v195
	v_rcp_f32_e32 v174, v174
	v_rcp_f32_e32 v192, v192
	v_rcp_f32_e32 v175, v175
	v_rcp_f32_e32 v193, v193
	v_rcp_f32_e32 v176, v176
	v_rcp_f32_e32 v194, v194
	v_rcp_f32_e32 v177, v177
	v_rcp_f32_e32 v195, v195
	v_mul_f32_e32 v88, v174, v88
	v_mul_f32_e32 v89, v192, v89
	v_mul_f32_e32 v90, v175, v90
	v_mul_f32_e32 v91, v193, v91
	v_mul_f32_e32 v84, v176, v84
	v_mul_f32_e32 v85, v194, v85
	v_mul_f32_e32 v86, v177, v86
	v_mul_f32_e32 v87, v195, v87
	v_cvt_pk_bf16_f32 v192, v88, v89
	v_cvt_pk_bf16_f32 v193, v90, v91
	v_cvt_pk_bf16_f32 v194, v84, v85
	v_cvt_pk_bf16_f32 v195, v86, v87
	global_store_dwordx4 v0, v[192:195], s[72:73] offset:256
	s_add_u32 s72, s72, 0x28000
	s_addc_u32 s73, s73, 0
	s_waitcnt vmcnt(15)
	v_lshlrev_b32_e32 v174, 16, v196
	v_lshlrev_b32_e32 v175, 16, v197
	v_lshlrev_b32_e32 v176, 16, v198
	v_lshlrev_b32_e32 v177, 16, v199
	v_and_b32_e32 v196, 0xffff0000, v196
	v_and_b32_e32 v197, 0xffff0000, v197
	v_and_b32_e32 v198, 0xffff0000, v198
	v_and_b32_e32 v199, 0xffff0000, v199
	v_mul_f32_e32 v174, 0xbfb8aa3b, v174
	v_mul_f32_e32 v196, 0xbfb8aa3b, v196
	v_mul_f32_e32 v175, 0xbfb8aa3b, v175
	v_mul_f32_e32 v197, 0xbfb8aa3b, v197
	v_mul_f32_e32 v176, 0xbfb8aa3b, v176
	v_mul_f32_e32 v198, 0xbfb8aa3b, v198
	v_mul_f32_e32 v177, 0xbfb8aa3b, v177
	v_mul_f32_e32 v199, 0xbfb8aa3b, v199
	v_exp_f32_e32 v174, v174
	v_exp_f32_e32 v196, v196
	v_exp_f32_e32 v175, v175
	v_exp_f32_e32 v197, v197
	v_exp_f32_e32 v176, v176
	v_exp_f32_e32 v198, v198
	v_exp_f32_e32 v177, v177
	v_exp_f32_e32 v199, v199
	v_add_f32_e32 v174, 1.0, v174
	v_add_f32_e32 v196, 1.0, v196
	v_add_f32_e32 v175, 1.0, v175
	v_add_f32_e32 v197, 1.0, v197
	v_add_f32_e32 v176, 1.0, v176
	v_add_f32_e32 v198, 1.0, v198
	v_add_f32_e32 v177, 1.0, v177
	v_add_f32_e32 v199, 1.0, v199
	v_rcp_f32_e32 v174, v174
	v_rcp_f32_e32 v196, v196
	v_rcp_f32_e32 v175, v175
	v_rcp_f32_e32 v197, v197
	v_rcp_f32_e32 v176, v176
	v_rcp_f32_e32 v198, v198
	v_rcp_f32_e32 v177, v177
	v_rcp_f32_e32 v199, v199
	v_mul_f32_e32 v112, v174, v112
	v_mul_f32_e32 v113, v196, v113
	v_mul_f32_e32 v114, v175, v114
	v_mul_f32_e32 v115, v197, v115
	v_mul_f32_e32 v108, v176, v108
	v_mul_f32_e32 v109, v198, v109
	v_mul_f32_e32 v110, v177, v110
	v_mul_f32_e32 v111, v199, v111
	v_cvt_pk_bf16_f32 v196, v112, v113
	v_cvt_pk_bf16_f32 v197, v114, v115
	v_cvt_pk_bf16_f32 v198, v108, v109
	v_cvt_pk_bf16_f32 v199, v110, v111
	global_store_dwordx4 v0, v[196:199], s[72:73]
	s_waitcnt vmcnt(15)
; __device__ __forceinline__ u32x4 pack8(const float (&f)[8]) { u32x4 o; o.x = cvt_pk_bf16(f[0], f[1]); o.y = cvt_pk_bf16(f[2], f[3]); o.z = cvt_pk_bf16(f[4], f[5]); o.w = cvt_pk_bf16(f[6], f[7]); return o; }
; __device__ __forceinline__ float sigmoidf_(float x) { return __builtin_amdgcn_rcpf(1.0f + __expf(-x)); }
;     __device__ __forceinline__ void operator()(const f32x4 (&acc)[2][2][4][2], const Unit& u, int wr, int wc, int fr, int fq) const {
;         const int row0 = u.pm * BM + wr * 64 + fr, col0 = u.pn * BM + wc * 32 + 8 * fq;
;         const bool split = u.nkt != ntFull;
;         const int goff = (split && u.z == 0) ? C_MA : C_MB;
;         float* S0 = SLAB + (size_t)((u.kt0 >> 2) * 2 + u.z) * 256 * D;
; #pragma unroll
;         for (int ai = 0; ai < 2; ++ai)
; #pragma unroll
;             for (int m = 0; m < 4; ++m) { const size_t r = (size_t)(row0 + ai * HALF + m * 16); bf16_t* prow = P + r * DP;
;                 float* srow = S0 + (size_t)(wr * 64 + fr + ai * HALF + m * 16) * D;
; #pragma unroll
;                 for (int bj = 0; bj < 2; ++bj) { const int c = col0 + bj * HALF;
;                     const u32x4 gw = *(const u32x4*)(prow + goff + c); float g[8]; unpack8(gw, g);
;                     const f32x4 v0 = acc[ai][bj][m][0], v1 = acc[ai][bj][m][1];
;                     float o[8];
; #pragma unroll
;                     for (int e = 0; e < 4; ++e) { o[e] = sigmoidf_(g[e]) * v0[e]; o[4 + e] = sigmoidf_(g[4 + e]) * v1[e]; }
;                     if (split) store8f(srow + c, o); else *(u32x4*)(prow + C_MIX + c) = pack8(o); }
;                 asm volatile("" ::: "memory"); }
	v_lshlrev_b32_e32 v174, 16, v200
	v_lshlrev_b32_e32 v175, 16, v201
	v_lshlrev_b32_e32 v176, 16, v202
	v_lshlrev_b32_e32 v177, 16, v203
	v_and_b32_e32 v200, 0xffff0000, v200
	v_and_b32_e32 v201, 0xffff0000, v201
	v_and_b32_e32 v202, 0xffff0000, v202
	v_and_b32_e32 v203, 0xffff0000, v203
	v_mul_f32_e32 v174, 0xbfb8aa3b, v174
	v_mul_f32_e32 v200, 0xbfb8aa3b, v200
	v_mul_f32_e32 v175, 0xbfb8aa3b, v175
	v_mul_f32_e32 v201, 0xbfb8aa3b, v201
	v_mul_f32_e32 v176, 0xbfb8aa3b, v176
	v_mul_f32_e32 v202, 0xbfb8aa3b, v202
	v_mul_f32_e32 v177, 0xbfb8aa3b, v177
	v_mul_f32_e32 v203, 0xbfb8aa3b, v203
	v_exp_f32_e32 v174, v174
	v_exp_f32_e32 v200, v200
	v_exp_f32_e32 v175, v175
	v_exp_f32_e32 v201, v201
	v_exp_f32_e32 v176, v176
	v_exp_f32_e32 v202, v202
	v_exp_f32_e32 v177, v177
	v_exp_f32_e32 v203, v203
	v_add_f32_e32 v174, 1.0, v174
	v_add_f32_e32 v200, 1.0, v200
	v_add_f32_e32 v175, 1.0, v175
	v_add_f32_e32 v201, 1.0, v201
	v_add_f32_e32 v176, 1.0, v176
	v_add_f32_e32 v202, 1.0, v202
	v_add_f32_e32 v177, 1.0, v177
	v_add_f32_e32 v203, 1.0, v203
	v_rcp_f32_e32 v174, v174
	v_rcp_f32_e32 v200, v200
	v_rcp_f32_e32 v175, v175
	v_rcp_f32_e32 v201, v201
	v_rcp_f32_e32 v176, v176
	v_rcp_f32_e32 v202, v202
	v_rcp_f32_e32 v177, v177
	v_rcp_f32_e32 v203, v203
	v_mul_f32_e32 v80, v174, v80
	v_mul_f32_e32 v81, v200, v81
	v_mul_f32_e32 v82, v175, v82
	v_mul_f32_e32 v83, v201, v83
	v_mul_f32_e32 v76, v176, v76
	v_mul_f32_e32 v77, v202, v77
	v_mul_f32_e32 v78, v177, v78
	v_mul_f32_e32 v79, v203, v79
	v_cvt_pk_bf16_f32 v200, v80, v81
	v_cvt_pk_bf16_f32 v201, v82, v83
	v_cvt_pk_bf16_f32 v202, v76, v77
	v_cvt_pk_bf16_f32 v203, v78, v79
	global_store_dwordx4 v0, v[200:203], s[72:73] offset:256
	s_add_u32 s72, s72, 0x28000
	s_addc_u32 s73, s73, 0
	s_waitcnt vmcnt(15)
	v_lshlrev_b32_e32 v174, 16, v224
	v_lshlrev_b32_e32 v175, 16, v225
	v_lshlrev_b32_e32 v176, 16, v226
	v_lshlrev_b32_e32 v177, 16, v227
	v_and_b32_e32 v224, 0xffff0000, v224
	v_and_b32_e32 v225, 0xffff0000, v225
	v_and_b32_e32 v226, 0xffff0000, v226
	v_and_b32_e32 v227, 0xffff0000, v227
	v_mul_f32_e32 v174, 0xbfb8aa3b, v174
	v_mul_f32_e32 v224, 0xbfb8aa3b, v224
	v_mul_f32_e32 v175, 0xbfb8aa3b, v175
	v_mul_f32_e32 v225, 0xbfb8aa3b, v225
	v_mul_f32_e32 v176, 0xbfb8aa3b, v176
	v_mul_f32_e32 v226, 0xbfb8aa3b, v226
	v_mul_f32_e32 v177, 0xbfb8aa3b, v177
	v_mul_f32_e32 v227, 0xbfb8aa3b, v227
	v_exp_f32_e32 v174, v174
	v_exp_f32_e32 v224, v224
	v_exp_f32_e32 v175, v175
	v_exp_f32_e32 v225, v225
	v_exp_f32_e32 v176, v176
	v_exp_f32_e32 v226, v226
	v_exp_f32_e32 v177, v177
	v_exp_f32_e32 v227, v227
	v_add_f32_e32 v174, 1.0, v174
	v_add_f32_e32 v224, 1.0, v224
	v_add_f32_e32 v175, 1.0, v175
	v_add_f32_e32 v225, 1.0, v225
	v_add_f32_e32 v176, 1.0, v176
	v_add_f32_e32 v226, 1.0, v226
	v_add_f32_e32 v177, 1.0, v177
	v_add_f32_e32 v227, 1.0, v227
	v_rcp_f32_e32 v174, v174
	v_rcp_f32_e32 v224, v224
	v_rcp_f32_e32 v175, v175
	v_rcp_f32_e32 v225, v225
	v_rcp_f32_e32 v176, v176
	v_rcp_f32_e32 v226, v226
	v_rcp_f32_e32 v177, v177
	v_rcp_f32_e32 v227, v227
	v_mul_f32_e32 v104, v174, v104
	v_mul_f32_e32 v105, v224, v105
	v_mul_f32_e32 v106, v175, v106
	v_mul_f32_e32 v107, v225, v107
	v_mul_f32_e32 v100, v176, v100
	v_mul_f32_e32 v101, v226, v101
	v_mul_f32_e32 v102, v177, v102
	v_mul_f32_e32 v103, v227, v103
	v_cvt_pk_bf16_f32 v224, v104, v105
	v_cvt_pk_bf16_f32 v225, v106, v107
	v_cvt_pk_bf16_f32 v226, v100, v101
	v_cvt_pk_bf16_f32 v227, v102, v103
	global_store_dwordx4 v0, v[224:227], s[72:73]
	s_waitcnt vmcnt(15)
	v_lshlrev_b32_e32 v174, 16, v228
	v_lshlrev_b32_e32 v175, 16, v229
	v_lshlrev_b32_e32 v176, 16, v230
	v_lshlrev_b32_e32 v177, 16, v231
	v_and_b32_e32 v228, 0xffff0000, v228
	v_and_b32_e32 v229, 0xffff0000, v229
	v_and_b32_e32 v230, 0xffff0000, v230
	v_and_b32_e32 v231, 0xffff0000, v231
	v_mul_f32_e32 v174, 0xbfb8aa3b, v174
	v_mul_f32_e32 v228, 0xbfb8aa3b, v228
	v_mul_f32_e32 v175, 0xbfb8aa3b, v175
	v_mul_f32_e32 v229, 0xbfb8aa3b, v229
	v_mul_f32_e32 v176, 0xbfb8aa3b, v176
	v_mul_f32_e32 v230, 0xbfb8aa3b, v230
	v_mul_f32_e32 v177, 0xbfb8aa3b, v177
	v_mul_f32_e32 v231, 0xbfb8aa3b, v231
	v_exp_f32_e32 v174, v174
	v_exp_f32_e32 v228, v228
	v_exp_f32_e32 v175, v175
	v_exp_f32_e32 v229, v229
	v_exp_f32_e32 v176, v176
	v_exp_f32_e32 v230, v230
	v_exp_f32_e32 v177, v177
	v_exp_f32_e32 v231, v231
	v_add_f32_e32 v174, 1.0, v174
	v_add_f32_e32 v228, 1.0, v228
	v_add_f32_e32 v175, 1.0, v175
	v_add_f32_e32 v229, 1.0, v229
	v_add_f32_e32 v176, 1.0, v176
	v_add_f32_e32 v230, 1.0, v230
	v_add_f32_e32 v177, 1.0, v177
	v_add_f32_e32 v231, 1.0, v231
	v_rcp_f32_e32 v174, v174
	v_rcp_f32_e32 v228, v228
	v_rcp_f32_e32 v175, v175
	v_rcp_f32_e32 v229, v229
	v_rcp_f32_e32 v176, v176
	v_rcp_f32_e32 v230, v230
	v_rcp_f32_e32 v177, v177
	v_rcp_f32_e32 v231, v231
	v_mul_f32_e32 v72, v174, v72
	v_mul_f32_e32 v73, v228, v73
	v_mul_f32_e32 v74, v175, v74
	v_mul_f32_e32 v75, v229, v75
	v_mul_f32_e32 v68, v176, v68
	v_mul_f32_e32 v69, v230, v69
	v_mul_f32_e32 v70, v177, v70
	v_mul_f32_e32 v71, v231, v71
	v_cvt_pk_bf16_f32 v228, v72, v73
	v_cvt_pk_bf16_f32 v229, v74, v75
	v_cvt_pk_bf16_f32 v230, v68, v69
	v_cvt_pk_bf16_f32 v231, v70, v71
	global_store_dwordx4 v0, v[228:231], s[72:73] offset:256
	s_add_u32 s72, s72, 0xc8000
	s_addc_u32 s73, s73, 0
	s_waitcnt vmcnt(15)
; __device__ __forceinline__ u32x4 pack8(const float (&f)[8]) { u32x4 o; o.x = cvt_pk_bf16(f[0], f[1]); o.y = cvt_pk_bf16(f[2], f[3]); o.z = cvt_pk_bf16(f[4], f[5]); o.w = cvt_pk_bf16(f[6], f[7]); return o; }
; __device__ __forceinline__ float sigmoidf_(float x) { return __builtin_amdgcn_rcpf(1.0f + __expf(-x)); }
;     __device__ __forceinline__ void operator()(const f32x4 (&acc)[2][2][4][2], const Unit& u, int wr, int wc, int fr, int fq) const {
;         const int row0 = u.pm * BM + wr * 64 + fr, col0 = u.pn * BM + wc * 32 + 8 * fq;
;         const bool split = u.nkt != ntFull;
;         const int goff = (split && u.z == 0) ? C_MA : C_MB;
;         float* S0 = SLAB + (size_t)((u.kt0 >> 2) * 2 + u.z) * 256 * D;
; #pragma unroll
;         for (int ai = 0; ai < 2; ++ai)
; #pragma unroll
;             for (int m = 0; m < 4; ++m) { const size_t r = (size_t)(row0 + ai * HALF + m * 16); bf16_t* prow = P + r * DP;
;                 float* srow = S0 + (size_t)(wr * 64 + fr + ai * HALF + m * 16) * D;
; #pragma unroll
;                 for (int bj = 0; bj < 2; ++bj) { const int c = col0 + bj * HALF;
;                     const u32x4 gw = *(const u32x4*)(prow + goff + c); float g[8]; unpack8(gw, g);
;                     const f32x4 v0 = acc[ai][bj][m][0], v1 = acc[ai][bj][m][1];
;                     float o[8];
; #pragma unroll
;                     for (int e = 0; e < 4; ++e) { o[e] = sigmoidf_(g[e]) * v0[e]; o[4 + e] = sigmoidf_(g[4 + e]) * v1[e]; }
;                     if (split) store8f(srow + c, o); else *(u32x4*)(prow + C_MIX + c) = pack8(o); }
;                 asm volatile("" ::: "memory"); }
	v_lshlrev_b32_e32 v174, 16, v232
	v_lshlrev_b32_e32 v175, 16, v233
	v_lshlrev_b32_e32 v176, 16, v234
	v_lshlrev_b32_e32 v177, 16, v235
	v_and_b32_e32 v232, 0xffff0000, v232
	v_and_b32_e32 v233, 0xffff0000, v233
	v_and_b32_e32 v234, 0xffff0000, v234
	v_and_b32_e32 v235, 0xffff0000, v235
	v_mul_f32_e32 v174, 0xbfb8aa3b, v174
	v_mul_f32_e32 v232, 0xbfb8aa3b, v232
	v_mul_f32_e32 v175, 0xbfb8aa3b, v175
	v_mul_f32_e32 v233, 0xbfb8aa3b, v233
	v_mul_f32_e32 v176, 0xbfb8aa3b, v176
	v_mul_f32_e32 v234, 0xbfb8aa3b, v234
	v_mul_f32_e32 v177, 0xbfb8aa3b, v177
	v_mul_f32_e32 v235, 0xbfb8aa3b, v235
	v_exp_f32_e32 v174, v174
	v_exp_f32_e32 v232, v232
	v_exp_f32_e32 v175, v175
	v_exp_f32_e32 v233, v233
	v_exp_f32_e32 v176, v176
	v_exp_f32_e32 v234, v234
	v_exp_f32_e32 v177, v177
	v_exp_f32_e32 v235, v235
	v_add_f32_e32 v174, 1.0, v174
	v_add_f32_e32 v232, 1.0, v232
	v_add_f32_e32 v175, 1.0, v175
	v_add_f32_e32 v233, 1.0, v233
	v_add_f32_e32 v176, 1.0, v176
	v_add_f32_e32 v234, 1.0, v234
	v_add_f32_e32 v177, 1.0, v177
	v_add_f32_e32 v235, 1.0, v235
	v_rcp_f32_e32 v174, v174
	v_rcp_f32_e32 v232, v232
	v_rcp_f32_e32 v175, v175
	v_rcp_f32_e32 v233, v233
	v_rcp_f32_e32 v176, v176
	v_rcp_f32_e32 v234, v234
	v_rcp_f32_e32 v177, v177
	v_rcp_f32_e32 v235, v235
	v_mul_f32_e32 v64, v174, v64
	v_mul_f32_e32 v65, v232, v65
	v_mul_f32_e32 v66, v175, v66
	v_mul_f32_e32 v67, v233, v67
	v_mul_f32_e32 v60, v176, v60
	v_mul_f32_e32 v61, v234, v61
	v_mul_f32_e32 v62, v177, v62
	v_mul_f32_e32 v63, v235, v63
	v_cvt_pk_bf16_f32 v232, v64, v65
	v_cvt_pk_bf16_f32 v233, v66, v67
	v_cvt_pk_bf16_f32 v234, v60, v61
	v_cvt_pk_bf16_f32 v235, v62, v63
	global_store_dwordx4 v0, v[232:235], s[72:73]
	s_waitcnt vmcnt(15)
	v_lshlrev_b32_e32 v174, 16, v236
	v_lshlrev_b32_e32 v175, 16, v237
	v_lshlrev_b32_e32 v176, 16, v238
	v_lshlrev_b32_e32 v177, 16, v239
	v_and_b32_e32 v236, 0xffff0000, v236
	v_and_b32_e32 v237, 0xffff0000, v237
	v_and_b32_e32 v238, 0xffff0000, v238
	v_and_b32_e32 v239, 0xffff0000, v239
	v_mul_f32_e32 v174, 0xbfb8aa3b, v174
	v_mul_f32_e32 v236, 0xbfb8aa3b, v236
	v_mul_f32_e32 v175, 0xbfb8aa3b, v175
	v_mul_f32_e32 v237, 0xbfb8aa3b, v237
	v_mul_f32_e32 v176, 0xbfb8aa3b, v176
	v_mul_f32_e32 v238, 0xbfb8aa3b, v238
	v_mul_f32_e32 v177, 0xbfb8aa3b, v177
	v_mul_f32_e32 v239, 0xbfb8aa3b, v239
	v_exp_f32_e32 v174, v174
	v_exp_f32_e32 v236, v236
	v_exp_f32_e32 v175, v175
	v_exp_f32_e32 v237, v237
	v_exp_f32_e32 v176, v176
	v_exp_f32_e32 v238, v238
	v_exp_f32_e32 v177, v177
	v_exp_f32_e32 v239, v239
	v_add_f32_e32 v174, 1.0, v174
	v_add_f32_e32 v236, 1.0, v236
	v_add_f32_e32 v175, 1.0, v175
	v_add_f32_e32 v237, 1.0, v237
	v_add_f32_e32 v176, 1.0, v176
	v_add_f32_e32 v238, 1.0, v238
	v_add_f32_e32 v177, 1.0, v177
	v_add_f32_e32 v239, 1.0, v239
	v_rcp_f32_e32 v174, v174
	v_rcp_f32_e32 v236, v236
	v_rcp_f32_e32 v175, v175
	v_rcp_f32_e32 v237, v237
	v_rcp_f32_e32 v176, v176
	v_rcp_f32_e32 v238, v238
	v_rcp_f32_e32 v177, v177
	v_rcp_f32_e32 v239, v239
	v_mul_f32_e32 v32, v174, v32
	v_mul_f32_e32 v33, v236, v33
	v_mul_f32_e32 v34, v175, v34
	v_mul_f32_e32 v35, v237, v35
	v_mul_f32_e32 v28, v176, v28
	v_mul_f32_e32 v29, v238, v29
	v_mul_f32_e32 v30, v177, v30
	v_mul_f32_e32 v31, v239, v31
	v_cvt_pk_bf16_f32 v236, v32, v33
	v_cvt_pk_bf16_f32 v237, v34, v35
	v_cvt_pk_bf16_f32 v238, v28, v29
	v_cvt_pk_bf16_f32 v239, v30, v31
	global_store_dwordx4 v0, v[236:239], s[72:73] offset:256
	s_add_u32 s72, s72, 0x28000
	s_addc_u32 s73, s73, 0
	s_waitcnt vmcnt(15)
	v_lshlrev_b32_e32 v174, 16, v240
	v_lshlrev_b32_e32 v175, 16, v241
	v_lshlrev_b32_e32 v176, 16, v242
	v_lshlrev_b32_e32 v177, 16, v243
	v_and_b32_e32 v240, 0xffff0000, v240
	v_and_b32_e32 v241, 0xffff0000, v241
	v_and_b32_e32 v242, 0xffff0000, v242
	v_and_b32_e32 v243, 0xffff0000, v243
	v_mul_f32_e32 v174, 0xbfb8aa3b, v174
	v_mul_f32_e32 v240, 0xbfb8aa3b, v240
	v_mul_f32_e32 v175, 0xbfb8aa3b, v175
	v_mul_f32_e32 v241, 0xbfb8aa3b, v241
	v_mul_f32_e32 v176, 0xbfb8aa3b, v176
	v_mul_f32_e32 v242, 0xbfb8aa3b, v242
	v_mul_f32_e32 v177, 0xbfb8aa3b, v177
	v_mul_f32_e32 v243, 0xbfb8aa3b, v243
	v_exp_f32_e32 v174, v174
	v_exp_f32_e32 v240, v240
	v_exp_f32_e32 v175, v175
	v_exp_f32_e32 v241, v241
	v_exp_f32_e32 v176, v176
	v_exp_f32_e32 v242, v242
	v_exp_f32_e32 v177, v177
	v_exp_f32_e32 v243, v243
	v_add_f32_e32 v174, 1.0, v174
	v_add_f32_e32 v240, 1.0, v240
	v_add_f32_e32 v175, 1.0, v175
	v_add_f32_e32 v241, 1.0, v241
	v_add_f32_e32 v176, 1.0, v176
	v_add_f32_e32 v242, 1.0, v242
	v_add_f32_e32 v177, 1.0, v177
	v_add_f32_e32 v243, 1.0, v243
	v_rcp_f32_e32 v174, v174
	v_rcp_f32_e32 v240, v240
	v_rcp_f32_e32 v175, v175
	v_rcp_f32_e32 v241, v241
	v_rcp_f32_e32 v176, v176
	v_rcp_f32_e32 v242, v242
	v_rcp_f32_e32 v177, v177
	v_rcp_f32_e32 v243, v243
	v_mul_f32_e32 v56, v174, v56
	v_mul_f32_e32 v57, v240, v57
	v_mul_f32_e32 v58, v175, v58
	v_mul_f32_e32 v59, v241, v59
	v_mul_f32_e32 v52, v176, v52
	v_mul_f32_e32 v53, v242, v53
	v_mul_f32_e32 v54, v177, v54
	v_mul_f32_e32 v55, v243, v55
	v_cvt_pk_bf16_f32 v240, v56, v57
	v_cvt_pk_bf16_f32 v241, v58, v59
	v_cvt_pk_bf16_f32 v242, v52, v53
	v_cvt_pk_bf16_f32 v243, v54, v55
	global_store_dwordx4 v0, v[240:243], s[72:73]
	s_waitcnt vmcnt(15)
; __device__ __forceinline__ u32x4 pack8(const float (&f)[8]) { u32x4 o; o.x = cvt_pk_bf16(f[0], f[1]); o.y = cvt_pk_bf16(f[2], f[3]); o.z = cvt_pk_bf16(f[4], f[5]); o.w = cvt_pk_bf16(f[6], f[7]); return o; }
; __device__ __forceinline__ float sigmoidf_(float x) { return __builtin_amdgcn_rcpf(1.0f + __expf(-x)); }
;     __device__ __forceinline__ void operator()(const f32x4 (&acc)[2][2][4][2], const Unit& u, int wr, int wc, int fr, int fq) const {
;     ...
;             for (int m = 0; m < 4; ++m) { const size_t r = (size_t)(row0 + ai * HALF + m * 16); bf16_t* prow = P + r * DP;
;                 float* srow = S0 + (size_t)(wr * 64 + fr + ai * HALF + m * 16) * D;
; #pragma unroll
;                 for (int bj = 0; bj < 2; ++bj) { const int c = col0 + bj * HALF;
;                     const u32x4 gw = *(const u32x4*)(prow + goff + c); float g[8]; unpack8(gw, g);
;                     const f32x4 v0 = acc[ai][bj][m][0], v1 = acc[ai][bj][m][1];
;                     float o[8];
; #pragma unroll
;                     for (int e = 0; e < 4; ++e) { o[e] = sigmoidf_(g[e]) * v0[e]; o[4 + e] = sigmoidf_(g[4 + e]) * v1[e]; }
;                     if (split) store8f(srow + c, o); else *(u32x4*)(prow + C_MIX + c) = pack8(o); }
	v_lshlrev_b32_e32 v174, 16, v244
	v_lshlrev_b32_e32 v175, 16, v245
	v_lshlrev_b32_e32 v176, 16, v246
	v_lshlrev_b32_e32 v177, 16, v247
	v_and_b32_e32 v244, 0xffff0000, v244
	v_and_b32_e32 v245, 0xffff0000, v245
	v_and_b32_e32 v246, 0xffff0000, v246
	v_and_b32_e32 v247, 0xffff0000, v247
	v_mul_f32_e32 v174, 0xbfb8aa3b, v174
	v_mul_f32_e32 v244, 0xbfb8aa3b, v244
	v_mul_f32_e32 v175, 0xbfb8aa3b, v175
	v_mul_f32_e32 v245, 0xbfb8aa3b, v245
	v_mul_f32_e32 v176, 0xbfb8aa3b, v176
	v_mul_f32_e32 v246, 0xbfb8aa3b, v246
	v_mul_f32_e32 v177, 0xbfb8aa3b, v177
	v_mul_f32_e32 v247, 0xbfb8aa3b, v247
	v_exp_f32_e32 v174, v174
	v_exp_f32_e32 v244, v244
	v_exp_f32_e32 v175, v175
	v_exp_f32_e32 v245, v245
	v_exp_f32_e32 v176, v176
	v_exp_f32_e32 v246, v246
	v_exp_f32_e32 v177, v177
	v_exp_f32_e32 v247, v247
	v_add_f32_e32 v174, 1.0, v174
	v_add_f32_e32 v244, 1.0, v244
	v_add_f32_e32 v175, 1.0, v175
	v_add_f32_e32 v245, 1.0, v245
	v_add_f32_e32 v176, 1.0, v176
	v_add_f32_e32 v246, 1.0, v246
	v_add_f32_e32 v177, 1.0, v177
	v_add_f32_e32 v247, 1.0, v247
	v_rcp_f32_e32 v174, v174
	v_rcp_f32_e32 v244, v244
	v_rcp_f32_e32 v175, v175
	v_rcp_f32_e32 v245, v245
	v_rcp_f32_e32 v176, v176
	v_rcp_f32_e32 v246, v246
	v_rcp_f32_e32 v177, v177
	v_rcp_f32_e32 v247, v247
	v_mul_f32_e32 v24, v174, v24
	v_mul_f32_e32 v25, v244, v25
	v_mul_f32_e32 v26, v175, v26
	v_mul_f32_e32 v27, v245, v27
	v_mul_f32_e32 v20, v176, v20
	v_mul_f32_e32 v21, v246, v21
	v_mul_f32_e32 v22, v177, v22
	v_mul_f32_e32 v23, v247, v23
	v_cvt_pk_bf16_f32 v244, v24, v25
	v_cvt_pk_bf16_f32 v245, v26, v27
	v_cvt_pk_bf16_f32 v246, v20, v21
	v_cvt_pk_bf16_f32 v247, v22, v23
	global_store_dwordx4 v0, v[244:247], s[72:73] offset:256
	s_add_u32 s72, s72, 0x28000
	s_addc_u32 s73, s73, 0
	s_waitcnt vmcnt(15)
	v_lshlrev_b32_e32 v174, 16, v248
	v_lshlrev_b32_e32 v175, 16, v249
	v_lshlrev_b32_e32 v176, 16, v250
	v_lshlrev_b32_e32 v177, 16, v251
	v_and_b32_e32 v248, 0xffff0000, v248
	v_and_b32_e32 v249, 0xffff0000, v249
	v_and_b32_e32 v250, 0xffff0000, v250
	v_and_b32_e32 v251, 0xffff0000, v251
	v_mul_f32_e32 v174, 0xbfb8aa3b, v174
	v_mul_f32_e32 v248, 0xbfb8aa3b, v248
	v_mul_f32_e32 v175, 0xbfb8aa3b, v175
	v_mul_f32_e32 v249, 0xbfb8aa3b, v249
	v_mul_f32_e32 v176, 0xbfb8aa3b, v176
	v_mul_f32_e32 v250, 0xbfb8aa3b, v250
	v_mul_f32_e32 v177, 0xbfb8aa3b, v177
	v_mul_f32_e32 v251, 0xbfb8aa3b, v251
	v_exp_f32_e32 v174, v174
	v_exp_f32_e32 v248, v248
	v_exp_f32_e32 v175, v175
	v_exp_f32_e32 v249, v249
	v_exp_f32_e32 v176, v176
	v_exp_f32_e32 v250, v250
	v_exp_f32_e32 v177, v177
	v_exp_f32_e32 v251, v251
	v_add_f32_e32 v174, 1.0, v174
	v_add_f32_e32 v248, 1.0, v248
	v_add_f32_e32 v175, 1.0, v175
	v_add_f32_e32 v249, 1.0, v249
	v_add_f32_e32 v176, 1.0, v176
	v_add_f32_e32 v250, 1.0, v250
	v_add_f32_e32 v177, 1.0, v177
	v_add_f32_e32 v251, 1.0, v251
	v_rcp_f32_e32 v174, v174
	v_rcp_f32_e32 v248, v248
	v_rcp_f32_e32 v175, v175
	v_rcp_f32_e32 v249, v249
	v_rcp_f32_e32 v176, v176
	v_rcp_f32_e32 v250, v250
	v_rcp_f32_e32 v177, v177
	v_rcp_f32_e32 v251, v251
	v_mul_f32_e32 v48, v174, v48
	v_mul_f32_e32 v49, v248, v49
	v_mul_f32_e32 v50, v175, v50
	v_mul_f32_e32 v51, v249, v51
	v_mul_f32_e32 v44, v176, v44
	v_mul_f32_e32 v45, v250, v45
	v_mul_f32_e32 v46, v177, v46
	v_mul_f32_e32 v47, v251, v47
	v_cvt_pk_bf16_f32 v248, v48, v49
	v_cvt_pk_bf16_f32 v249, v50, v51
	v_cvt_pk_bf16_f32 v250, v44, v45
	v_cvt_pk_bf16_f32 v251, v46, v47
	global_store_dwordx4 v0, v[248:251], s[72:73]
	s_waitcnt vmcnt(15)
	v_lshlrev_b32_e32 v174, 16, v132
	v_lshlrev_b32_e32 v175, 16, v133
	v_lshlrev_b32_e32 v176, 16, v134
	v_lshlrev_b32_e32 v177, 16, v135
	v_and_b32_e32 v132, 0xffff0000, v132
	v_and_b32_e32 v133, 0xffff0000, v133
	v_and_b32_e32 v134, 0xffff0000, v134
	v_and_b32_e32 v135, 0xffff0000, v135
	v_mul_f32_e32 v174, 0xbfb8aa3b, v174
	v_mul_f32_e32 v132, 0xbfb8aa3b, v132
	v_mul_f32_e32 v175, 0xbfb8aa3b, v175
	v_mul_f32_e32 v133, 0xbfb8aa3b, v133
	v_mul_f32_e32 v176, 0xbfb8aa3b, v176
	v_mul_f32_e32 v134, 0xbfb8aa3b, v134
	v_mul_f32_e32 v177, 0xbfb8aa3b, v177
	v_mul_f32_e32 v135, 0xbfb8aa3b, v135
	v_exp_f32_e32 v174, v174
	v_exp_f32_e32 v132, v132
	v_exp_f32_e32 v175, v175
	v_exp_f32_e32 v133, v133
	v_exp_f32_e32 v176, v176
	v_exp_f32_e32 v134, v134
	v_exp_f32_e32 v177, v177
	v_exp_f32_e32 v135, v135
	v_add_f32_e32 v174, 1.0, v174
	v_add_f32_e32 v132, 1.0, v132
	v_add_f32_e32 v175, 1.0, v175
	v_add_f32_e32 v133, 1.0, v133
	v_add_f32_e32 v176, 1.0, v176
	v_add_f32_e32 v134, 1.0, v134
	v_add_f32_e32 v177, 1.0, v177
	v_add_f32_e32 v135, 1.0, v135
	v_rcp_f32_e32 v174, v174
	v_rcp_f32_e32 v132, v132
	v_rcp_f32_e32 v175, v175
	v_rcp_f32_e32 v133, v133
	v_rcp_f32_e32 v176, v176
	v_rcp_f32_e32 v134, v134
	v_rcp_f32_e32 v177, v177
	v_rcp_f32_e32 v135, v135
	v_mul_f32_e32 v16, v174, v16
	v_mul_f32_e32 v17, v132, v17
	v_mul_f32_e32 v18, v175, v18
	v_mul_f32_e32 v19, v133, v19
	v_mul_f32_e32 v12, v176, v12
	v_mul_f32_e32 v13, v134, v13
	v_mul_f32_e32 v14, v177, v14
	v_mul_f32_e32 v15, v135, v15
	v_cvt_pk_bf16_f32 v132, v16, v17
	v_cvt_pk_bf16_f32 v133, v18, v19
	v_cvt_pk_bf16_f32 v134, v12, v13
	v_cvt_pk_bf16_f32 v135, v14, v15
	global_store_dwordx4 v0, v[132:135], s[72:73] offset:256
	s_add_u32 s72, s72, 0x28000
	s_addc_u32 s73, s73, 0
	s_waitcnt vmcnt(15)
; __device__ __forceinline__ u32x4 pack8(const float (&f)[8]) { u32x4 o; o.x = cvt_pk_bf16(f[0], f[1]); o.y = cvt_pk_bf16(f[2], f[3]); o.z = cvt_pk_bf16(f[4], f[5]); o.w = cvt_pk_bf16(f[6], f[7]); return o; }
; __device__ __forceinline__ float sigmoidf_(float x) { return __builtin_amdgcn_rcpf(1.0f + __expf(-x)); }
;     __device__ __forceinline__ void operator()(const f32x4 (&acc)[2][2][4][2], const Unit& u, int wr, int wc, int fr, int fq) const {
;     ...
;         const int goff = (split && u.z == 0) ? C_MA : C_MB;
;         float* S0 = SLAB + (size_t)((u.kt0 >> 2) * 2 + u.z) * 256 * D;
; #pragma unroll
;         for (int ai = 0; ai < 2; ++ai)
; #pragma unroll
;             for (int m = 0; m < 4; ++m) { const size_t r = (size_t)(row0 + ai * HALF + m * 16); bf16_t* prow = P + r * DP;
;                 float* srow = S0 + (size_t)(wr * 64 + fr + ai * HALF + m * 16) * D;
; #pragma unroll
;                 for (int bj = 0; bj < 2; ++bj) { const int c = col0 + bj * HALF;
;                     const u32x4 gw = *(const u32x4*)(prow + goff + c); float g[8]; unpack8(gw, g);
;                     const f32x4 v0 = acc[ai][bj][m][0], v1 = acc[ai][bj][m][1];
;                     float o[8];
; #pragma unroll
;                     for (int e = 0; e < 4; ++e) { o[e] = sigmoidf_(g[e]) * v0[e]; o[4 + e] = sigmoidf_(g[4 + e]) * v1[e]; }
;                     if (split) store8f(srow + c, o); else *(u32x4*)(prow + C_MIX + c) = pack8(o); }
	v_lshlrev_b32_e32 v174, 16, v136
	v_lshlrev_b32_e32 v175, 16, v137
	v_lshlrev_b32_e32 v176, 16, v138
	v_lshlrev_b32_e32 v177, 16, v139
	v_and_b32_e32 v136, 0xffff0000, v136
	v_and_b32_e32 v137, 0xffff0000, v137
	v_and_b32_e32 v138, 0xffff0000, v138
	v_and_b32_e32 v139, 0xffff0000, v139
	v_mul_f32_e32 v174, 0xbfb8aa3b, v174
	v_mul_f32_e32 v136, 0xbfb8aa3b, v136
	v_mul_f32_e32 v175, 0xbfb8aa3b, v175
	v_mul_f32_e32 v137, 0xbfb8aa3b, v137
	v_mul_f32_e32 v176, 0xbfb8aa3b, v176
	v_mul_f32_e32 v138, 0xbfb8aa3b, v138
	v_mul_f32_e32 v177, 0xbfb8aa3b, v177
	v_mul_f32_e32 v139, 0xbfb8aa3b, v139
	v_exp_f32_e32 v174, v174
	v_exp_f32_e32 v136, v136
	v_exp_f32_e32 v175, v175
	v_exp_f32_e32 v137, v137
	v_exp_f32_e32 v176, v176
	v_exp_f32_e32 v138, v138
	v_exp_f32_e32 v177, v177
	v_exp_f32_e32 v139, v139
	v_add_f32_e32 v174, 1.0, v174
	v_add_f32_e32 v136, 1.0, v136
	v_add_f32_e32 v175, 1.0, v175
	v_add_f32_e32 v137, 1.0, v137
	v_add_f32_e32 v176, 1.0, v176
	v_add_f32_e32 v138, 1.0, v138
	v_add_f32_e32 v177, 1.0, v177
	v_add_f32_e32 v139, 1.0, v139
	v_rcp_f32_e32 v174, v174
	v_rcp_f32_e32 v136, v136
	v_rcp_f32_e32 v175, v175
	v_rcp_f32_e32 v137, v137
	v_rcp_f32_e32 v176, v176
	v_rcp_f32_e32 v138, v138
	v_rcp_f32_e32 v177, v177
	v_rcp_f32_e32 v139, v139
	v_mul_f32_e32 v40, v174, v40
	v_mul_f32_e32 v41, v136, v41
	v_mul_f32_e32 v42, v175, v42
	v_mul_f32_e32 v43, v137, v43
	v_mul_f32_e32 v36, v176, v36
	v_mul_f32_e32 v37, v138, v37
	v_mul_f32_e32 v38, v177, v38
	v_mul_f32_e32 v39, v139, v39
	v_cvt_pk_bf16_f32 v136, v40, v41
	v_cvt_pk_bf16_f32 v137, v42, v43
	v_cvt_pk_bf16_f32 v138, v36, v37
	v_cvt_pk_bf16_f32 v139, v38, v39
	global_store_dwordx4 v0, v[136:139], s[72:73]
	s_waitcnt vmcnt(15)
	v_lshlrev_b32_e32 v174, 16, v170
	v_lshlrev_b32_e32 v175, 16, v171
	v_lshlrev_b32_e32 v176, 16, v172
	v_lshlrev_b32_e32 v177, 16, v173
	v_and_b32_e32 v170, 0xffff0000, v170
	v_and_b32_e32 v171, 0xffff0000, v171
	v_and_b32_e32 v172, 0xffff0000, v172
	v_and_b32_e32 v173, 0xffff0000, v173
	v_mul_f32_e32 v174, 0xbfb8aa3b, v174
	v_mul_f32_e32 v170, 0xbfb8aa3b, v170
	v_mul_f32_e32 v175, 0xbfb8aa3b, v175
	v_mul_f32_e32 v171, 0xbfb8aa3b, v171
	v_mul_f32_e32 v176, 0xbfb8aa3b, v176
	v_mul_f32_e32 v172, 0xbfb8aa3b, v172
	v_mul_f32_e32 v177, 0xbfb8aa3b, v177
	v_mul_f32_e32 v173, 0xbfb8aa3b, v173
	v_exp_f32_e32 v174, v174
	v_exp_f32_e32 v170, v170
	v_exp_f32_e32 v175, v175
	v_exp_f32_e32 v171, v171
	v_exp_f32_e32 v176, v176
	v_exp_f32_e32 v172, v172
	v_exp_f32_e32 v177, v177
	v_exp_f32_e32 v173, v173
	v_add_f32_e32 v174, 1.0, v174
	v_add_f32_e32 v170, 1.0, v170
	v_add_f32_e32 v175, 1.0, v175
	v_add_f32_e32 v171, 1.0, v171
	v_add_f32_e32 v176, 1.0, v176
	v_add_f32_e32 v172, 1.0, v172
	v_add_f32_e32 v177, 1.0, v177
	v_add_f32_e32 v173, 1.0, v173
	v_rcp_f32_e32 v174, v174
	v_rcp_f32_e32 v170, v170
	v_rcp_f32_e32 v175, v175
	v_rcp_f32_e32 v171, v171
	v_rcp_f32_e32 v176, v176
	v_rcp_f32_e32 v172, v172
	v_rcp_f32_e32 v177, v177
	v_rcp_f32_e32 v173, v173
	v_mul_f32_e32 v8, v174, v8
	v_mul_f32_e32 v9, v170, v9
	v_mul_f32_e32 v10, v175, v10
	v_mul_f32_e32 v11, v171, v11
	v_mul_f32_e32 v4, v176, v4
	v_mul_f32_e32 v5, v172, v5
	v_mul_f32_e32 v6, v177, v6
	v_mul_f32_e32 v7, v173, v7
	v_cvt_pk_bf16_f32 v170, v8, v9
	v_cvt_pk_bf16_f32 v171, v10, v11
	v_cvt_pk_bf16_f32 v172, v4, v5
	v_cvt_pk_bf16_f32 v173, v6, v7
	global_store_dwordx4 v0, v[170:173], s[72:73] offset:256
	s_branch .LBB0_579
.Lab_split:
	s_movk_i32 s21, 0x2000
	s_cmp_eq_u32 s16, 0
	s_cselect_b32 s21, 0x800, s21
	s_add_u32 s68, s8, s21
	s_addc_u32 s69, s9, 0
	s_ashr_i32 s4, s4, 1
	s_and_b32 s4, s4, -2
	s_add_i32 s4, s4, s16
	s_lshl_b32 s4, s4, 20
	s_add_u32 s72, s86, s4
	s_addc_u32 s73, s87, 0
	v_lshlrev_b32_e32 v2, 12, v148
	v_lshl_add_u32 v2, v3, 2, v2
	global_load_dwordx4 v[180:183], v0, s[68:69]
	global_load_dwordx4 v[184:187], v0, s[68:69] offset:256
	s_add_u32 s68, s68, 0x28000
	s_addc_u32 s69, s69, 0
	global_load_dwordx4 v[188:191], v0, s[68:69]
	global_load_dwordx4 v[192:195], v0, s[68:69] offset:256
	s_add_u32 s68, s68, 0x28000
	s_addc_u32 s69, s69, 0
	global_load_dwordx4 v[196:199], v0, s[68:69]
	global_load_dwordx4 v[200:203], v0, s[68:69] offset:256
	s_add_u32 s68, s68, 0x28000
	s_addc_u32 s69, s69, 0
	global_load_dwordx4 v[224:227], v0, s[68:69]
	global_load_dwordx4 v[228:231], v0, s[68:69] offset:256
	s_add_u32 s68, s68, 0xc8000
	s_addc_u32 s69, s69, 0
	global_load_dwordx4 v[232:235], v0, s[68:69]
	global_load_dwordx4 v[236:239], v0, s[68:69] offset:256
	s_add_u32 s68, s68, 0x28000
	s_addc_u32 s69, s69, 0
	global_load_dwordx4 v[240:243], v0, s[68:69]
	global_load_dwordx4 v[244:247], v0, s[68:69] offset:256
	s_add_u32 s68, s68, 0x28000
	s_addc_u32 s69, s69, 0
	global_load_dwordx4 v[248:251], v0, s[68:69]
	global_load_dwordx4 v[132:135], v0, s[68:69] offset:256
	s_add_u32 s68, s68, 0x28000
	s_addc_u32 s69, s69, 0
	global_load_dwordx4 v[136:139], v0, s[68:69]
	global_load_dwordx4 v[170:173], v0, s[68:69] offset:256
	s_waitcnt vmcnt(15)
; __device__ __forceinline__ u32x4 pack8(const float (&f)[8]) { u32x4 o; o.x = cvt_pk_bf16(f[0], f[1]); o.y = cvt_pk_bf16(f[2], f[3]); o.z = cvt_pk_bf16(f[4], f[5]); o.w = cvt_pk_bf16(f[6], f[7]); return o; }
; __device__ __forceinline__ float sigmoidf_(float x) { return __builtin_amdgcn_rcpf(1.0f + __expf(-x)); }
;     __device__ __forceinline__ void operator()(const f32x4 (&acc)[2][2][4][2], const Unit& u, int wr, int wc, int fr, int fq) const {
;     ...
;                 for (int bj = 0; bj < 2; ++bj) { const int c = col0 + bj * HALF;
;                     const u32x4 gw = *(const u32x4*)(prow + goff + c); float g[8]; unpack8(gw, g);
;                     const f32x4 v0 = acc[ai][bj][m][0], v1 = acc[ai][bj][m][1];
;                     float o[8];
; #pragma unroll
;                     for (int e = 0; e < 4; ++e) { o[e] = sigmoidf_(g[e]) * v0[e]; o[4 + e] = sigmoidf_(g[4 + e]) * v1[e]; }
;                     if (split) store8f(srow + c, o); else *(u32x4*)(prow + C_MIX + c) = pack8(o); }
	v_lshlrev_b32_e32 v174, 16, v180
	v_lshlrev_b32_e32 v175, 16, v181
	v_lshlrev_b32_e32 v176, 16, v182
	v_lshlrev_b32_e32 v177, 16, v183
	v_and_b32_e32 v180, 0xffff0000, v180
	v_and_b32_e32 v181, 0xffff0000, v181
	v_and_b32_e32 v182, 0xffff0000, v182
	v_and_b32_e32 v183, 0xffff0000, v183
	v_mul_f32_e32 v174, 0xbfb8aa3b, v174
	v_mul_f32_e32 v180, 0xbfb8aa3b, v180
	v_mul_f32_e32 v175, 0xbfb8aa3b, v175
	v_mul_f32_e32 v181, 0xbfb8aa3b, v181
	v_mul_f32_e32 v176, 0xbfb8aa3b, v176
	v_mul_f32_e32 v182, 0xbfb8aa3b, v182
	v_mul_f32_e32 v177, 0xbfb8aa3b, v177
	v_mul_f32_e32 v183, 0xbfb8aa3b, v183
	v_exp_f32_e32 v174, v174
	v_exp_f32_e32 v180, v180
	v_exp_f32_e32 v175, v175
	v_exp_f32_e32 v181, v181
	v_exp_f32_e32 v176, v176
	v_exp_f32_e32 v182, v182
	v_exp_f32_e32 v177, v177
	v_exp_f32_e32 v183, v183
	v_add_f32_e32 v174, 1.0, v174
	v_add_f32_e32 v180, 1.0, v180
	v_add_f32_e32 v175, 1.0, v175
	v_add_f32_e32 v181, 1.0, v181
	v_add_f32_e32 v176, 1.0, v176
	v_add_f32_e32 v182, 1.0, v182
	v_add_f32_e32 v177, 1.0, v177
	v_add_f32_e32 v183, 1.0, v183
	v_rcp_f32_e32 v174, v174
	v_rcp_f32_e32 v180, v180
	v_rcp_f32_e32 v175, v175
	v_rcp_f32_e32 v181, v181
	v_rcp_f32_e32 v176, v176
	v_rcp_f32_e32 v182, v182
	v_rcp_f32_e32 v177, v177
	v_rcp_f32_e32 v183, v183
	v_mul_f32_e32 v128, v174, v128
	v_mul_f32_e32 v129, v180, v129
	v_mul_f32_e32 v130, v175, v130
	v_mul_f32_e32 v131, v181, v131
	v_mul_f32_e32 v124, v176, v124
	v_mul_f32_e32 v125, v182, v125
	v_mul_f32_e32 v126, v177, v126
	v_mul_f32_e32 v127, v183, v127
	global_store_dwordx4 v2, v[128:131], s[72:73]
	global_store_dwordx4 v2, v[124:127], s[72:73] offset:16
	s_waitcnt vmcnt(16)
	v_lshlrev_b32_e32 v174, 16, v184
	v_lshlrev_b32_e32 v175, 16, v185
	v_lshlrev_b32_e32 v176, 16, v186
	v_lshlrev_b32_e32 v177, 16, v187
	v_and_b32_e32 v184, 0xffff0000, v184
	v_and_b32_e32 v185, 0xffff0000, v185
	v_and_b32_e32 v186, 0xffff0000, v186
	v_and_b32_e32 v187, 0xffff0000, v187
	v_mul_f32_e32 v174, 0xbfb8aa3b, v174
	v_mul_f32_e32 v184, 0xbfb8aa3b, v184
	v_mul_f32_e32 v175, 0xbfb8aa3b, v175
	v_mul_f32_e32 v185, 0xbfb8aa3b, v185
	v_mul_f32_e32 v176, 0xbfb8aa3b, v176
	v_mul_f32_e32 v186, 0xbfb8aa3b, v186
	v_mul_f32_e32 v177, 0xbfb8aa3b, v177
	v_mul_f32_e32 v187, 0xbfb8aa3b, v187
	v_exp_f32_e32 v174, v174
	v_exp_f32_e32 v184, v184
	v_exp_f32_e32 v175, v175
	v_exp_f32_e32 v185, v185
	v_exp_f32_e32 v176, v176
	v_exp_f32_e32 v186, v186
	v_exp_f32_e32 v177, v177
	v_exp_f32_e32 v187, v187
	v_add_f32_e32 v174, 1.0, v174
	v_add_f32_e32 v184, 1.0, v184
	v_add_f32_e32 v175, 1.0, v175
	v_add_f32_e32 v185, 1.0, v185
	v_add_f32_e32 v176, 1.0, v176
	v_add_f32_e32 v186, 1.0, v186
	v_add_f32_e32 v177, 1.0, v177
	v_add_f32_e32 v187, 1.0, v187
	v_rcp_f32_e32 v174, v174
	v_rcp_f32_e32 v184, v184
	v_rcp_f32_e32 v175, v175
	v_rcp_f32_e32 v185, v185
	v_rcp_f32_e32 v176, v176
	v_rcp_f32_e32 v186, v186
	v_rcp_f32_e32 v177, v177
	v_rcp_f32_e32 v187, v187
	v_mul_f32_e32 v96, v174, v96
	v_mul_f32_e32 v97, v184, v97
	v_mul_f32_e32 v98, v175, v98
	v_mul_f32_e32 v99, v185, v99
	v_mul_f32_e32 v92, v176, v92
	v_mul_f32_e32 v93, v186, v93
	v_mul_f32_e32 v94, v177, v94
	v_mul_f32_e32 v95, v187, v95
	global_store_dwordx4 v2, v[96:99], s[72:73] offset:512
	global_store_dwordx4 v2, v[92:95], s[72:73] offset:528
	s_add_u32 s72, s72, 0x10000
	s_addc_u32 s73, s73, 0
	s_waitcnt vmcnt(17)
	v_lshlrev_b32_e32 v174, 16, v188
	v_lshlrev_b32_e32 v175, 16, v189
	v_lshlrev_b32_e32 v176, 16, v190
	v_lshlrev_b32_e32 v177, 16, v191
	v_and_b32_e32 v188, 0xffff0000, v188
	v_and_b32_e32 v189, 0xffff0000, v189
	v_and_b32_e32 v190, 0xffff0000, v190
	v_and_b32_e32 v191, 0xffff0000, v191
	v_mul_f32_e32 v174, 0xbfb8aa3b, v174
	v_mul_f32_e32 v188, 0xbfb8aa3b, v188
	v_mul_f32_e32 v175, 0xbfb8aa3b, v175
	v_mul_f32_e32 v189, 0xbfb8aa3b, v189
	v_mul_f32_e32 v176, 0xbfb8aa3b, v176
	v_mul_f32_e32 v190, 0xbfb8aa3b, v190
	v_mul_f32_e32 v177, 0xbfb8aa3b, v177
	v_mul_f32_e32 v191, 0xbfb8aa3b, v191
	v_exp_f32_e32 v174, v174
	v_exp_f32_e32 v188, v188
	v_exp_f32_e32 v175, v175
	v_exp_f32_e32 v189, v189
	v_exp_f32_e32 v176, v176
	v_exp_f32_e32 v190, v190
	v_exp_f32_e32 v177, v177
	v_exp_f32_e32 v191, v191
	v_add_f32_e32 v174, 1.0, v174
	v_add_f32_e32 v188, 1.0, v188
	v_add_f32_e32 v175, 1.0, v175
	v_add_f32_e32 v189, 1.0, v189
	v_add_f32_e32 v176, 1.0, v176
	v_add_f32_e32 v190, 1.0, v190
	v_add_f32_e32 v177, 1.0, v177
	v_add_f32_e32 v191, 1.0, v191
	v_rcp_f32_e32 v174, v174
	v_rcp_f32_e32 v188, v188
	v_rcp_f32_e32 v175, v175
	v_rcp_f32_e32 v189, v189
	v_rcp_f32_e32 v176, v176
	v_rcp_f32_e32 v190, v190
	v_rcp_f32_e32 v177, v177
	v_rcp_f32_e32 v191, v191
	v_mul_f32_e32 v120, v174, v120
	v_mul_f32_e32 v121, v188, v121
	v_mul_f32_e32 v122, v175, v122
	v_mul_f32_e32 v123, v189, v123
	v_mul_f32_e32 v116, v176, v116
	v_mul_f32_e32 v117, v190, v117
	v_mul_f32_e32 v118, v177, v118
	v_mul_f32_e32 v119, v191, v119
	global_store_dwordx4 v2, v[120:123], s[72:73]
	global_store_dwordx4 v2, v[116:119], s[72:73] offset:16
	s_waitcnt vmcnt(18)
; __device__ __forceinline__ u32x4 pack8(const float (&f)[8]) { u32x4 o; o.x = cvt_pk_bf16(f[0], f[1]); o.y = cvt_pk_bf16(f[2], f[3]); o.z = cvt_pk_bf16(f[4], f[5]); o.w = cvt_pk_bf16(f[6], f[7]); return o; }
; __device__ __forceinline__ float sigmoidf_(float x) { return __builtin_amdgcn_rcpf(1.0f + __expf(-x)); }
;     __device__ __forceinline__ void operator()(const f32x4 (&acc)[2][2][4][2], const Unit& u, int wr, int wc, int fr, int fq) const {
;     ...
;                 for (int bj = 0; bj < 2; ++bj) { const int c = col0 + bj * HALF;
;                     const u32x4 gw = *(const u32x4*)(prow + goff + c); float g[8]; unpack8(gw, g);
;                     const f32x4 v0 = acc[ai][bj][m][0], v1 = acc[ai][bj][m][1];
;                     float o[8];
; #pragma unroll
;                     for (int e = 0; e < 4; ++e) { o[e] = sigmoidf_(g[e]) * v0[e]; o[4 + e] = sigmoidf_(g[4 + e]) * v1[e]; }
;                     if (split) store8f(srow + c, o); else *(u32x4*)(prow + C_MIX + c) = pack8(o); }
	v_lshlrev_b32_e32 v174, 16, v192
	v_lshlrev_b32_e32 v175, 16, v193
	v_lshlrev_b32_e32 v176, 16, v194
	v_lshlrev_b32_e32 v177, 16, v195
	v_and_b32_e32 v192, 0xffff0000, v192
	v_and_b32_e32 v193, 0xffff0000, v193
	v_and_b32_e32 v194, 0xffff0000, v194
	v_and_b32_e32 v195, 0xffff0000, v195
	v_mul_f32_e32 v174, 0xbfb8aa3b, v174
	v_mul_f32_e32 v192, 0xbfb8aa3b, v192
	v_mul_f32_e32 v175, 0xbfb8aa3b, v175
	v_mul_f32_e32 v193, 0xbfb8aa3b, v193
	v_mul_f32_e32 v176, 0xbfb8aa3b, v176
	v_mul_f32_e32 v194, 0xbfb8aa3b, v194
	v_mul_f32_e32 v177, 0xbfb8aa3b, v177
	v_mul_f32_e32 v195, 0xbfb8aa3b, v195
	v_exp_f32_e32 v174, v174
	v_exp_f32_e32 v192, v192
	v_exp_f32_e32 v175, v175
	v_exp_f32_e32 v193, v193
	v_exp_f32_e32 v176, v176
	v_exp_f32_e32 v194, v194
	v_exp_f32_e32 v177, v177
	v_exp_f32_e32 v195, v195
	v_add_f32_e32 v174, 1.0, v174
	v_add_f32_e32 v192, 1.0, v192
	v_add_f32_e32 v175, 1.0, v175
	v_add_f32_e32 v193, 1.0, v193
	v_add_f32_e32 v176, 1.0, v176
	v_add_f32_e32 v194, 1.0, v194
	v_add_f32_e32 v177, 1.0, v177
	v_add_f32_e32 v195, 1.0, v195
	v_rcp_f32_e32 v174, v174
	v_rcp_f32_e32 v192, v192
	v_rcp_f32_e32 v175, v175
	v_rcp_f32_e32 v193, v193
	v_rcp_f32_e32 v176, v176
	v_rcp_f32_e32 v194, v194
	v_rcp_f32_e32 v177, v177
	v_rcp_f32_e32 v195, v195
	v_mul_f32_e32 v88, v174, v88
	v_mul_f32_e32 v89, v192, v89
	v_mul_f32_e32 v90, v175, v90
	v_mul_f32_e32 v91, v193, v91
	v_mul_f32_e32 v84, v176, v84
	v_mul_f32_e32 v85, v194, v85
	v_mul_f32_e32 v86, v177, v86
	v_mul_f32_e32 v87, v195, v87
	global_store_dwordx4 v2, v[88:91], s[72:73] offset:512
	global_store_dwordx4 v2, v[84:87], s[72:73] offset:528
	s_add_u32 s72, s72, 0x10000
	s_addc_u32 s73, s73, 0
	s_waitcnt vmcnt(19)
	v_lshlrev_b32_e32 v174, 16, v196
	v_lshlrev_b32_e32 v175, 16, v197
	v_lshlrev_b32_e32 v176, 16, v198
	v_lshlrev_b32_e32 v177, 16, v199
	v_and_b32_e32 v196, 0xffff0000, v196
	v_and_b32_e32 v197, 0xffff0000, v197
	v_and_b32_e32 v198, 0xffff0000, v198
	v_and_b32_e32 v199, 0xffff0000, v199
	v_mul_f32_e32 v174, 0xbfb8aa3b, v174
	v_mul_f32_e32 v196, 0xbfb8aa3b, v196
	v_mul_f32_e32 v175, 0xbfb8aa3b, v175
	v_mul_f32_e32 v197, 0xbfb8aa3b, v197
	v_mul_f32_e32 v176, 0xbfb8aa3b, v176
	v_mul_f32_e32 v198, 0xbfb8aa3b, v198
	v_mul_f32_e32 v177, 0xbfb8aa3b, v177
	v_mul_f32_e32 v199, 0xbfb8aa3b, v199
	v_exp_f32_e32 v174, v174
	v_exp_f32_e32 v196, v196
	v_exp_f32_e32 v175, v175
	v_exp_f32_e32 v197, v197
	v_exp_f32_e32 v176, v176
	v_exp_f32_e32 v198, v198
	v_exp_f32_e32 v177, v177
	v_exp_f32_e32 v199, v199
	v_add_f32_e32 v174, 1.0, v174
	v_add_f32_e32 v196, 1.0, v196
	v_add_f32_e32 v175, 1.0, v175
	v_add_f32_e32 v197, 1.0, v197
	v_add_f32_e32 v176, 1.0, v176
	v_add_f32_e32 v198, 1.0, v198
	v_add_f32_e32 v177, 1.0, v177
	v_add_f32_e32 v199, 1.0, v199
	v_rcp_f32_e32 v174, v174
	v_rcp_f32_e32 v196, v196
	v_rcp_f32_e32 v175, v175
	v_rcp_f32_e32 v197, v197
	v_rcp_f32_e32 v176, v176
	v_rcp_f32_e32 v198, v198
	v_rcp_f32_e32 v177, v177
	v_rcp_f32_e32 v199, v199
	v_mul_f32_e32 v112, v174, v112
	v_mul_f32_e32 v113, v196, v113
	v_mul_f32_e32 v114, v175, v114
	v_mul_f32_e32 v115, v197, v115
	v_mul_f32_e32 v108, v176, v108
	v_mul_f32_e32 v109, v198, v109
	v_mul_f32_e32 v110, v177, v110
	v_mul_f32_e32 v111, v199, v111
	global_store_dwordx4 v2, v[112:115], s[72:73]
	global_store_dwordx4 v2, v[108:111], s[72:73] offset:16
	s_waitcnt vmcnt(20)
	v_lshlrev_b32_e32 v174, 16, v200
	v_lshlrev_b32_e32 v175, 16, v201
	v_lshlrev_b32_e32 v176, 16, v202
	v_lshlrev_b32_e32 v177, 16, v203
	v_and_b32_e32 v200, 0xffff0000, v200
	v_and_b32_e32 v201, 0xffff0000, v201
	v_and_b32_e32 v202, 0xffff0000, v202
	v_and_b32_e32 v203, 0xffff0000, v203
	v_mul_f32_e32 v174, 0xbfb8aa3b, v174
	v_mul_f32_e32 v200, 0xbfb8aa3b, v200
	v_mul_f32_e32 v175, 0xbfb8aa3b, v175
	v_mul_f32_e32 v201, 0xbfb8aa3b, v201
	v_mul_f32_e32 v176, 0xbfb8aa3b, v176
	v_mul_f32_e32 v202, 0xbfb8aa3b, v202
	v_mul_f32_e32 v177, 0xbfb8aa3b, v177
	v_mul_f32_e32 v203, 0xbfb8aa3b, v203
	v_exp_f32_e32 v174, v174
	v_exp_f32_e32 v200, v200
	v_exp_f32_e32 v175, v175
	v_exp_f32_e32 v201, v201
	v_exp_f32_e32 v176, v176
	v_exp_f32_e32 v202, v202
	v_exp_f32_e32 v177, v177
	v_exp_f32_e32 v203, v203
	v_add_f32_e32 v174, 1.0, v174
	v_add_f32_e32 v200, 1.0, v200
	v_add_f32_e32 v175, 1.0, v175
	v_add_f32_e32 v201, 1.0, v201
	v_add_f32_e32 v176, 1.0, v176
	v_add_f32_e32 v202, 1.0, v202
	v_add_f32_e32 v177, 1.0, v177
	v_add_f32_e32 v203, 1.0, v203
	v_rcp_f32_e32 v174, v174
	v_rcp_f32_e32 v200, v200
	v_rcp_f32_e32 v175, v175
	v_rcp_f32_e32 v201, v201
	v_rcp_f32_e32 v176, v176
	v_rcp_f32_e32 v202, v202
	v_rcp_f32_e32 v177, v177
	v_rcp_f32_e32 v203, v203
	v_mul_f32_e32 v80, v174, v80
	v_mul_f32_e32 v81, v200, v81
	v_mul_f32_e32 v82, v175, v82
	v_mul_f32_e32 v83, v201, v83
	v_mul_f32_e32 v76, v176, v76
	v_mul_f32_e32 v77, v202, v77
	v_mul_f32_e32 v78, v177, v78
	v_mul_f32_e32 v79, v203, v79
	global_store_dwordx4 v2, v[80:83], s[72:73] offset:512
	global_store_dwordx4 v2, v[76:79], s[72:73] offset:528
	s_add_u32 s72, s72, 0x10000
	s_addc_u32 s73, s73, 0
	s_waitcnt vmcnt(21)
; __device__ __forceinline__ u32x4 pack8(const float (&f)[8]) { u32x4 o; o.x = cvt_pk_bf16(f[0], f[1]); o.y = cvt_pk_bf16(f[2], f[3]); o.z = cvt_pk_bf16(f[4], f[5]); o.w = cvt_pk_bf16(f[6], f[7]); return o; }
; __device__ __forceinline__ float sigmoidf_(float x) { return __builtin_amdgcn_rcpf(1.0f + __expf(-x)); }
;     __device__ __forceinline__ void operator()(const f32x4 (&acc)[2][2][4][2], const Unit& u, int wr, int wc, int fr, int fq) const {
;     ...
;                 for (int bj = 0; bj < 2; ++bj) { const int c = col0 + bj * HALF;
;                     const u32x4 gw = *(const u32x4*)(prow + goff + c); float g[8]; unpack8(gw, g);
;                     const f32x4 v0 = acc[ai][bj][m][0], v1 = acc[ai][bj][m][1];
;                     float o[8];
; #pragma unroll
;                     for (int e = 0; e < 4; ++e) { o[e] = sigmoidf_(g[e]) * v0[e]; o[4 + e] = sigmoidf_(g[4 + e]) * v1[e]; }
;                     if (split) store8f(srow + c, o); else *(u32x4*)(prow + C_MIX + c) = pack8(o); }
	v_lshlrev_b32_e32 v174, 16, v224
	v_lshlrev_b32_e32 v175, 16, v225
	v_lshlrev_b32_e32 v176, 16, v226
	v_lshlrev_b32_e32 v177, 16, v227
	v_and_b32_e32 v224, 0xffff0000, v224
	v_and_b32_e32 v225, 0xffff0000, v225
	v_and_b32_e32 v226, 0xffff0000, v226
	v_and_b32_e32 v227, 0xffff0000, v227
	v_mul_f32_e32 v174, 0xbfb8aa3b, v174
	v_mul_f32_e32 v224, 0xbfb8aa3b, v224
	v_mul_f32_e32 v175, 0xbfb8aa3b, v175
	v_mul_f32_e32 v225, 0xbfb8aa3b, v225
	v_mul_f32_e32 v176, 0xbfb8aa3b, v176
	v_mul_f32_e32 v226, 0xbfb8aa3b, v226
	v_mul_f32_e32 v177, 0xbfb8aa3b, v177
	v_mul_f32_e32 v227, 0xbfb8aa3b, v227
	v_exp_f32_e32 v174, v174
	v_exp_f32_e32 v224, v224
	v_exp_f32_e32 v175, v175
	v_exp_f32_e32 v225, v225
	v_exp_f32_e32 v176, v176
	v_exp_f32_e32 v226, v226
	v_exp_f32_e32 v177, v177
	v_exp_f32_e32 v227, v227
	v_add_f32_e32 v174, 1.0, v174
	v_add_f32_e32 v224, 1.0, v224
	v_add_f32_e32 v175, 1.0, v175
	v_add_f32_e32 v225, 1.0, v225
	v_add_f32_e32 v176, 1.0, v176
	v_add_f32_e32 v226, 1.0, v226
	v_add_f32_e32 v177, 1.0, v177
	v_add_f32_e32 v227, 1.0, v227
	v_rcp_f32_e32 v174, v174
	v_rcp_f32_e32 v224, v224
	v_rcp_f32_e32 v175, v175
	v_rcp_f32_e32 v225, v225
	v_rcp_f32_e32 v176, v176
	v_rcp_f32_e32 v226, v226
	v_rcp_f32_e32 v177, v177
	v_rcp_f32_e32 v227, v227
	v_mul_f32_e32 v104, v174, v104
	v_mul_f32_e32 v105, v224, v105
	v_mul_f32_e32 v106, v175, v106
	v_mul_f32_e32 v107, v225, v107
	v_mul_f32_e32 v100, v176, v100
	v_mul_f32_e32 v101, v226, v101
	v_mul_f32_e32 v102, v177, v102
	v_mul_f32_e32 v103, v227, v103
	global_store_dwordx4 v2, v[104:107], s[72:73]
	global_store_dwordx4 v2, v[100:103], s[72:73] offset:16
	s_waitcnt vmcnt(22)
	v_lshlrev_b32_e32 v174, 16, v228
	v_lshlrev_b32_e32 v175, 16, v229
	v_lshlrev_b32_e32 v176, 16, v230
	v_lshlrev_b32_e32 v177, 16, v231
	v_and_b32_e32 v228, 0xffff0000, v228
	v_and_b32_e32 v229, 0xffff0000, v229
	v_and_b32_e32 v230, 0xffff0000, v230
	v_and_b32_e32 v231, 0xffff0000, v231
	v_mul_f32_e32 v174, 0xbfb8aa3b, v174
	v_mul_f32_e32 v228, 0xbfb8aa3b, v228
	v_mul_f32_e32 v175, 0xbfb8aa3b, v175
	v_mul_f32_e32 v229, 0xbfb8aa3b, v229
	v_mul_f32_e32 v176, 0xbfb8aa3b, v176
	v_mul_f32_e32 v230, 0xbfb8aa3b, v230
	v_mul_f32_e32 v177, 0xbfb8aa3b, v177
	v_mul_f32_e32 v231, 0xbfb8aa3b, v231
	v_exp_f32_e32 v174, v174
	v_exp_f32_e32 v228, v228
	v_exp_f32_e32 v175, v175
	v_exp_f32_e32 v229, v229
	v_exp_f32_e32 v176, v176
	v_exp_f32_e32 v230, v230
	v_exp_f32_e32 v177, v177
	v_exp_f32_e32 v231, v231
	v_add_f32_e32 v174, 1.0, v174
	v_add_f32_e32 v228, 1.0, v228
	v_add_f32_e32 v175, 1.0, v175
	v_add_f32_e32 v229, 1.0, v229
	v_add_f32_e32 v176, 1.0, v176
	v_add_f32_e32 v230, 1.0, v230
	v_add_f32_e32 v177, 1.0, v177
	v_add_f32_e32 v231, 1.0, v231
	v_rcp_f32_e32 v174, v174
	v_rcp_f32_e32 v228, v228
	v_rcp_f32_e32 v175, v175
	v_rcp_f32_e32 v229, v229
	v_rcp_f32_e32 v176, v176
	v_rcp_f32_e32 v230, v230
	v_rcp_f32_e32 v177, v177
	v_rcp_f32_e32 v231, v231
	v_mul_f32_e32 v72, v174, v72
	v_mul_f32_e32 v73, v228, v73
	v_mul_f32_e32 v74, v175, v74
	v_mul_f32_e32 v75, v229, v75
	v_mul_f32_e32 v68, v176, v68
	v_mul_f32_e32 v69, v230, v69
	v_mul_f32_e32 v70, v177, v70
	v_mul_f32_e32 v71, v231, v71
	global_store_dwordx4 v2, v[72:75], s[72:73] offset:512
	global_store_dwordx4 v2, v[68:71], s[72:73] offset:528
	s_add_u32 s72, s72, 0x50000
	s_addc_u32 s73, s73, 0
	s_waitcnt vmcnt(23)
	v_lshlrev_b32_e32 v174, 16, v232
	v_lshlrev_b32_e32 v175, 16, v233
	v_lshlrev_b32_e32 v176, 16, v234
	v_lshlrev_b32_e32 v177, 16, v235
	v_and_b32_e32 v232, 0xffff0000, v232
	v_and_b32_e32 v233, 0xffff0000, v233
	v_and_b32_e32 v234, 0xffff0000, v234
	v_and_b32_e32 v235, 0xffff0000, v235
	v_mul_f32_e32 v174, 0xbfb8aa3b, v174
	v_mul_f32_e32 v232, 0xbfb8aa3b, v232
	v_mul_f32_e32 v175, 0xbfb8aa3b, v175
	v_mul_f32_e32 v233, 0xbfb8aa3b, v233
	v_mul_f32_e32 v176, 0xbfb8aa3b, v176
	v_mul_f32_e32 v234, 0xbfb8aa3b, v234
	v_mul_f32_e32 v177, 0xbfb8aa3b, v177
	v_mul_f32_e32 v235, 0xbfb8aa3b, v235
	v_exp_f32_e32 v174, v174
	v_exp_f32_e32 v232, v232
	v_exp_f32_e32 v175, v175
	v_exp_f32_e32 v233, v233
	v_exp_f32_e32 v176, v176
	v_exp_f32_e32 v234, v234
	v_exp_f32_e32 v177, v177
	v_exp_f32_e32 v235, v235
	v_add_f32_e32 v174, 1.0, v174
	v_add_f32_e32 v232, 1.0, v232
	v_add_f32_e32 v175, 1.0, v175
	v_add_f32_e32 v233, 1.0, v233
	v_add_f32_e32 v176, 1.0, v176
	v_add_f32_e32 v234, 1.0, v234
	v_add_f32_e32 v177, 1.0, v177
	v_add_f32_e32 v235, 1.0, v235
	v_rcp_f32_e32 v174, v174
	v_rcp_f32_e32 v232, v232
	v_rcp_f32_e32 v175, v175
	v_rcp_f32_e32 v233, v233
	v_rcp_f32_e32 v176, v176
	v_rcp_f32_e32 v234, v234
	v_rcp_f32_e32 v177, v177
	v_rcp_f32_e32 v235, v235
	v_mul_f32_e32 v64, v174, v64
	v_mul_f32_e32 v65, v232, v65
	v_mul_f32_e32 v66, v175, v66
	v_mul_f32_e32 v67, v233, v67
	v_mul_f32_e32 v60, v176, v60
	v_mul_f32_e32 v61, v234, v61
	v_mul_f32_e32 v62, v177, v62
	v_mul_f32_e32 v63, v235, v63
	global_store_dwordx4 v2, v[64:67], s[72:73]
	global_store_dwordx4 v2, v[60:63], s[72:73] offset:16
	s_waitcnt vmcnt(24)
; __device__ __forceinline__ u32x4 pack8(const float (&f)[8]) { u32x4 o; o.x = cvt_pk_bf16(f[0], f[1]); o.y = cvt_pk_bf16(f[2], f[3]); o.z = cvt_pk_bf16(f[4], f[5]); o.w = cvt_pk_bf16(f[6], f[7]); return o; }
; __device__ __forceinline__ float sigmoidf_(float x) { return __builtin_amdgcn_rcpf(1.0f + __expf(-x)); }
;     __device__ __forceinline__ void operator()(const f32x4 (&acc)[2][2][4][2], const Unit& u, int wr, int wc, int fr, int fq) const {
;     ...
;                 for (int bj = 0; bj < 2; ++bj) { const int c = col0 + bj * HALF;
;                     const u32x4 gw = *(const u32x4*)(prow + goff + c); float g[8]; unpack8(gw, g);
;                     const f32x4 v0 = acc[ai][bj][m][0], v1 = acc[ai][bj][m][1];
;                     float o[8];
; #pragma unroll
;                     for (int e = 0; e < 4; ++e) { o[e] = sigmoidf_(g[e]) * v0[e]; o[4 + e] = sigmoidf_(g[4 + e]) * v1[e]; }
;                     if (split) store8f(srow + c, o); else *(u32x4*)(prow + C_MIX + c) = pack8(o); }
	v_lshlrev_b32_e32 v174, 16, v236
	v_lshlrev_b32_e32 v175, 16, v237
	v_lshlrev_b32_e32 v176, 16, v238
	v_lshlrev_b32_e32 v177, 16, v239
	v_and_b32_e32 v236, 0xffff0000, v236
	v_and_b32_e32 v237, 0xffff0000, v237
	v_and_b32_e32 v238, 0xffff0000, v238
	v_and_b32_e32 v239, 0xffff0000, v239
	v_mul_f32_e32 v174, 0xbfb8aa3b, v174
	v_mul_f32_e32 v236, 0xbfb8aa3b, v236
	v_mul_f32_e32 v175, 0xbfb8aa3b, v175
	v_mul_f32_e32 v237, 0xbfb8aa3b, v237
	v_mul_f32_e32 v176, 0xbfb8aa3b, v176
	v_mul_f32_e32 v238, 0xbfb8aa3b, v238
	v_mul_f32_e32 v177, 0xbfb8aa3b, v177
	v_mul_f32_e32 v239, 0xbfb8aa3b, v239
	v_exp_f32_e32 v174, v174
	v_exp_f32_e32 v236, v236
	v_exp_f32_e32 v175, v175
	v_exp_f32_e32 v237, v237
	v_exp_f32_e32 v176, v176
	v_exp_f32_e32 v238, v238
	v_exp_f32_e32 v177, v177
	v_exp_f32_e32 v239, v239
	v_add_f32_e32 v174, 1.0, v174
	v_add_f32_e32 v236, 1.0, v236
	v_add_f32_e32 v175, 1.0, v175
	v_add_f32_e32 v237, 1.0, v237
	v_add_f32_e32 v176, 1.0, v176
	v_add_f32_e32 v238, 1.0, v238
	v_add_f32_e32 v177, 1.0, v177
	v_add_f32_e32 v239, 1.0, v239
	v_rcp_f32_e32 v174, v174
	v_rcp_f32_e32 v236, v236
	v_rcp_f32_e32 v175, v175
	v_rcp_f32_e32 v237, v237
	v_rcp_f32_e32 v176, v176
	v_rcp_f32_e32 v238, v238
	v_rcp_f32_e32 v177, v177
	v_rcp_f32_e32 v239, v239
	v_mul_f32_e32 v32, v174, v32
	v_mul_f32_e32 v33, v236, v33
	v_mul_f32_e32 v34, v175, v34
	v_mul_f32_e32 v35, v237, v35
	v_mul_f32_e32 v28, v176, v28
	v_mul_f32_e32 v29, v238, v29
	v_mul_f32_e32 v30, v177, v30
	v_mul_f32_e32 v31, v239, v31
	global_store_dwordx4 v2, v[32:35], s[72:73] offset:512
	global_store_dwordx4 v2, v[28:31], s[72:73] offset:528
	s_add_u32 s72, s72, 0x10000
	s_addc_u32 s73, s73, 0
	s_waitcnt vmcnt(25)
	v_lshlrev_b32_e32 v174, 16, v240
	v_lshlrev_b32_e32 v175, 16, v241
	v_lshlrev_b32_e32 v176, 16, v242
	v_lshlrev_b32_e32 v177, 16, v243
	v_and_b32_e32 v240, 0xffff0000, v240
	v_and_b32_e32 v241, 0xffff0000, v241
	v_and_b32_e32 v242, 0xffff0000, v242
	v_and_b32_e32 v243, 0xffff0000, v243
	v_mul_f32_e32 v174, 0xbfb8aa3b, v174
	v_mul_f32_e32 v240, 0xbfb8aa3b, v240
	v_mul_f32_e32 v175, 0xbfb8aa3b, v175
	v_mul_f32_e32 v241, 0xbfb8aa3b, v241
	v_mul_f32_e32 v176, 0xbfb8aa3b, v176
	v_mul_f32_e32 v242, 0xbfb8aa3b, v242
	v_mul_f32_e32 v177, 0xbfb8aa3b, v177
	v_mul_f32_e32 v243, 0xbfb8aa3b, v243
	v_exp_f32_e32 v174, v174
	v_exp_f32_e32 v240, v240
	v_exp_f32_e32 v175, v175
	v_exp_f32_e32 v241, v241
	v_exp_f32_e32 v176, v176
	v_exp_f32_e32 v242, v242
	v_exp_f32_e32 v177, v177
	v_exp_f32_e32 v243, v243
	v_add_f32_e32 v174, 1.0, v174
	v_add_f32_e32 v240, 1.0, v240
	v_add_f32_e32 v175, 1.0, v175
	v_add_f32_e32 v241, 1.0, v241
	v_add_f32_e32 v176, 1.0, v176
	v_add_f32_e32 v242, 1.0, v242
	v_add_f32_e32 v177, 1.0, v177
	v_add_f32_e32 v243, 1.0, v243
	v_rcp_f32_e32 v174, v174
	v_rcp_f32_e32 v240, v240
	v_rcp_f32_e32 v175, v175
	v_rcp_f32_e32 v241, v241
	v_rcp_f32_e32 v176, v176
	v_rcp_f32_e32 v242, v242
	v_rcp_f32_e32 v177, v177
	v_rcp_f32_e32 v243, v243
	v_mul_f32_e32 v56, v174, v56
	v_mul_f32_e32 v57, v240, v57
	v_mul_f32_e32 v58, v175, v58
	v_mul_f32_e32 v59, v241, v59
	v_mul_f32_e32 v52, v176, v52
	v_mul_f32_e32 v53, v242, v53
	v_mul_f32_e32 v54, v177, v54
	v_mul_f32_e32 v55, v243, v55
	global_store_dwordx4 v2, v[56:59], s[72:73]
	global_store_dwordx4 v2, v[52:55], s[72:73] offset:16
	s_waitcnt vmcnt(26)
	v_lshlrev_b32_e32 v174, 16, v244
	v_lshlrev_b32_e32 v175, 16, v245
	v_lshlrev_b32_e32 v176, 16, v246
	v_lshlrev_b32_e32 v177, 16, v247
	v_and_b32_e32 v244, 0xffff0000, v244
	v_and_b32_e32 v245, 0xffff0000, v245
	v_and_b32_e32 v246, 0xffff0000, v246
	v_and_b32_e32 v247, 0xffff0000, v247
	v_mul_f32_e32 v174, 0xbfb8aa3b, v174
	v_mul_f32_e32 v244, 0xbfb8aa3b, v244
	v_mul_f32_e32 v175, 0xbfb8aa3b, v175
	v_mul_f32_e32 v245, 0xbfb8aa3b, v245
	v_mul_f32_e32 v176, 0xbfb8aa3b, v176
	v_mul_f32_e32 v246, 0xbfb8aa3b, v246
	v_mul_f32_e32 v177, 0xbfb8aa3b, v177
	v_mul_f32_e32 v247, 0xbfb8aa3b, v247
	v_exp_f32_e32 v174, v174
	v_exp_f32_e32 v244, v244
	v_exp_f32_e32 v175, v175
	v_exp_f32_e32 v245, v245
	v_exp_f32_e32 v176, v176
	v_exp_f32_e32 v246, v246
	v_exp_f32_e32 v177, v177
	v_exp_f32_e32 v247, v247
	v_add_f32_e32 v174, 1.0, v174
	v_add_f32_e32 v244, 1.0, v244
	v_add_f32_e32 v175, 1.0, v175
	v_add_f32_e32 v245, 1.0, v245
	v_add_f32_e32 v176, 1.0, v176
	v_add_f32_e32 v246, 1.0, v246
	v_add_f32_e32 v177, 1.0, v177
	v_add_f32_e32 v247, 1.0, v247
	v_rcp_f32_e32 v174, v174
	v_rcp_f32_e32 v244, v244
	v_rcp_f32_e32 v175, v175
	v_rcp_f32_e32 v245, v245
	v_rcp_f32_e32 v176, v176
	v_rcp_f32_e32 v246, v246
	v_rcp_f32_e32 v177, v177
	v_rcp_f32_e32 v247, v247
	v_mul_f32_e32 v24, v174, v24
	v_mul_f32_e32 v25, v244, v25
	v_mul_f32_e32 v26, v175, v26
	v_mul_f32_e32 v27, v245, v27
	v_mul_f32_e32 v20, v176, v20
	v_mul_f32_e32 v21, v246, v21
	v_mul_f32_e32 v22, v177, v22
	v_mul_f32_e32 v23, v247, v23
	global_store_dwordx4 v2, v[24:27], s[72:73] offset:512
	global_store_dwordx4 v2, v[20:23], s[72:73] offset:528
	s_add_u32 s72, s72, 0x10000
	s_addc_u32 s73, s73, 0
	s_waitcnt vmcnt(27)
; __device__ __forceinline__ u32x4 pack8(const float (&f)[8]) { u32x4 o; o.x = cvt_pk_bf16(f[0], f[1]); o.y = cvt_pk_bf16(f[2], f[3]); o.z = cvt_pk_bf16(f[4], f[5]); o.w = cvt_pk_bf16(f[6], f[7]); return o; }
; __device__ __forceinline__ float sigmoidf_(float x) { return __builtin_amdgcn_rcpf(1.0f + __expf(-x)); }
;     __device__ __forceinline__ void operator()(const f32x4 (&acc)[2][2][4][2], const Unit& u, int wr, int wc, int fr, int fq) const {
;     ...
;                 for (int bj = 0; bj < 2; ++bj) { const int c = col0 + bj * HALF;
;                     const u32x4 gw = *(const u32x4*)(prow + goff + c); float g[8]; unpack8(gw, g);
;                     const f32x4 v0 = acc[ai][bj][m][0], v1 = acc[ai][bj][m][1];
;                     float o[8];
; #pragma unroll
;                     for (int e = 0; e < 4; ++e) { o[e] = sigmoidf_(g[e]) * v0[e]; o[4 + e] = sigmoidf_(g[4 + e]) * v1[e]; }
;                     if (split) store8f(srow + c, o); else *(u32x4*)(prow + C_MIX + c) = pack8(o); }
	v_lshlrev_b32_e32 v174, 16, v248
	v_lshlrev_b32_e32 v175, 16, v249
	v_lshlrev_b32_e32 v176, 16, v250
	v_lshlrev_b32_e32 v177, 16, v251
	v_and_b32_e32 v248, 0xffff0000, v248
	v_and_b32_e32 v249, 0xffff0000, v249
	v_and_b32_e32 v250, 0xffff0000, v250
	v_and_b32_e32 v251, 0xffff0000, v251
	v_mul_f32_e32 v174, 0xbfb8aa3b, v174
	v_mul_f32_e32 v248, 0xbfb8aa3b, v248
	v_mul_f32_e32 v175, 0xbfb8aa3b, v175
	v_mul_f32_e32 v249, 0xbfb8aa3b, v249
	v_mul_f32_e32 v176, 0xbfb8aa3b, v176
	v_mul_f32_e32 v250, 0xbfb8aa3b, v250
	v_mul_f32_e32 v177, 0xbfb8aa3b, v177
	v_mul_f32_e32 v251, 0xbfb8aa3b, v251
	v_exp_f32_e32 v174, v174
	v_exp_f32_e32 v248, v248
	v_exp_f32_e32 v175, v175
	v_exp_f32_e32 v249, v249
	v_exp_f32_e32 v176, v176
	v_exp_f32_e32 v250, v250
	v_exp_f32_e32 v177, v177
	v_exp_f32_e32 v251, v251
	v_add_f32_e32 v174, 1.0, v174
	v_add_f32_e32 v248, 1.0, v248
	v_add_f32_e32 v175, 1.0, v175
	v_add_f32_e32 v249, 1.0, v249
	v_add_f32_e32 v176, 1.0, v176
	v_add_f32_e32 v250, 1.0, v250
	v_add_f32_e32 v177, 1.0, v177
	v_add_f32_e32 v251, 1.0, v251
	v_rcp_f32_e32 v174, v174
	v_rcp_f32_e32 v248, v248
	v_rcp_f32_e32 v175, v175
	v_rcp_f32_e32 v249, v249
	v_rcp_f32_e32 v176, v176
	v_rcp_f32_e32 v250, v250
	v_rcp_f32_e32 v177, v177
	v_rcp_f32_e32 v251, v251
	v_mul_f32_e32 v48, v174, v48
	v_mul_f32_e32 v49, v248, v49
	v_mul_f32_e32 v50, v175, v50
	v_mul_f32_e32 v51, v249, v51
	v_mul_f32_e32 v44, v176, v44
	v_mul_f32_e32 v45, v250, v45
	v_mul_f32_e32 v46, v177, v46
	v_mul_f32_e32 v47, v251, v47
	global_store_dwordx4 v2, v[48:51], s[72:73]
	global_store_dwordx4 v2, v[44:47], s[72:73] offset:16
	s_waitcnt vmcnt(28)
	v_lshlrev_b32_e32 v174, 16, v132
	v_lshlrev_b32_e32 v175, 16, v133
	v_lshlrev_b32_e32 v176, 16, v134
	v_lshlrev_b32_e32 v177, 16, v135
	v_and_b32_e32 v132, 0xffff0000, v132
	v_and_b32_e32 v133, 0xffff0000, v133
	v_and_b32_e32 v134, 0xffff0000, v134
	v_and_b32_e32 v135, 0xffff0000, v135
	v_mul_f32_e32 v174, 0xbfb8aa3b, v174
	v_mul_f32_e32 v132, 0xbfb8aa3b, v132
	v_mul_f32_e32 v175, 0xbfb8aa3b, v175
	v_mul_f32_e32 v133, 0xbfb8aa3b, v133
	v_mul_f32_e32 v176, 0xbfb8aa3b, v176
	v_mul_f32_e32 v134, 0xbfb8aa3b, v134
	v_mul_f32_e32 v177, 0xbfb8aa3b, v177
	v_mul_f32_e32 v135, 0xbfb8aa3b, v135
	v_exp_f32_e32 v174, v174
	v_exp_f32_e32 v132, v132
	v_exp_f32_e32 v175, v175
	v_exp_f32_e32 v133, v133
	v_exp_f32_e32 v176, v176
	v_exp_f32_e32 v134, v134
	v_exp_f32_e32 v177, v177
	v_exp_f32_e32 v135, v135
	v_add_f32_e32 v174, 1.0, v174
	v_add_f32_e32 v132, 1.0, v132
	v_add_f32_e32 v175, 1.0, v175
	v_add_f32_e32 v133, 1.0, v133
	v_add_f32_e32 v176, 1.0, v176
	v_add_f32_e32 v134, 1.0, v134
	v_add_f32_e32 v177, 1.0, v177
	v_add_f32_e32 v135, 1.0, v135
	v_rcp_f32_e32 v174, v174
	v_rcp_f32_e32 v132, v132
	v_rcp_f32_e32 v175, v175
	v_rcp_f32_e32 v133, v133
	v_rcp_f32_e32 v176, v176
	v_rcp_f32_e32 v134, v134
	v_rcp_f32_e32 v177, v177
	v_rcp_f32_e32 v135, v135
	v_mul_f32_e32 v16, v174, v16
	v_mul_f32_e32 v17, v132, v17
	v_mul_f32_e32 v18, v175, v18
	v_mul_f32_e32 v19, v133, v19
	v_mul_f32_e32 v12, v176, v12
	v_mul_f32_e32 v13, v134, v13
	v_mul_f32_e32 v14, v177, v14
	v_mul_f32_e32 v15, v135, v15
	global_store_dwordx4 v2, v[16:19], s[72:73] offset:512
	global_store_dwordx4 v2, v[12:15], s[72:73] offset:528
	s_add_u32 s72, s72, 0x10000
	s_addc_u32 s73, s73, 0
	s_waitcnt vmcnt(29)
	v_lshlrev_b32_e32 v174, 16, v136
	v_lshlrev_b32_e32 v175, 16, v137
	v_lshlrev_b32_e32 v176, 16, v138
	v_lshlrev_b32_e32 v177, 16, v139
	v_and_b32_e32 v136, 0xffff0000, v136
	v_and_b32_e32 v137, 0xffff0000, v137
	v_and_b32_e32 v138, 0xffff0000, v138
	v_and_b32_e32 v139, 0xffff0000, v139
	v_mul_f32_e32 v174, 0xbfb8aa3b, v174
	v_mul_f32_e32 v136, 0xbfb8aa3b, v136
	v_mul_f32_e32 v175, 0xbfb8aa3b, v175
	v_mul_f32_e32 v137, 0xbfb8aa3b, v137
	v_mul_f32_e32 v176, 0xbfb8aa3b, v176
	v_mul_f32_e32 v138, 0xbfb8aa3b, v138
	v_mul_f32_e32 v177, 0xbfb8aa3b, v177
	v_mul_f32_e32 v139, 0xbfb8aa3b, v139
	v_exp_f32_e32 v174, v174
	v_exp_f32_e32 v136, v136
	v_exp_f32_e32 v175, v175
	v_exp_f32_e32 v137, v137
	v_exp_f32_e32 v176, v176
	v_exp_f32_e32 v138, v138
	v_exp_f32_e32 v177, v177
	v_exp_f32_e32 v139, v139
	v_add_f32_e32 v174, 1.0, v174
	v_add_f32_e32 v136, 1.0, v136
	v_add_f32_e32 v175, 1.0, v175
	v_add_f32_e32 v137, 1.0, v137
	v_add_f32_e32 v176, 1.0, v176
	v_add_f32_e32 v138, 1.0, v138
	v_add_f32_e32 v177, 1.0, v177
	v_add_f32_e32 v139, 1.0, v139
	v_rcp_f32_e32 v174, v174
	v_rcp_f32_e32 v136, v136
	v_rcp_f32_e32 v175, v175
	v_rcp_f32_e32 v137, v137
	v_rcp_f32_e32 v176, v176
	v_rcp_f32_e32 v138, v138
	v_rcp_f32_e32 v177, v177
	v_rcp_f32_e32 v139, v139
	v_mul_f32_e32 v40, v174, v40
	v_mul_f32_e32 v41, v136, v41
	v_mul_f32_e32 v42, v175, v42
	v_mul_f32_e32 v43, v137, v43
	v_mul_f32_e32 v36, v176, v36
	v_mul_f32_e32 v37, v138, v37
	v_mul_f32_e32 v38, v177, v38
	v_mul_f32_e32 v39, v139, v39
	global_store_dwordx4 v2, v[40:43], s[72:73]
	global_store_dwordx4 v2, v[36:39], s[72:73] offset:16
	s_waitcnt vmcnt(30)
	v_lshlrev_b32_e32 v174, 16, v170
	v_lshlrev_b32_e32 v175, 16, v171
	v_lshlrev_b32_e32 v176, 16, v172
	v_lshlrev_b32_e32 v177, 16, v173
	v_and_b32_e32 v170, 0xffff0000, v170
	v_and_b32_e32 v171, 0xffff0000, v171
	v_and_b32_e32 v172, 0xffff0000, v172
	v_and_b32_e32 v173, 0xffff0000, v173
	v_mul_f32_e32 v174, 0xbfb8aa3b, v174
	v_mul_f32_e32 v170, 0xbfb8aa3b, v170
	v_mul_f32_e32 v175, 0xbfb8aa3b, v175
	v_mul_f32_e32 v171, 0xbfb8aa3b, v171
	v_mul_f32_e32 v176, 0xbfb8aa3b, v176
	v_mul_f32_e32 v172, 0xbfb8aa3b, v172
	v_mul_f32_e32 v177, 0xbfb8aa3b, v177
	v_mul_f32_e32 v173, 0xbfb8aa3b, v173
	v_exp_f32_e32 v174, v174
	v_exp_f32_e32 v170, v170
	v_exp_f32_e32 v175, v175
	v_exp_f32_e32 v171, v171
	v_exp_f32_e32 v176, v176
	v_exp_f32_e32 v172, v172
	v_exp_f32_e32 v177, v177
	v_exp_f32_e32 v173, v173
	v_add_f32_e32 v174, 1.0, v174
	v_add_f32_e32 v170, 1.0, v170
	v_add_f32_e32 v175, 1.0, v175
	v_add_f32_e32 v171, 1.0, v171
	v_add_f32_e32 v176, 1.0, v176
	v_add_f32_e32 v172, 1.0, v172
	v_add_f32_e32 v177, 1.0, v177
	v_add_f32_e32 v173, 1.0, v173
	v_rcp_f32_e32 v174, v174
	v_rcp_f32_e32 v170, v170
	v_rcp_f32_e32 v175, v175
	v_rcp_f32_e32 v171, v171
	v_rcp_f32_e32 v176, v176
	v_rcp_f32_e32 v172, v172
	v_rcp_f32_e32 v177, v177
	v_rcp_f32_e32 v173, v173
	v_mul_f32_e32 v8, v174, v8
	v_mul_f32_e32 v9, v170, v9
	v_mul_f32_e32 v10, v175, v10
	v_mul_f32_e32 v11, v171, v11
	v_mul_f32_e32 v4, v176, v4
	v_mul_f32_e32 v5, v172, v5
	v_mul_f32_e32 v6, v177, v6
	v_mul_f32_e32 v7, v173, v7
	global_store_dwordx4 v2, v[8:11], s[72:73] offset:512
	global_store_dwordx4 v2, v[4:7], s[72:73] offset:528
	s_branch .LBB0_579
;     __device__ __forceinline__ void mid(f32x4 (&acc)[2][2][4][2], const Unit& u, int wr, int wc, int fr, int fq) const {
;         const int row0 = u.pm * BM + wr * 64 + fr, col0 = u.pn * BM + wc * 32 + 8 * fq;
; #pragma unroll
;         for (int ai = 0; ai < 2; ++ai)
; #pragma unroll
;             for (int m = 0; m < 4; ++m) { const bf16_t* prow = P + (size_t)(row0 + ai * HALF + m * 16) * DP;
; #pragma unroll
;                 for (int bj = 0; bj < 2; ++bj) { const int c = col0 + bj * HALF;
;                     float ga[8], gb[8]; unpack8(__builtin_nontemporal_load((const u32x4*)(prow + C_MA + c)), ga); unpack8(*(const u32x4*)(prow + C_MB + c), gb);
; #pragma unroll
;                     for (int e = 0; e < 4; ++e) { acc[ai][bj][m][0][e] *= (1.0f + __expf(-gb[e])) * __builtin_amdgcn_rcpf(1.0f + __expf(-ga[e]));
;                                                   acc[ai][bj][m][1][e] *= (1.0f + __expf(-gb[4 + e])) * __builtin_amdgcn_rcpf(1.0f + __expf(-ga[4 + e])); } }
;                 asm volatile("" ::: "memory"); }
.Lab_mid:
	v_add_u32_e32 v0, s15, v148
	v_mul_lo_u32 v0, v0, s33
	v_lshl_or_b32 v3, s66, 8, v149
	v_lshl_add_u32 v0, v3, 1, v0
	s_add_u32 s68, s8, 0x800
	s_addc_u32 s69, s9, 0
	s_add_u32 s72, s8, 0x2000
	s_addc_u32 s73, s9, 0
	global_load_dwordx4 v[180:183], v0, s[68:69] nt
	global_load_dwordx4 v[232:235], v0, s[72:73]
	global_load_dwordx4 v[184:187], v0, s[68:69] offset:256 nt
	global_load_dwordx4 v[236:239], v0, s[72:73] offset:256
	s_add_u32 s68, s68, 0x28000
	s_addc_u32 s69, s69, 0
	s_add_u32 s72, s72, 0x28000
	s_addc_u32 s73, s73, 0
	global_load_dwordx4 v[188:191], v0, s[68:69] nt
	global_load_dwordx4 v[240:243], v0, s[72:73]
	global_load_dwordx4 v[192:195], v0, s[68:69] offset:256 nt
	global_load_dwordx4 v[244:247], v0, s[72:73] offset:256
	s_add_u32 s68, s68, 0x28000
	s_addc_u32 s69, s69, 0
	s_add_u32 s72, s72, 0x28000
	s_addc_u32 s73, s73, 0
	global_load_dwordx4 v[196:199], v0, s[68:69] nt
	global_load_dwordx4 v[248:251], v0, s[72:73]
	global_load_dwordx4 v[200:203], v0, s[68:69] offset:256 nt
	global_load_dwordx4 v[132:135], v0, s[72:73] offset:256
	s_add_u32 s68, s68, 0x28000
	s_addc_u32 s69, s69, 0
	s_add_u32 s72, s72, 0x28000
	s_addc_u32 s73, s73, 0
	global_load_dwordx4 v[224:227], v0, s[68:69] nt
	global_load_dwordx4 v[136:139], v0, s[72:73]
	global_load_dwordx4 v[228:231], v0, s[68:69] offset:256 nt
	global_load_dwordx4 v[170:173], v0, s[72:73] offset:256
	s_waitcnt vmcnt(14)
	v_lshlrev_b32_e32 v174, 16, v180
	v_lshlrev_b32_e32 v175, 16, v181
	v_lshlrev_b32_e32 v176, 16, v182
	v_lshlrev_b32_e32 v177, 16, v183
	v_and_b32_e32 v180, 0xffff0000, v180
	v_and_b32_e32 v181, 0xffff0000, v181
	v_and_b32_e32 v182, 0xffff0000, v182
	v_and_b32_e32 v183, 0xffff0000, v183
	v_lshlrev_b32_e32 v205, 16, v232
	v_lshlrev_b32_e32 v206, 16, v233
	v_lshlrev_b32_e32 v208, 16, v234
	v_lshlrev_b32_e32 v210, 16, v235
	v_and_b32_e32 v232, 0xffff0000, v232
	v_and_b32_e32 v233, 0xffff0000, v233
	v_and_b32_e32 v234, 0xffff0000, v234
	v_and_b32_e32 v235, 0xffff0000, v235
	v_mul_f32_e32 v174, 0xbfb8aa3b, v174
	v_mul_f32_e32 v180, 0xbfb8aa3b, v180
	v_mul_f32_e32 v175, 0xbfb8aa3b, v175
	v_mul_f32_e32 v181, 0xbfb8aa3b, v181
	v_mul_f32_e32 v176, 0xbfb8aa3b, v176
	v_mul_f32_e32 v182, 0xbfb8aa3b, v182
	v_mul_f32_e32 v177, 0xbfb8aa3b, v177
	v_mul_f32_e32 v183, 0xbfb8aa3b, v183
	v_mul_f32_e32 v205, 0xbfb8aa3b, v205
	v_mul_f32_e32 v232, 0xbfb8aa3b, v232
	v_mul_f32_e32 v206, 0xbfb8aa3b, v206
	v_mul_f32_e32 v233, 0xbfb8aa3b, v233
	v_mul_f32_e32 v208, 0xbfb8aa3b, v208
	v_mul_f32_e32 v234, 0xbfb8aa3b, v234
	v_mul_f32_e32 v210, 0xbfb8aa3b, v210
	v_mul_f32_e32 v235, 0xbfb8aa3b, v235
	v_exp_f32_e32 v174, v174
	v_exp_f32_e32 v180, v180
	v_exp_f32_e32 v175, v175
	v_exp_f32_e32 v181, v181
	v_exp_f32_e32 v176, v176
	v_exp_f32_e32 v182, v182
	v_exp_f32_e32 v177, v177
	v_exp_f32_e32 v183, v183
	v_exp_f32_e32 v205, v205
	v_exp_f32_e32 v232, v232
	v_exp_f32_e32 v206, v206
	v_exp_f32_e32 v233, v233
	v_exp_f32_e32 v208, v208
	v_exp_f32_e32 v234, v234
	v_exp_f32_e32 v210, v210
	v_exp_f32_e32 v235, v235
	v_add_f32_e32 v174, 1.0, v174
	v_add_f32_e32 v180, 1.0, v180
	v_add_f32_e32 v175, 1.0, v175
	v_add_f32_e32 v181, 1.0, v181
	v_add_f32_e32 v176, 1.0, v176
	v_add_f32_e32 v182, 1.0, v182
	v_add_f32_e32 v177, 1.0, v177
	v_add_f32_e32 v183, 1.0, v183
	v_add_f32_e32 v205, 1.0, v205
	v_add_f32_e32 v232, 1.0, v232
	v_add_f32_e32 v206, 1.0, v206
	v_add_f32_e32 v233, 1.0, v233
	v_add_f32_e32 v208, 1.0, v208
	v_add_f32_e32 v234, 1.0, v234
	v_add_f32_e32 v210, 1.0, v210
	v_add_f32_e32 v235, 1.0, v235
	v_rcp_f32_e32 v174, v174
	v_rcp_f32_e32 v180, v180
	v_rcp_f32_e32 v175, v175
	v_rcp_f32_e32 v181, v181
	v_rcp_f32_e32 v176, v176
	v_rcp_f32_e32 v182, v182
	v_rcp_f32_e32 v177, v177
	v_rcp_f32_e32 v183, v183
	v_mul_f32_e32 v205, v205, v174
	v_mul_f32_e32 v232, v232, v180
	v_mul_f32_e32 v206, v206, v175
	v_mul_f32_e32 v233, v233, v181
	v_mul_f32_e32 v208, v208, v176
	v_mul_f32_e32 v234, v234, v182
	v_mul_f32_e32 v210, v210, v177
	v_mul_f32_e32 v235, v235, v183
	v_mul_f32_e32 v128, v128, v205
	v_mul_f32_e32 v129, v129, v232
	v_mul_f32_e32 v130, v130, v206
	v_mul_f32_e32 v131, v131, v233
	v_mul_f32_e32 v124, v124, v208
	v_mul_f32_e32 v125, v125, v234
	v_mul_f32_e32 v126, v126, v210
	v_mul_f32_e32 v127, v127, v235
	s_waitcnt vmcnt(12)
;     __device__ __forceinline__ void mid(f32x4 (&acc)[2][2][4][2], const Unit& u, int wr, int wc, int fr, int fq) const {
;     ...
;             for (int m = 0; m < 4; ++m) { const bf16_t* prow = P + (size_t)(row0 + ai * HALF + m * 16) * DP;
; #pragma unroll
;                 for (int bj = 0; bj < 2; ++bj) { const int c = col0 + bj * HALF;
;                     float ga[8], gb[8]; unpack8(__builtin_nontemporal_load((const u32x4*)(prow + C_MA + c)), ga); unpack8(*(const u32x4*)(prow + C_MB + c), gb);
; #pragma unroll
;                     for (int e = 0; e < 4; ++e) { acc[ai][bj][m][0][e] *= (1.0f + __expf(-gb[e])) * __builtin_amdgcn_rcpf(1.0f + __expf(-ga[e]));
;                                                   acc[ai][bj][m][1][e] *= (1.0f + __expf(-gb[4 + e])) * __builtin_amdgcn_rcpf(1.0f + __expf(-ga[4 + e])); } }
	v_lshlrev_b32_e32 v174, 16, v184
	v_lshlrev_b32_e32 v175, 16, v185
	v_lshlrev_b32_e32 v176, 16, v186
	v_lshlrev_b32_e32 v177, 16, v187
	v_and_b32_e32 v184, 0xffff0000, v184
	v_and_b32_e32 v185, 0xffff0000, v185
	v_and_b32_e32 v186, 0xffff0000, v186
	v_and_b32_e32 v187, 0xffff0000, v187
	v_lshlrev_b32_e32 v205, 16, v236
	v_lshlrev_b32_e32 v206, 16, v237
	v_lshlrev_b32_e32 v208, 16, v238
	v_lshlrev_b32_e32 v210, 16, v239
	v_and_b32_e32 v236, 0xffff0000, v236
	v_and_b32_e32 v237, 0xffff0000, v237
	v_and_b32_e32 v238, 0xffff0000, v238
	v_and_b32_e32 v239, 0xffff0000, v239
	v_mul_f32_e32 v174, 0xbfb8aa3b, v174
	v_mul_f32_e32 v184, 0xbfb8aa3b, v184
	v_mul_f32_e32 v175, 0xbfb8aa3b, v175
	v_mul_f32_e32 v185, 0xbfb8aa3b, v185
	v_mul_f32_e32 v176, 0xbfb8aa3b, v176
	v_mul_f32_e32 v186, 0xbfb8aa3b, v186
	v_mul_f32_e32 v177, 0xbfb8aa3b, v177
	v_mul_f32_e32 v187, 0xbfb8aa3b, v187
	v_mul_f32_e32 v205, 0xbfb8aa3b, v205
	v_mul_f32_e32 v236, 0xbfb8aa3b, v236
	v_mul_f32_e32 v206, 0xbfb8aa3b, v206
	v_mul_f32_e32 v237, 0xbfb8aa3b, v237
	v_mul_f32_e32 v208, 0xbfb8aa3b, v208
	v_mul_f32_e32 v238, 0xbfb8aa3b, v238
	v_mul_f32_e32 v210, 0xbfb8aa3b, v210
	v_mul_f32_e32 v239, 0xbfb8aa3b, v239
	v_exp_f32_e32 v174, v174
	v_exp_f32_e32 v184, v184
	v_exp_f32_e32 v175, v175
	v_exp_f32_e32 v185, v185
	v_exp_f32_e32 v176, v176
	v_exp_f32_e32 v186, v186
	v_exp_f32_e32 v177, v177
	v_exp_f32_e32 v187, v187
	v_exp_f32_e32 v205, v205
	v_exp_f32_e32 v236, v236
	v_exp_f32_e32 v206, v206
	v_exp_f32_e32 v237, v237
	v_exp_f32_e32 v208, v208
	v_exp_f32_e32 v238, v238
	v_exp_f32_e32 v210, v210
	v_exp_f32_e32 v239, v239
	v_add_f32_e32 v174, 1.0, v174
	v_add_f32_e32 v184, 1.0, v184
	v_add_f32_e32 v175, 1.0, v175
	v_add_f32_e32 v185, 1.0, v185
	v_add_f32_e32 v176, 1.0, v176
	v_add_f32_e32 v186, 1.0, v186
	v_add_f32_e32 v177, 1.0, v177
	v_add_f32_e32 v187, 1.0, v187
	v_add_f32_e32 v205, 1.0, v205
	v_add_f32_e32 v236, 1.0, v236
	v_add_f32_e32 v206, 1.0, v206
	v_add_f32_e32 v237, 1.0, v237
	v_add_f32_e32 v208, 1.0, v208
	v_add_f32_e32 v238, 1.0, v238
	v_add_f32_e32 v210, 1.0, v210
	v_add_f32_e32 v239, 1.0, v239
	v_rcp_f32_e32 v174, v174
	v_rcp_f32_e32 v184, v184
	v_rcp_f32_e32 v175, v175
	v_rcp_f32_e32 v185, v185
	v_rcp_f32_e32 v176, v176
	v_rcp_f32_e32 v186, v186
	v_rcp_f32_e32 v177, v177
	v_rcp_f32_e32 v187, v187
	v_mul_f32_e32 v205, v205, v174
	v_mul_f32_e32 v236, v236, v184
	v_mul_f32_e32 v206, v206, v175
	v_mul_f32_e32 v237, v237, v185
	v_mul_f32_e32 v208, v208, v176
	v_mul_f32_e32 v238, v238, v186
	v_mul_f32_e32 v210, v210, v177
	v_mul_f32_e32 v239, v239, v187
	v_mul_f32_e32 v96, v96, v205
	v_mul_f32_e32 v97, v97, v236
	v_mul_f32_e32 v98, v98, v206
	v_mul_f32_e32 v99, v99, v237
	v_mul_f32_e32 v92, v92, v208
	v_mul_f32_e32 v93, v93, v238
	v_mul_f32_e32 v94, v94, v210
	v_mul_f32_e32 v95, v95, v239
	s_waitcnt vmcnt(10)
	v_lshlrev_b32_e32 v174, 16, v188
	v_lshlrev_b32_e32 v175, 16, v189
	v_lshlrev_b32_e32 v176, 16, v190
	v_lshlrev_b32_e32 v177, 16, v191
	v_and_b32_e32 v188, 0xffff0000, v188
	v_and_b32_e32 v189, 0xffff0000, v189
	v_and_b32_e32 v190, 0xffff0000, v190
	v_and_b32_e32 v191, 0xffff0000, v191
	v_lshlrev_b32_e32 v205, 16, v240
	v_lshlrev_b32_e32 v206, 16, v241
	v_lshlrev_b32_e32 v208, 16, v242
	v_lshlrev_b32_e32 v210, 16, v243
	v_and_b32_e32 v240, 0xffff0000, v240
	v_and_b32_e32 v241, 0xffff0000, v241
	v_and_b32_e32 v242, 0xffff0000, v242
	v_and_b32_e32 v243, 0xffff0000, v243
	v_mul_f32_e32 v174, 0xbfb8aa3b, v174
	v_mul_f32_e32 v188, 0xbfb8aa3b, v188
	v_mul_f32_e32 v175, 0xbfb8aa3b, v175
	v_mul_f32_e32 v189, 0xbfb8aa3b, v189
	v_mul_f32_e32 v176, 0xbfb8aa3b, v176
	v_mul_f32_e32 v190, 0xbfb8aa3b, v190
	v_mul_f32_e32 v177, 0xbfb8aa3b, v177
	v_mul_f32_e32 v191, 0xbfb8aa3b, v191
	v_mul_f32_e32 v205, 0xbfb8aa3b, v205
	v_mul_f32_e32 v240, 0xbfb8aa3b, v240
	v_mul_f32_e32 v206, 0xbfb8aa3b, v206
	v_mul_f32_e32 v241, 0xbfb8aa3b, v241
	v_mul_f32_e32 v208, 0xbfb8aa3b, v208
	v_mul_f32_e32 v242, 0xbfb8aa3b, v242
	v_mul_f32_e32 v210, 0xbfb8aa3b, v210
	v_mul_f32_e32 v243, 0xbfb8aa3b, v243
	v_exp_f32_e32 v174, v174
	v_exp_f32_e32 v188, v188
	v_exp_f32_e32 v175, v175
	v_exp_f32_e32 v189, v189
	v_exp_f32_e32 v176, v176
	v_exp_f32_e32 v190, v190
	v_exp_f32_e32 v177, v177
	v_exp_f32_e32 v191, v191
	v_exp_f32_e32 v205, v205
	v_exp_f32_e32 v240, v240
	v_exp_f32_e32 v206, v206
	v_exp_f32_e32 v241, v241
	v_exp_f32_e32 v208, v208
	v_exp_f32_e32 v242, v242
	v_exp_f32_e32 v210, v210
	v_exp_f32_e32 v243, v243
	v_add_f32_e32 v174, 1.0, v174
	v_add_f32_e32 v188, 1.0, v188
	v_add_f32_e32 v175, 1.0, v175
	v_add_f32_e32 v189, 1.0, v189
	v_add_f32_e32 v176, 1.0, v176
	v_add_f32_e32 v190, 1.0, v190
	v_add_f32_e32 v177, 1.0, v177
	v_add_f32_e32 v191, 1.0, v191
	v_add_f32_e32 v205, 1.0, v205
	v_add_f32_e32 v240, 1.0, v240
	v_add_f32_e32 v206, 1.0, v206
	v_add_f32_e32 v241, 1.0, v241
	v_add_f32_e32 v208, 1.0, v208
	v_add_f32_e32 v242, 1.0, v242
	v_add_f32_e32 v210, 1.0, v210
	v_add_f32_e32 v243, 1.0, v243
	v_rcp_f32_e32 v174, v174
	v_rcp_f32_e32 v188, v188
	v_rcp_f32_e32 v175, v175
	v_rcp_f32_e32 v189, v189
	v_rcp_f32_e32 v176, v176
	v_rcp_f32_e32 v190, v190
	v_rcp_f32_e32 v177, v177
	v_rcp_f32_e32 v191, v191
	v_mul_f32_e32 v205, v205, v174
	v_mul_f32_e32 v240, v240, v188
	v_mul_f32_e32 v206, v206, v175
	v_mul_f32_e32 v241, v241, v189
	v_mul_f32_e32 v208, v208, v176
	v_mul_f32_e32 v242, v242, v190
	v_mul_f32_e32 v210, v210, v177
	v_mul_f32_e32 v243, v243, v191
	v_mul_f32_e32 v120, v120, v205
	v_mul_f32_e32 v121, v121, v240
	v_mul_f32_e32 v122, v122, v206
	v_mul_f32_e32 v123, v123, v241
	v_mul_f32_e32 v116, v116, v208
	v_mul_f32_e32 v117, v117, v242
	v_mul_f32_e32 v118, v118, v210
	v_mul_f32_e32 v119, v119, v243
	s_waitcnt vmcnt(8)
;     __device__ __forceinline__ void mid(f32x4 (&acc)[2][2][4][2], const Unit& u, int wr, int wc, int fr, int fq) const {
;     ...
;             for (int m = 0; m < 4; ++m) { const bf16_t* prow = P + (size_t)(row0 + ai * HALF + m * 16) * DP;
; #pragma unroll
;                 for (int bj = 0; bj < 2; ++bj) { const int c = col0 + bj * HALF;
;                     float ga[8], gb[8]; unpack8(__builtin_nontemporal_load((const u32x4*)(prow + C_MA + c)), ga); unpack8(*(const u32x4*)(prow + C_MB + c), gb);
; #pragma unroll
;                     for (int e = 0; e < 4; ++e) { acc[ai][bj][m][0][e] *= (1.0f + __expf(-gb[e])) * __builtin_amdgcn_rcpf(1.0f + __expf(-ga[e]));
;                                                   acc[ai][bj][m][1][e] *= (1.0f + __expf(-gb[4 + e])) * __builtin_amdgcn_rcpf(1.0f + __expf(-ga[4 + e])); } }
	v_lshlrev_b32_e32 v174, 16, v192
	v_lshlrev_b32_e32 v175, 16, v193
	v_lshlrev_b32_e32 v176, 16, v194
	v_lshlrev_b32_e32 v177, 16, v195
	v_and_b32_e32 v192, 0xffff0000, v192
	v_and_b32_e32 v193, 0xffff0000, v193
	v_and_b32_e32 v194, 0xffff0000, v194
	v_and_b32_e32 v195, 0xffff0000, v195
	v_lshlrev_b32_e32 v205, 16, v244
	v_lshlrev_b32_e32 v206, 16, v245
	v_lshlrev_b32_e32 v208, 16, v246
	v_lshlrev_b32_e32 v210, 16, v247
	v_and_b32_e32 v244, 0xffff0000, v244
	v_and_b32_e32 v245, 0xffff0000, v245
	v_and_b32_e32 v246, 0xffff0000, v246
	v_and_b32_e32 v247, 0xffff0000, v247
	v_mul_f32_e32 v174, 0xbfb8aa3b, v174
	v_mul_f32_e32 v192, 0xbfb8aa3b, v192
	v_mul_f32_e32 v175, 0xbfb8aa3b, v175
	v_mul_f32_e32 v193, 0xbfb8aa3b, v193
	v_mul_f32_e32 v176, 0xbfb8aa3b, v176
	v_mul_f32_e32 v194, 0xbfb8aa3b, v194
	v_mul_f32_e32 v177, 0xbfb8aa3b, v177
	v_mul_f32_e32 v195, 0xbfb8aa3b, v195
	v_mul_f32_e32 v205, 0xbfb8aa3b, v205
	v_mul_f32_e32 v244, 0xbfb8aa3b, v244
	v_mul_f32_e32 v206, 0xbfb8aa3b, v206
	v_mul_f32_e32 v245, 0xbfb8aa3b, v245
	v_mul_f32_e32 v208, 0xbfb8aa3b, v208
	v_mul_f32_e32 v246, 0xbfb8aa3b, v246
	v_mul_f32_e32 v210, 0xbfb8aa3b, v210
	v_mul_f32_e32 v247, 0xbfb8aa3b, v247
	v_exp_f32_e32 v174, v174
	v_exp_f32_e32 v192, v192
	v_exp_f32_e32 v175, v175
	v_exp_f32_e32 v193, v193
	v_exp_f32_e32 v176, v176
	v_exp_f32_e32 v194, v194
	v_exp_f32_e32 v177, v177
	v_exp_f32_e32 v195, v195
	v_exp_f32_e32 v205, v205
	v_exp_f32_e32 v244, v244
	v_exp_f32_e32 v206, v206
	v_exp_f32_e32 v245, v245
	v_exp_f32_e32 v208, v208
	v_exp_f32_e32 v246, v246
	v_exp_f32_e32 v210, v210
	v_exp_f32_e32 v247, v247
	v_add_f32_e32 v174, 1.0, v174
	v_add_f32_e32 v192, 1.0, v192
	v_add_f32_e32 v175, 1.0, v175
	v_add_f32_e32 v193, 1.0, v193
	v_add_f32_e32 v176, 1.0, v176
	v_add_f32_e32 v194, 1.0, v194
	v_add_f32_e32 v177, 1.0, v177
	v_add_f32_e32 v195, 1.0, v195
	v_add_f32_e32 v205, 1.0, v205
	v_add_f32_e32 v244, 1.0, v244
	v_add_f32_e32 v206, 1.0, v206
	v_add_f32_e32 v245, 1.0, v245
	v_add_f32_e32 v208, 1.0, v208
	v_add_f32_e32 v246, 1.0, v246
	v_add_f32_e32 v210, 1.0, v210
	v_add_f32_e32 v247, 1.0, v247
	v_rcp_f32_e32 v174, v174
	v_rcp_f32_e32 v192, v192
	v_rcp_f32_e32 v175, v175
	v_rcp_f32_e32 v193, v193
	v_rcp_f32_e32 v176, v176
	v_rcp_f32_e32 v194, v194
	v_rcp_f32_e32 v177, v177
	v_rcp_f32_e32 v195, v195
	v_mul_f32_e32 v205, v205, v174
	v_mul_f32_e32 v244, v244, v192
	v_mul_f32_e32 v206, v206, v175
	v_mul_f32_e32 v245, v245, v193
	v_mul_f32_e32 v208, v208, v176
	v_mul_f32_e32 v246, v246, v194
	v_mul_f32_e32 v210, v210, v177
	v_mul_f32_e32 v247, v247, v195
	v_mul_f32_e32 v88, v88, v205
	v_mul_f32_e32 v89, v89, v244
	v_mul_f32_e32 v90, v90, v206
	v_mul_f32_e32 v91, v91, v245
	v_mul_f32_e32 v84, v84, v208
	v_mul_f32_e32 v85, v85, v246
	v_mul_f32_e32 v86, v86, v210
	v_mul_f32_e32 v87, v87, v247
	s_waitcnt vmcnt(6)
	v_lshlrev_b32_e32 v174, 16, v196
	v_lshlrev_b32_e32 v175, 16, v197
	v_lshlrev_b32_e32 v176, 16, v198
	v_lshlrev_b32_e32 v177, 16, v199
	v_and_b32_e32 v196, 0xffff0000, v196
	v_and_b32_e32 v197, 0xffff0000, v197
	v_and_b32_e32 v198, 0xffff0000, v198
	v_and_b32_e32 v199, 0xffff0000, v199
	v_lshlrev_b32_e32 v205, 16, v248
	v_lshlrev_b32_e32 v206, 16, v249
	v_lshlrev_b32_e32 v208, 16, v250
	v_lshlrev_b32_e32 v210, 16, v251
	v_and_b32_e32 v248, 0xffff0000, v248
	v_and_b32_e32 v249, 0xffff0000, v249
	v_and_b32_e32 v250, 0xffff0000, v250
	v_and_b32_e32 v251, 0xffff0000, v251
	v_mul_f32_e32 v174, 0xbfb8aa3b, v174
	v_mul_f32_e32 v196, 0xbfb8aa3b, v196
	v_mul_f32_e32 v175, 0xbfb8aa3b, v175
	v_mul_f32_e32 v197, 0xbfb8aa3b, v197
	v_mul_f32_e32 v176, 0xbfb8aa3b, v176
	v_mul_f32_e32 v198, 0xbfb8aa3b, v198
	v_mul_f32_e32 v177, 0xbfb8aa3b, v177
	v_mul_f32_e32 v199, 0xbfb8aa3b, v199
	v_mul_f32_e32 v205, 0xbfb8aa3b, v205
	v_mul_f32_e32 v248, 0xbfb8aa3b, v248
	v_mul_f32_e32 v206, 0xbfb8aa3b, v206
	v_mul_f32_e32 v249, 0xbfb8aa3b, v249
	v_mul_f32_e32 v208, 0xbfb8aa3b, v208
	v_mul_f32_e32 v250, 0xbfb8aa3b, v250
	v_mul_f32_e32 v210, 0xbfb8aa3b, v210
	v_mul_f32_e32 v251, 0xbfb8aa3b, v251
	v_exp_f32_e32 v174, v174
	v_exp_f32_e32 v196, v196
	v_exp_f32_e32 v175, v175
	v_exp_f32_e32 v197, v197
	v_exp_f32_e32 v176, v176
	v_exp_f32_e32 v198, v198
	v_exp_f32_e32 v177, v177
	v_exp_f32_e32 v199, v199
	v_exp_f32_e32 v205, v205
	v_exp_f32_e32 v248, v248
	v_exp_f32_e32 v206, v206
	v_exp_f32_e32 v249, v249
	v_exp_f32_e32 v208, v208
	v_exp_f32_e32 v250, v250
	v_exp_f32_e32 v210, v210
	v_exp_f32_e32 v251, v251
	v_add_f32_e32 v174, 1.0, v174
	v_add_f32_e32 v196, 1.0, v196
	v_add_f32_e32 v175, 1.0, v175
	v_add_f32_e32 v197, 1.0, v197
	v_add_f32_e32 v176, 1.0, v176
	v_add_f32_e32 v198, 1.0, v198
	v_add_f32_e32 v177, 1.0, v177
	v_add_f32_e32 v199, 1.0, v199
	v_add_f32_e32 v205, 1.0, v205
	v_add_f32_e32 v248, 1.0, v248
	v_add_f32_e32 v206, 1.0, v206
	v_add_f32_e32 v249, 1.0, v249
	v_add_f32_e32 v208, 1.0, v208
	v_add_f32_e32 v250, 1.0, v250
	v_add_f32_e32 v210, 1.0, v210
	v_add_f32_e32 v251, 1.0, v251
	v_rcp_f32_e32 v174, v174
	v_rcp_f32_e32 v196, v196
	v_rcp_f32_e32 v175, v175
	v_rcp_f32_e32 v197, v197
	v_rcp_f32_e32 v176, v176
	v_rcp_f32_e32 v198, v198
	v_rcp_f32_e32 v177, v177
	v_rcp_f32_e32 v199, v199
	v_mul_f32_e32 v205, v205, v174
	v_mul_f32_e32 v248, v248, v196
	v_mul_f32_e32 v206, v206, v175
	v_mul_f32_e32 v249, v249, v197
	v_mul_f32_e32 v208, v208, v176
	v_mul_f32_e32 v250, v250, v198
	v_mul_f32_e32 v210, v210, v177
	v_mul_f32_e32 v251, v251, v199
	v_mul_f32_e32 v112, v112, v205
	v_mul_f32_e32 v113, v113, v248
	v_mul_f32_e32 v114, v114, v206
	v_mul_f32_e32 v115, v115, v249
	v_mul_f32_e32 v108, v108, v208
	v_mul_f32_e32 v109, v109, v250
	v_mul_f32_e32 v110, v110, v210
	v_mul_f32_e32 v111, v111, v251
	s_waitcnt vmcnt(4)
;     __device__ __forceinline__ void mid(f32x4 (&acc)[2][2][4][2], const Unit& u, int wr, int wc, int fr, int fq) const {
;     ...
;             for (int m = 0; m < 4; ++m) { const bf16_t* prow = P + (size_t)(row0 + ai * HALF + m * 16) * DP;
; #pragma unroll
;                 for (int bj = 0; bj < 2; ++bj) { const int c = col0 + bj * HALF;
;                     float ga[8], gb[8]; unpack8(__builtin_nontemporal_load((const u32x4*)(prow + C_MA + c)), ga); unpack8(*(const u32x4*)(prow + C_MB + c), gb);
; #pragma unroll
;                     for (int e = 0; e < 4; ++e) { acc[ai][bj][m][0][e] *= (1.0f + __expf(-gb[e])) * __builtin_amdgcn_rcpf(1.0f + __expf(-ga[e]));
;                                                   acc[ai][bj][m][1][e] *= (1.0f + __expf(-gb[4 + e])) * __builtin_amdgcn_rcpf(1.0f + __expf(-ga[4 + e])); } }
	v_lshlrev_b32_e32 v174, 16, v200
	v_lshlrev_b32_e32 v175, 16, v201
	v_lshlrev_b32_e32 v176, 16, v202
	v_lshlrev_b32_e32 v177, 16, v203
	v_and_b32_e32 v200, 0xffff0000, v200
	v_and_b32_e32 v201, 0xffff0000, v201
	v_and_b32_e32 v202, 0xffff0000, v202
	v_and_b32_e32 v203, 0xffff0000, v203
	v_lshlrev_b32_e32 v205, 16, v132
	v_lshlrev_b32_e32 v206, 16, v133
	v_lshlrev_b32_e32 v208, 16, v134
	v_lshlrev_b32_e32 v210, 16, v135
	v_and_b32_e32 v132, 0xffff0000, v132
	v_and_b32_e32 v133, 0xffff0000, v133
	v_and_b32_e32 v134, 0xffff0000, v134
	v_and_b32_e32 v135, 0xffff0000, v135
	v_mul_f32_e32 v174, 0xbfb8aa3b, v174
	v_mul_f32_e32 v200, 0xbfb8aa3b, v200
	v_mul_f32_e32 v175, 0xbfb8aa3b, v175
	v_mul_f32_e32 v201, 0xbfb8aa3b, v201
	v_mul_f32_e32 v176, 0xbfb8aa3b, v176
	v_mul_f32_e32 v202, 0xbfb8aa3b, v202
	v_mul_f32_e32 v177, 0xbfb8aa3b, v177
	v_mul_f32_e32 v203, 0xbfb8aa3b, v203
	v_mul_f32_e32 v205, 0xbfb8aa3b, v205
	v_mul_f32_e32 v132, 0xbfb8aa3b, v132
	v_mul_f32_e32 v206, 0xbfb8aa3b, v206
	v_mul_f32_e32 v133, 0xbfb8aa3b, v133
	v_mul_f32_e32 v208, 0xbfb8aa3b, v208
	v_mul_f32_e32 v134, 0xbfb8aa3b, v134
	v_mul_f32_e32 v210, 0xbfb8aa3b, v210
	v_mul_f32_e32 v135, 0xbfb8aa3b, v135
	v_exp_f32_e32 v174, v174
	v_exp_f32_e32 v200, v200
	v_exp_f32_e32 v175, v175
	v_exp_f32_e32 v201, v201
	v_exp_f32_e32 v176, v176
	v_exp_f32_e32 v202, v202
	v_exp_f32_e32 v177, v177
	v_exp_f32_e32 v203, v203
	v_exp_f32_e32 v205, v205
	v_exp_f32_e32 v132, v132
	v_exp_f32_e32 v206, v206
	v_exp_f32_e32 v133, v133
	v_exp_f32_e32 v208, v208
	v_exp_f32_e32 v134, v134
	v_exp_f32_e32 v210, v210
	v_exp_f32_e32 v135, v135
	v_add_f32_e32 v174, 1.0, v174
	v_add_f32_e32 v200, 1.0, v200
	v_add_f32_e32 v175, 1.0, v175
	v_add_f32_e32 v201, 1.0, v201
	v_add_f32_e32 v176, 1.0, v176
	v_add_f32_e32 v202, 1.0, v202
	v_add_f32_e32 v177, 1.0, v177
	v_add_f32_e32 v203, 1.0, v203
	v_add_f32_e32 v205, 1.0, v205
	v_add_f32_e32 v132, 1.0, v132
	v_add_f32_e32 v206, 1.0, v206
	v_add_f32_e32 v133, 1.0, v133
	v_add_f32_e32 v208, 1.0, v208
	v_add_f32_e32 v134, 1.0, v134
	v_add_f32_e32 v210, 1.0, v210
	v_add_f32_e32 v135, 1.0, v135
	v_rcp_f32_e32 v174, v174
	v_rcp_f32_e32 v200, v200
	v_rcp_f32_e32 v175, v175
	v_rcp_f32_e32 v201, v201
	v_rcp_f32_e32 v176, v176
	v_rcp_f32_e32 v202, v202
	v_rcp_f32_e32 v177, v177
	v_rcp_f32_e32 v203, v203
	v_mul_f32_e32 v205, v205, v174
	v_mul_f32_e32 v132, v132, v200
	v_mul_f32_e32 v206, v206, v175
	v_mul_f32_e32 v133, v133, v201
	v_mul_f32_e32 v208, v208, v176
	v_mul_f32_e32 v134, v134, v202
	v_mul_f32_e32 v210, v210, v177
	v_mul_f32_e32 v135, v135, v203
	v_mul_f32_e32 v80, v80, v205
	v_mul_f32_e32 v81, v81, v132
	v_mul_f32_e32 v82, v82, v206
	v_mul_f32_e32 v83, v83, v133
	v_mul_f32_e32 v76, v76, v208
	v_mul_f32_e32 v77, v77, v134
	v_mul_f32_e32 v78, v78, v210
	v_mul_f32_e32 v79, v79, v135
	s_waitcnt vmcnt(2)
	v_lshlrev_b32_e32 v174, 16, v224
	v_lshlrev_b32_e32 v175, 16, v225
	v_lshlrev_b32_e32 v176, 16, v226
	v_lshlrev_b32_e32 v177, 16, v227
	v_and_b32_e32 v224, 0xffff0000, v224
	v_and_b32_e32 v225, 0xffff0000, v225
	v_and_b32_e32 v226, 0xffff0000, v226
	v_and_b32_e32 v227, 0xffff0000, v227
	v_lshlrev_b32_e32 v205, 16, v136
	v_lshlrev_b32_e32 v206, 16, v137
	v_lshlrev_b32_e32 v208, 16, v138
	v_lshlrev_b32_e32 v210, 16, v139
	v_and_b32_e32 v136, 0xffff0000, v136
	v_and_b32_e32 v137, 0xffff0000, v137
	v_and_b32_e32 v138, 0xffff0000, v138
	v_and_b32_e32 v139, 0xffff0000, v139
	v_mul_f32_e32 v174, 0xbfb8aa3b, v174
	v_mul_f32_e32 v224, 0xbfb8aa3b, v224
	v_mul_f32_e32 v175, 0xbfb8aa3b, v175
	v_mul_f32_e32 v225, 0xbfb8aa3b, v225
	v_mul_f32_e32 v176, 0xbfb8aa3b, v176
	v_mul_f32_e32 v226, 0xbfb8aa3b, v226
	v_mul_f32_e32 v177, 0xbfb8aa3b, v177
	v_mul_f32_e32 v227, 0xbfb8aa3b, v227
	v_mul_f32_e32 v205, 0xbfb8aa3b, v205
	v_mul_f32_e32 v136, 0xbfb8aa3b, v136
	v_mul_f32_e32 v206, 0xbfb8aa3b, v206
	v_mul_f32_e32 v137, 0xbfb8aa3b, v137
	v_mul_f32_e32 v208, 0xbfb8aa3b, v208
	v_mul_f32_e32 v138, 0xbfb8aa3b, v138
	v_mul_f32_e32 v210, 0xbfb8aa3b, v210
	v_mul_f32_e32 v139, 0xbfb8aa3b, v139
	v_exp_f32_e32 v174, v174
	v_exp_f32_e32 v224, v224
	v_exp_f32_e32 v175, v175
	v_exp_f32_e32 v225, v225
	v_exp_f32_e32 v176, v176
	v_exp_f32_e32 v226, v226
	v_exp_f32_e32 v177, v177
	v_exp_f32_e32 v227, v227
	v_exp_f32_e32 v205, v205
	v_exp_f32_e32 v136, v136
	v_exp_f32_e32 v206, v206
	v_exp_f32_e32 v137, v137
	v_exp_f32_e32 v208, v208
	v_exp_f32_e32 v138, v138
	v_exp_f32_e32 v210, v210
	v_exp_f32_e32 v139, v139
	v_add_f32_e32 v174, 1.0, v174
	v_add_f32_e32 v224, 1.0, v224
	v_add_f32_e32 v175, 1.0, v175
	v_add_f32_e32 v225, 1.0, v225
	v_add_f32_e32 v176, 1.0, v176
	v_add_f32_e32 v226, 1.0, v226
	v_add_f32_e32 v177, 1.0, v177
	v_add_f32_e32 v227, 1.0, v227
	v_add_f32_e32 v205, 1.0, v205
	v_add_f32_e32 v136, 1.0, v136
	v_add_f32_e32 v206, 1.0, v206
	v_add_f32_e32 v137, 1.0, v137
	v_add_f32_e32 v208, 1.0, v208
	v_add_f32_e32 v138, 1.0, v138
	v_add_f32_e32 v210, 1.0, v210
	v_add_f32_e32 v139, 1.0, v139
	v_rcp_f32_e32 v174, v174
	v_rcp_f32_e32 v224, v224
	v_rcp_f32_e32 v175, v175
	v_rcp_f32_e32 v225, v225
	v_rcp_f32_e32 v176, v176
	v_rcp_f32_e32 v226, v226
	v_rcp_f32_e32 v177, v177
	v_rcp_f32_e32 v227, v227
	v_mul_f32_e32 v205, v205, v174
	v_mul_f32_e32 v136, v136, v224
	v_mul_f32_e32 v206, v206, v175
	v_mul_f32_e32 v137, v137, v225
	v_mul_f32_e32 v208, v208, v176
	v_mul_f32_e32 v138, v138, v226
	v_mul_f32_e32 v210, v210, v177
	v_mul_f32_e32 v139, v139, v227
	v_mul_f32_e32 v104, v104, v205
	v_mul_f32_e32 v105, v105, v136
	v_mul_f32_e32 v106, v106, v206
	v_mul_f32_e32 v107, v107, v137
	v_mul_f32_e32 v100, v100, v208
	v_mul_f32_e32 v101, v101, v138
	v_mul_f32_e32 v102, v102, v210
	v_mul_f32_e32 v103, v103, v139
	s_waitcnt vmcnt(0)
;     __device__ __forceinline__ void mid(f32x4 (&acc)[2][2][4][2], const Unit& u, int wr, int wc, int fr, int fq) const {
;         const int row0 = u.pm * BM + wr * 64 + fr, col0 = u.pn * BM + wc * 32 + 8 * fq;
; #pragma unroll
;         for (int ai = 0; ai < 2; ++ai)
; #pragma unroll
;             for (int m = 0; m < 4; ++m) { const bf16_t* prow = P + (size_t)(row0 + ai * HALF + m * 16) * DP;
; #pragma unroll
;                 for (int bj = 0; bj < 2; ++bj) { const int c = col0 + bj * HALF;
;                     float ga[8], gb[8]; unpack8(__builtin_nontemporal_load((const u32x4*)(prow + C_MA + c)), ga); unpack8(*(const u32x4*)(prow + C_MB + c), gb);
; #pragma unroll
;                     for (int e = 0; e < 4; ++e) { acc[ai][bj][m][0][e] *= (1.0f + __expf(-gb[e])) * __builtin_amdgcn_rcpf(1.0f + __expf(-ga[e]));
;                                                   acc[ai][bj][m][1][e] *= (1.0f + __expf(-gb[4 + e])) * __builtin_amdgcn_rcpf(1.0f + __expf(-ga[4 + e])); } }
;                 asm volatile("" ::: "memory"); }
	v_lshlrev_b32_e32 v174, 16, v228
	v_lshlrev_b32_e32 v175, 16, v229
	v_lshlrev_b32_e32 v176, 16, v230
	v_lshlrev_b32_e32 v177, 16, v231
	v_and_b32_e32 v228, 0xffff0000, v228
	v_and_b32_e32 v229, 0xffff0000, v229
	v_and_b32_e32 v230, 0xffff0000, v230
	v_and_b32_e32 v231, 0xffff0000, v231
	v_lshlrev_b32_e32 v205, 16, v170
	v_lshlrev_b32_e32 v206, 16, v171
	v_lshlrev_b32_e32 v208, 16, v172
	v_lshlrev_b32_e32 v210, 16, v173
	v_and_b32_e32 v170, 0xffff0000, v170
	v_and_b32_e32 v171, 0xffff0000, v171
	v_and_b32_e32 v172, 0xffff0000, v172
	v_and_b32_e32 v173, 0xffff0000, v173
	v_mul_f32_e32 v174, 0xbfb8aa3b, v174
	v_mul_f32_e32 v228, 0xbfb8aa3b, v228
	v_mul_f32_e32 v175, 0xbfb8aa3b, v175
	v_mul_f32_e32 v229, 0xbfb8aa3b, v229
	v_mul_f32_e32 v176, 0xbfb8aa3b, v176
	v_mul_f32_e32 v230, 0xbfb8aa3b, v230
	v_mul_f32_e32 v177, 0xbfb8aa3b, v177
	v_mul_f32_e32 v231, 0xbfb8aa3b, v231
	v_mul_f32_e32 v205, 0xbfb8aa3b, v205
	v_mul_f32_e32 v170, 0xbfb8aa3b, v170
	v_mul_f32_e32 v206, 0xbfb8aa3b, v206
	v_mul_f32_e32 v171, 0xbfb8aa3b, v171
	v_mul_f32_e32 v208, 0xbfb8aa3b, v208
	v_mul_f32_e32 v172, 0xbfb8aa3b, v172
	v_mul_f32_e32 v210, 0xbfb8aa3b, v210
	v_mul_f32_e32 v173, 0xbfb8aa3b, v173
	v_exp_f32_e32 v174, v174
	v_exp_f32_e32 v228, v228
	v_exp_f32_e32 v175, v175
	v_exp_f32_e32 v229, v229
	v_exp_f32_e32 v176, v176
	v_exp_f32_e32 v230, v230
	v_exp_f32_e32 v177, v177
	v_exp_f32_e32 v231, v231
	v_exp_f32_e32 v205, v205
	v_exp_f32_e32 v170, v170
	v_exp_f32_e32 v206, v206
	v_exp_f32_e32 v171, v171
	v_exp_f32_e32 v208, v208
	v_exp_f32_e32 v172, v172
	v_exp_f32_e32 v210, v210
	v_exp_f32_e32 v173, v173
	v_add_f32_e32 v174, 1.0, v174
	v_add_f32_e32 v228, 1.0, v228
	v_add_f32_e32 v175, 1.0, v175
	v_add_f32_e32 v229, 1.0, v229
	v_add_f32_e32 v176, 1.0, v176
	v_add_f32_e32 v230, 1.0, v230
	v_add_f32_e32 v177, 1.0, v177
	v_add_f32_e32 v231, 1.0, v231
	v_add_f32_e32 v205, 1.0, v205
	v_add_f32_e32 v170, 1.0, v170
	v_add_f32_e32 v206, 1.0, v206
	v_add_f32_e32 v171, 1.0, v171
	v_add_f32_e32 v208, 1.0, v208
	v_add_f32_e32 v172, 1.0, v172
	v_add_f32_e32 v210, 1.0, v210
	v_add_f32_e32 v173, 1.0, v173
	v_rcp_f32_e32 v174, v174
	v_rcp_f32_e32 v228, v228
	v_rcp_f32_e32 v175, v175
	v_rcp_f32_e32 v229, v229
	v_rcp_f32_e32 v176, v176
	v_rcp_f32_e32 v230, v230
	v_rcp_f32_e32 v177, v177
	v_rcp_f32_e32 v231, v231
	v_mul_f32_e32 v205, v205, v174
	v_mul_f32_e32 v170, v170, v228
	v_mul_f32_e32 v206, v206, v175
	v_mul_f32_e32 v171, v171, v229
	v_mul_f32_e32 v208, v208, v176
	v_mul_f32_e32 v172, v172, v230
	v_mul_f32_e32 v210, v210, v177
	v_mul_f32_e32 v173, v173, v231
	v_mul_f32_e32 v72, v72, v205
	v_mul_f32_e32 v73, v73, v170
	v_mul_f32_e32 v74, v74, v206
	v_mul_f32_e32 v75, v75, v171
	v_mul_f32_e32 v68, v68, v208
	v_mul_f32_e32 v69, v69, v172
	v_mul_f32_e32 v70, v70, v210
	v_mul_f32_e32 v71, v71, v173
	s_add_u32 s68, s68, 0xc8000
	s_addc_u32 s69, s69, 0
	s_add_u32 s72, s72, 0xc8000
	s_addc_u32 s73, s73, 0
	global_load_dwordx4 v[180:183], v0, s[68:69] nt
	global_load_dwordx4 v[232:235], v0, s[72:73]
	global_load_dwordx4 v[184:187], v0, s[68:69] offset:256 nt
	global_load_dwordx4 v[236:239], v0, s[72:73] offset:256
	s_add_u32 s68, s68, 0x28000
	s_addc_u32 s69, s69, 0
	s_add_u32 s72, s72, 0x28000
	s_addc_u32 s73, s73, 0
	global_load_dwordx4 v[188:191], v0, s[68:69] nt
	global_load_dwordx4 v[240:243], v0, s[72:73]
	global_load_dwordx4 v[192:195], v0, s[68:69] offset:256 nt
	global_load_dwordx4 v[244:247], v0, s[72:73] offset:256
	s_add_u32 s68, s68, 0x28000
	s_addc_u32 s69, s69, 0
	s_add_u32 s72, s72, 0x28000
	s_addc_u32 s73, s73, 0
	global_load_dwordx4 v[196:199], v0, s[68:69] nt
	global_load_dwordx4 v[248:251], v0, s[72:73]
	global_load_dwordx4 v[200:203], v0, s[68:69] offset:256 nt
	global_load_dwordx4 v[132:135], v0, s[72:73] offset:256
	s_add_u32 s68, s68, 0x28000
	s_addc_u32 s69, s69, 0
	s_add_u32 s72, s72, 0x28000
	s_addc_u32 s73, s73, 0
	global_load_dwordx4 v[224:227], v0, s[68:69] nt
	global_load_dwordx4 v[136:139], v0, s[72:73]
	global_load_dwordx4 v[228:231], v0, s[68:69] offset:256 nt
	global_load_dwordx4 v[170:173], v0, s[72:73] offset:256
	s_waitcnt vmcnt(14)
	v_lshlrev_b32_e32 v174, 16, v180
	v_lshlrev_b32_e32 v175, 16, v181
	v_lshlrev_b32_e32 v176, 16, v182
	v_lshlrev_b32_e32 v177, 16, v183
	v_and_b32_e32 v180, 0xffff0000, v180
	v_and_b32_e32 v181, 0xffff0000, v181
	v_and_b32_e32 v182, 0xffff0000, v182
	v_and_b32_e32 v183, 0xffff0000, v183
	v_lshlrev_b32_e32 v205, 16, v232
	v_lshlrev_b32_e32 v206, 16, v233
	v_lshlrev_b32_e32 v208, 16, v234
	v_lshlrev_b32_e32 v210, 16, v235
	v_and_b32_e32 v232, 0xffff0000, v232
	v_and_b32_e32 v233, 0xffff0000, v233
	v_and_b32_e32 v234, 0xffff0000, v234
	v_and_b32_e32 v235, 0xffff0000, v235
	v_mul_f32_e32 v174, 0xbfb8aa3b, v174
	v_mul_f32_e32 v180, 0xbfb8aa3b, v180
	v_mul_f32_e32 v175, 0xbfb8aa3b, v175
	v_mul_f32_e32 v181, 0xbfb8aa3b, v181
	v_mul_f32_e32 v176, 0xbfb8aa3b, v176
	v_mul_f32_e32 v182, 0xbfb8aa3b, v182
	v_mul_f32_e32 v177, 0xbfb8aa3b, v177
	v_mul_f32_e32 v183, 0xbfb8aa3b, v183
	v_mul_f32_e32 v205, 0xbfb8aa3b, v205
	v_mul_f32_e32 v232, 0xbfb8aa3b, v232
	v_mul_f32_e32 v206, 0xbfb8aa3b, v206
	v_mul_f32_e32 v233, 0xbfb8aa3b, v233
	v_mul_f32_e32 v208, 0xbfb8aa3b, v208
	v_mul_f32_e32 v234, 0xbfb8aa3b, v234
	v_mul_f32_e32 v210, 0xbfb8aa3b, v210
	v_mul_f32_e32 v235, 0xbfb8aa3b, v235
	v_exp_f32_e32 v174, v174
	v_exp_f32_e32 v180, v180
	v_exp_f32_e32 v175, v175
	v_exp_f32_e32 v181, v181
	v_exp_f32_e32 v176, v176
	v_exp_f32_e32 v182, v182
	v_exp_f32_e32 v177, v177
	v_exp_f32_e32 v183, v183
	v_exp_f32_e32 v205, v205
	v_exp_f32_e32 v232, v232
	v_exp_f32_e32 v206, v206
	v_exp_f32_e32 v233, v233
	v_exp_f32_e32 v208, v208
	v_exp_f32_e32 v234, v234
	v_exp_f32_e32 v210, v210
	v_exp_f32_e32 v235, v235
	v_add_f32_e32 v174, 1.0, v174
	v_add_f32_e32 v180, 1.0, v180
	v_add_f32_e32 v175, 1.0, v175
	v_add_f32_e32 v181, 1.0, v181
	v_add_f32_e32 v176, 1.0, v176
	v_add_f32_e32 v182, 1.0, v182
	v_add_f32_e32 v177, 1.0, v177
	v_add_f32_e32 v183, 1.0, v183
	v_add_f32_e32 v205, 1.0, v205
	v_add_f32_e32 v232, 1.0, v232
	v_add_f32_e32 v206, 1.0, v206
	v_add_f32_e32 v233, 1.0, v233
	v_add_f32_e32 v208, 1.0, v208
	v_add_f32_e32 v234, 1.0, v234
	v_add_f32_e32 v210, 1.0, v210
	v_add_f32_e32 v235, 1.0, v235
	v_rcp_f32_e32 v174, v174
	v_rcp_f32_e32 v180, v180
	v_rcp_f32_e32 v175, v175
	v_rcp_f32_e32 v181, v181
	v_rcp_f32_e32 v176, v176
	v_rcp_f32_e32 v182, v182
	v_rcp_f32_e32 v177, v177
	v_rcp_f32_e32 v183, v183
	v_mul_f32_e32 v205, v205, v174
	v_mul_f32_e32 v232, v232, v180
	v_mul_f32_e32 v206, v206, v175
	v_mul_f32_e32 v233, v233, v181
	v_mul_f32_e32 v208, v208, v176
	v_mul_f32_e32 v234, v234, v182
	v_mul_f32_e32 v210, v210, v177
	v_mul_f32_e32 v235, v235, v183
	v_mul_f32_e32 v64, v64, v205
	v_mul_f32_e32 v65, v65, v232
	v_mul_f32_e32 v66, v66, v206
	v_mul_f32_e32 v67, v67, v233
	v_mul_f32_e32 v60, v60, v208
	v_mul_f32_e32 v61, v61, v234
	v_mul_f32_e32 v62, v62, v210
	v_mul_f32_e32 v63, v63, v235
	s_waitcnt vmcnt(12)
;     __device__ __forceinline__ void mid(f32x4 (&acc)[2][2][4][2], const Unit& u, int wr, int wc, int fr, int fq) const {
;     ...
;             for (int m = 0; m < 4; ++m) { const bf16_t* prow = P + (size_t)(row0 + ai * HALF + m * 16) * DP;
; #pragma unroll
;                 for (int bj = 0; bj < 2; ++bj) { const int c = col0 + bj * HALF;
;                     float ga[8], gb[8]; unpack8(__builtin_nontemporal_load((const u32x4*)(prow + C_MA + c)), ga); unpack8(*(const u32x4*)(prow + C_MB + c), gb);
; #pragma unroll
;                     for (int e = 0; e < 4; ++e) { acc[ai][bj][m][0][e] *= (1.0f + __expf(-gb[e])) * __builtin_amdgcn_rcpf(1.0f + __expf(-ga[e]));
;                                                   acc[ai][bj][m][1][e] *= (1.0f + __expf(-gb[4 + e])) * __builtin_amdgcn_rcpf(1.0f + __expf(-ga[4 + e])); } }
	v_lshlrev_b32_e32 v174, 16, v184
	v_lshlrev_b32_e32 v175, 16, v185
	v_lshlrev_b32_e32 v176, 16, v186
	v_lshlrev_b32_e32 v177, 16, v187
	v_and_b32_e32 v184, 0xffff0000, v184
	v_and_b32_e32 v185, 0xffff0000, v185
	v_and_b32_e32 v186, 0xffff0000, v186
	v_and_b32_e32 v187, 0xffff0000, v187
	v_lshlrev_b32_e32 v205, 16, v236
	v_lshlrev_b32_e32 v206, 16, v237
	v_lshlrev_b32_e32 v208, 16, v238
	v_lshlrev_b32_e32 v210, 16, v239
	v_and_b32_e32 v236, 0xffff0000, v236
	v_and_b32_e32 v237, 0xffff0000, v237
	v_and_b32_e32 v238, 0xffff0000, v238
	v_and_b32_e32 v239, 0xffff0000, v239
	v_mul_f32_e32 v174, 0xbfb8aa3b, v174
	v_mul_f32_e32 v184, 0xbfb8aa3b, v184
	v_mul_f32_e32 v175, 0xbfb8aa3b, v175
	v_mul_f32_e32 v185, 0xbfb8aa3b, v185
	v_mul_f32_e32 v176, 0xbfb8aa3b, v176
	v_mul_f32_e32 v186, 0xbfb8aa3b, v186
	v_mul_f32_e32 v177, 0xbfb8aa3b, v177
	v_mul_f32_e32 v187, 0xbfb8aa3b, v187
	v_mul_f32_e32 v205, 0xbfb8aa3b, v205
	v_mul_f32_e32 v236, 0xbfb8aa3b, v236
	v_mul_f32_e32 v206, 0xbfb8aa3b, v206
	v_mul_f32_e32 v237, 0xbfb8aa3b, v237
	v_mul_f32_e32 v208, 0xbfb8aa3b, v208
	v_mul_f32_e32 v238, 0xbfb8aa3b, v238
	v_mul_f32_e32 v210, 0xbfb8aa3b, v210
	v_mul_f32_e32 v239, 0xbfb8aa3b, v239
	v_exp_f32_e32 v174, v174
	v_exp_f32_e32 v184, v184
	v_exp_f32_e32 v175, v175
	v_exp_f32_e32 v185, v185
	v_exp_f32_e32 v176, v176
	v_exp_f32_e32 v186, v186
	v_exp_f32_e32 v177, v177
	v_exp_f32_e32 v187, v187
	v_exp_f32_e32 v205, v205
	v_exp_f32_e32 v236, v236
	v_exp_f32_e32 v206, v206
	v_exp_f32_e32 v237, v237
	v_exp_f32_e32 v208, v208
	v_exp_f32_e32 v238, v238
	v_exp_f32_e32 v210, v210
	v_exp_f32_e32 v239, v239
	v_add_f32_e32 v174, 1.0, v174
	v_add_f32_e32 v184, 1.0, v184
	v_add_f32_e32 v175, 1.0, v175
	v_add_f32_e32 v185, 1.0, v185
	v_add_f32_e32 v176, 1.0, v176
	v_add_f32_e32 v186, 1.0, v186
	v_add_f32_e32 v177, 1.0, v177
	v_add_f32_e32 v187, 1.0, v187
	v_add_f32_e32 v205, 1.0, v205
	v_add_f32_e32 v236, 1.0, v236
	v_add_f32_e32 v206, 1.0, v206
	v_add_f32_e32 v237, 1.0, v237
	v_add_f32_e32 v208, 1.0, v208
	v_add_f32_e32 v238, 1.0, v238
	v_add_f32_e32 v210, 1.0, v210
	v_add_f32_e32 v239, 1.0, v239
	v_rcp_f32_e32 v174, v174
	v_rcp_f32_e32 v184, v184
	v_rcp_f32_e32 v175, v175
	v_rcp_f32_e32 v185, v185
	v_rcp_f32_e32 v176, v176
	v_rcp_f32_e32 v186, v186
	v_rcp_f32_e32 v177, v177
	v_rcp_f32_e32 v187, v187
	v_mul_f32_e32 v205, v205, v174
	v_mul_f32_e32 v236, v236, v184
	v_mul_f32_e32 v206, v206, v175
	v_mul_f32_e32 v237, v237, v185
	v_mul_f32_e32 v208, v208, v176
	v_mul_f32_e32 v238, v238, v186
	v_mul_f32_e32 v210, v210, v177
	v_mul_f32_e32 v239, v239, v187
	v_mul_f32_e32 v32, v32, v205
	v_mul_f32_e32 v33, v33, v236
	v_mul_f32_e32 v34, v34, v206
	v_mul_f32_e32 v35, v35, v237
	v_mul_f32_e32 v28, v28, v208
	v_mul_f32_e32 v29, v29, v238
	v_mul_f32_e32 v30, v30, v210
	v_mul_f32_e32 v31, v31, v239
	s_waitcnt vmcnt(10)
	v_lshlrev_b32_e32 v174, 16, v188
	v_lshlrev_b32_e32 v175, 16, v189
	v_lshlrev_b32_e32 v176, 16, v190
	v_lshlrev_b32_e32 v177, 16, v191
	v_and_b32_e32 v188, 0xffff0000, v188
	v_and_b32_e32 v189, 0xffff0000, v189
	v_and_b32_e32 v190, 0xffff0000, v190
	v_and_b32_e32 v191, 0xffff0000, v191
	v_lshlrev_b32_e32 v205, 16, v240
	v_lshlrev_b32_e32 v206, 16, v241
	v_lshlrev_b32_e32 v208, 16, v242
	v_lshlrev_b32_e32 v210, 16, v243
	v_and_b32_e32 v240, 0xffff0000, v240
	v_and_b32_e32 v241, 0xffff0000, v241
	v_and_b32_e32 v242, 0xffff0000, v242
	v_and_b32_e32 v243, 0xffff0000, v243
	v_mul_f32_e32 v174, 0xbfb8aa3b, v174
	v_mul_f32_e32 v188, 0xbfb8aa3b, v188
	v_mul_f32_e32 v175, 0xbfb8aa3b, v175
	v_mul_f32_e32 v189, 0xbfb8aa3b, v189
	v_mul_f32_e32 v176, 0xbfb8aa3b, v176
	v_mul_f32_e32 v190, 0xbfb8aa3b, v190
	v_mul_f32_e32 v177, 0xbfb8aa3b, v177
	v_mul_f32_e32 v191, 0xbfb8aa3b, v191
	v_mul_f32_e32 v205, 0xbfb8aa3b, v205
	v_mul_f32_e32 v240, 0xbfb8aa3b, v240
	v_mul_f32_e32 v206, 0xbfb8aa3b, v206
	v_mul_f32_e32 v241, 0xbfb8aa3b, v241
	v_mul_f32_e32 v208, 0xbfb8aa3b, v208
	v_mul_f32_e32 v242, 0xbfb8aa3b, v242
	v_mul_f32_e32 v210, 0xbfb8aa3b, v210
	v_mul_f32_e32 v243, 0xbfb8aa3b, v243
	v_exp_f32_e32 v174, v174
	v_exp_f32_e32 v188, v188
	v_exp_f32_e32 v175, v175
	v_exp_f32_e32 v189, v189
	v_exp_f32_e32 v176, v176
	v_exp_f32_e32 v190, v190
	v_exp_f32_e32 v177, v177
	v_exp_f32_e32 v191, v191
	v_exp_f32_e32 v205, v205
	v_exp_f32_e32 v240, v240
	v_exp_f32_e32 v206, v206
	v_exp_f32_e32 v241, v241
	v_exp_f32_e32 v208, v208
	v_exp_f32_e32 v242, v242
	v_exp_f32_e32 v210, v210
	v_exp_f32_e32 v243, v243
	v_add_f32_e32 v174, 1.0, v174
	v_add_f32_e32 v188, 1.0, v188
	v_add_f32_e32 v175, 1.0, v175
	v_add_f32_e32 v189, 1.0, v189
	v_add_f32_e32 v176, 1.0, v176
	v_add_f32_e32 v190, 1.0, v190
	v_add_f32_e32 v177, 1.0, v177
	v_add_f32_e32 v191, 1.0, v191
	v_add_f32_e32 v205, 1.0, v205
	v_add_f32_e32 v240, 1.0, v240
	v_add_f32_e32 v206, 1.0, v206
	v_add_f32_e32 v241, 1.0, v241
	v_add_f32_e32 v208, 1.0, v208
	v_add_f32_e32 v242, 1.0, v242
	v_add_f32_e32 v210, 1.0, v210
	v_add_f32_e32 v243, 1.0, v243
	v_rcp_f32_e32 v174, v174
	v_rcp_f32_e32 v188, v188
	v_rcp_f32_e32 v175, v175
	v_rcp_f32_e32 v189, v189
	v_rcp_f32_e32 v176, v176
	v_rcp_f32_e32 v190, v190
	v_rcp_f32_e32 v177, v177
	v_rcp_f32_e32 v191, v191
	v_mul_f32_e32 v205, v205, v174
	v_mul_f32_e32 v240, v240, v188
	v_mul_f32_e32 v206, v206, v175
	v_mul_f32_e32 v241, v241, v189
	v_mul_f32_e32 v208, v208, v176
	v_mul_f32_e32 v242, v242, v190
	v_mul_f32_e32 v210, v210, v177
	v_mul_f32_e32 v243, v243, v191
	v_mul_f32_e32 v56, v56, v205
	v_mul_f32_e32 v57, v57, v240
	v_mul_f32_e32 v58, v58, v206
	v_mul_f32_e32 v59, v59, v241
	v_mul_f32_e32 v52, v52, v208
	v_mul_f32_e32 v53, v53, v242
	v_mul_f32_e32 v54, v54, v210
	v_mul_f32_e32 v55, v55, v243
	s_waitcnt vmcnt(8)
;     __device__ __forceinline__ void mid(f32x4 (&acc)[2][2][4][2], const Unit& u, int wr, int wc, int fr, int fq) const {
;     ...
;             for (int m = 0; m < 4; ++m) { const bf16_t* prow = P + (size_t)(row0 + ai * HALF + m * 16) * DP;
; #pragma unroll
;                 for (int bj = 0; bj < 2; ++bj) { const int c = col0 + bj * HALF;
;                     float ga[8], gb[8]; unpack8(__builtin_nontemporal_load((const u32x4*)(prow + C_MA + c)), ga); unpack8(*(const u32x4*)(prow + C_MB + c), gb);
; #pragma unroll
;                     for (int e = 0; e < 4; ++e) { acc[ai][bj][m][0][e] *= (1.0f + __expf(-gb[e])) * __builtin_amdgcn_rcpf(1.0f + __expf(-ga[e]));
;                                                   acc[ai][bj][m][1][e] *= (1.0f + __expf(-gb[4 + e])) * __builtin_amdgcn_rcpf(1.0f + __expf(-ga[4 + e])); } }
	v_lshlrev_b32_e32 v174, 16, v192
	v_lshlrev_b32_e32 v175, 16, v193
	v_lshlrev_b32_e32 v176, 16, v194
	v_lshlrev_b32_e32 v177, 16, v195
	v_and_b32_e32 v192, 0xffff0000, v192
	v_and_b32_e32 v193, 0xffff0000, v193
	v_and_b32_e32 v194, 0xffff0000, v194
	v_and_b32_e32 v195, 0xffff0000, v195
	v_lshlrev_b32_e32 v205, 16, v244
	v_lshlrev_b32_e32 v206, 16, v245
	v_lshlrev_b32_e32 v208, 16, v246
	v_lshlrev_b32_e32 v210, 16, v247
	v_and_b32_e32 v244, 0xffff0000, v244
	v_and_b32_e32 v245, 0xffff0000, v245
	v_and_b32_e32 v246, 0xffff0000, v246
	v_and_b32_e32 v247, 0xffff0000, v247
	v_mul_f32_e32 v174, 0xbfb8aa3b, v174
	v_mul_f32_e32 v192, 0xbfb8aa3b, v192
	v_mul_f32_e32 v175, 0xbfb8aa3b, v175
	v_mul_f32_e32 v193, 0xbfb8aa3b, v193
	v_mul_f32_e32 v176, 0xbfb8aa3b, v176
	v_mul_f32_e32 v194, 0xbfb8aa3b, v194
	v_mul_f32_e32 v177, 0xbfb8aa3b, v177
	v_mul_f32_e32 v195, 0xbfb8aa3b, v195
	v_mul_f32_e32 v205, 0xbfb8aa3b, v205
	v_mul_f32_e32 v244, 0xbfb8aa3b, v244
	v_mul_f32_e32 v206, 0xbfb8aa3b, v206
	v_mul_f32_e32 v245, 0xbfb8aa3b, v245
	v_mul_f32_e32 v208, 0xbfb8aa3b, v208
	v_mul_f32_e32 v246, 0xbfb8aa3b, v246
	v_mul_f32_e32 v210, 0xbfb8aa3b, v210
	v_mul_f32_e32 v247, 0xbfb8aa3b, v247
	v_exp_f32_e32 v174, v174
	v_exp_f32_e32 v192, v192
	v_exp_f32_e32 v175, v175
	v_exp_f32_e32 v193, v193
	v_exp_f32_e32 v176, v176
	v_exp_f32_e32 v194, v194
	v_exp_f32_e32 v177, v177
	v_exp_f32_e32 v195, v195
	v_exp_f32_e32 v205, v205
	v_exp_f32_e32 v244, v244
	v_exp_f32_e32 v206, v206
	v_exp_f32_e32 v245, v245
	v_exp_f32_e32 v208, v208
	v_exp_f32_e32 v246, v246
	v_exp_f32_e32 v210, v210
	v_exp_f32_e32 v247, v247
	v_add_f32_e32 v174, 1.0, v174
	v_add_f32_e32 v192, 1.0, v192
	v_add_f32_e32 v175, 1.0, v175
	v_add_f32_e32 v193, 1.0, v193
	v_add_f32_e32 v176, 1.0, v176
	v_add_f32_e32 v194, 1.0, v194
	v_add_f32_e32 v177, 1.0, v177
	v_add_f32_e32 v195, 1.0, v195
	v_add_f32_e32 v205, 1.0, v205
	v_add_f32_e32 v244, 1.0, v244
	v_add_f32_e32 v206, 1.0, v206
	v_add_f32_e32 v245, 1.0, v245
	v_add_f32_e32 v208, 1.0, v208
	v_add_f32_e32 v246, 1.0, v246
	v_add_f32_e32 v210, 1.0, v210
	v_add_f32_e32 v247, 1.0, v247
	v_rcp_f32_e32 v174, v174
	v_rcp_f32_e32 v192, v192
	v_rcp_f32_e32 v175, v175
	v_rcp_f32_e32 v193, v193
	v_rcp_f32_e32 v176, v176
	v_rcp_f32_e32 v194, v194
	v_rcp_f32_e32 v177, v177
	v_rcp_f32_e32 v195, v195
	v_mul_f32_e32 v205, v205, v174
	v_mul_f32_e32 v244, v244, v192
	v_mul_f32_e32 v206, v206, v175
	v_mul_f32_e32 v245, v245, v193
	v_mul_f32_e32 v208, v208, v176
	v_mul_f32_e32 v246, v246, v194
	v_mul_f32_e32 v210, v210, v177
	v_mul_f32_e32 v247, v247, v195
	v_mul_f32_e32 v24, v24, v205
	v_mul_f32_e32 v25, v25, v244
	v_mul_f32_e32 v26, v26, v206
	v_mul_f32_e32 v27, v27, v245
	v_mul_f32_e32 v20, v20, v208
	v_mul_f32_e32 v21, v21, v246
	v_mul_f32_e32 v22, v22, v210
	v_mul_f32_e32 v23, v23, v247
	s_waitcnt vmcnt(6)
	v_lshlrev_b32_e32 v174, 16, v196
	v_lshlrev_b32_e32 v175, 16, v197
	v_lshlrev_b32_e32 v176, 16, v198
	v_lshlrev_b32_e32 v177, 16, v199
	v_and_b32_e32 v196, 0xffff0000, v196
	v_and_b32_e32 v197, 0xffff0000, v197
	v_and_b32_e32 v198, 0xffff0000, v198
	v_and_b32_e32 v199, 0xffff0000, v199
	v_lshlrev_b32_e32 v205, 16, v248
	v_lshlrev_b32_e32 v206, 16, v249
	v_lshlrev_b32_e32 v208, 16, v250
	v_lshlrev_b32_e32 v210, 16, v251
	v_and_b32_e32 v248, 0xffff0000, v248
	v_and_b32_e32 v249, 0xffff0000, v249
	v_and_b32_e32 v250, 0xffff0000, v250
	v_and_b32_e32 v251, 0xffff0000, v251
	v_mul_f32_e32 v174, 0xbfb8aa3b, v174
	v_mul_f32_e32 v196, 0xbfb8aa3b, v196
	v_mul_f32_e32 v175, 0xbfb8aa3b, v175
	v_mul_f32_e32 v197, 0xbfb8aa3b, v197
	v_mul_f32_e32 v176, 0xbfb8aa3b, v176
	v_mul_f32_e32 v198, 0xbfb8aa3b, v198
	v_mul_f32_e32 v177, 0xbfb8aa3b, v177
	v_mul_f32_e32 v199, 0xbfb8aa3b, v199
	v_mul_f32_e32 v205, 0xbfb8aa3b, v205
	v_mul_f32_e32 v248, 0xbfb8aa3b, v248
	v_mul_f32_e32 v206, 0xbfb8aa3b, v206
	v_mul_f32_e32 v249, 0xbfb8aa3b, v249
	v_mul_f32_e32 v208, 0xbfb8aa3b, v208
	v_mul_f32_e32 v250, 0xbfb8aa3b, v250
	v_mul_f32_e32 v210, 0xbfb8aa3b, v210
	v_mul_f32_e32 v251, 0xbfb8aa3b, v251
	v_exp_f32_e32 v174, v174
	v_exp_f32_e32 v196, v196
	v_exp_f32_e32 v175, v175
	v_exp_f32_e32 v197, v197
	v_exp_f32_e32 v176, v176
	v_exp_f32_e32 v198, v198
	v_exp_f32_e32 v177, v177
	v_exp_f32_e32 v199, v199
	v_exp_f32_e32 v205, v205
	v_exp_f32_e32 v248, v248
	v_exp_f32_e32 v206, v206
	v_exp_f32_e32 v249, v249
	v_exp_f32_e32 v208, v208
	v_exp_f32_e32 v250, v250
	v_exp_f32_e32 v210, v210
	v_exp_f32_e32 v251, v251
	v_add_f32_e32 v174, 1.0, v174
	v_add_f32_e32 v196, 1.0, v196
	v_add_f32_e32 v175, 1.0, v175
	v_add_f32_e32 v197, 1.0, v197
	v_add_f32_e32 v176, 1.0, v176
	v_add_f32_e32 v198, 1.0, v198
	v_add_f32_e32 v177, 1.0, v177
	v_add_f32_e32 v199, 1.0, v199
	v_add_f32_e32 v205, 1.0, v205
	v_add_f32_e32 v248, 1.0, v248
	v_add_f32_e32 v206, 1.0, v206
	v_add_f32_e32 v249, 1.0, v249
	v_add_f32_e32 v208, 1.0, v208
	v_add_f32_e32 v250, 1.0, v250
	v_add_f32_e32 v210, 1.0, v210
	v_add_f32_e32 v251, 1.0, v251
	v_rcp_f32_e32 v174, v174
	v_rcp_f32_e32 v196, v196
	v_rcp_f32_e32 v175, v175
	v_rcp_f32_e32 v197, v197
	v_rcp_f32_e32 v176, v176
	v_rcp_f32_e32 v198, v198
	v_rcp_f32_e32 v177, v177
	v_rcp_f32_e32 v199, v199
	v_mul_f32_e32 v205, v205, v174
	v_mul_f32_e32 v248, v248, v196
	v_mul_f32_e32 v206, v206, v175
	v_mul_f32_e32 v249, v249, v197
	v_mul_f32_e32 v208, v208, v176
	v_mul_f32_e32 v250, v250, v198
	v_mul_f32_e32 v210, v210, v177
	v_mul_f32_e32 v251, v251, v199
	v_mul_f32_e32 v48, v48, v205
	v_mul_f32_e32 v49, v49, v248
	v_mul_f32_e32 v50, v50, v206
	v_mul_f32_e32 v51, v51, v249
	v_mul_f32_e32 v44, v44, v208
	v_mul_f32_e32 v45, v45, v250
	v_mul_f32_e32 v46, v46, v210
	v_mul_f32_e32 v47, v47, v251
	s_waitcnt vmcnt(4)
;     __device__ __forceinline__ void mid(f32x4 (&acc)[2][2][4][2], const Unit& u, int wr, int wc, int fr, int fq) const {
;     ...
;             for (int m = 0; m < 4; ++m) { const bf16_t* prow = P + (size_t)(row0 + ai * HALF + m * 16) * DP;
; #pragma unroll
;                 for (int bj = 0; bj < 2; ++bj) { const int c = col0 + bj * HALF;
;                     float ga[8], gb[8]; unpack8(__builtin_nontemporal_load((const u32x4*)(prow + C_MA + c)), ga); unpack8(*(const u32x4*)(prow + C_MB + c), gb);
; #pragma unroll
;                     for (int e = 0; e < 4; ++e) { acc[ai][bj][m][0][e] *= (1.0f + __expf(-gb[e])) * __builtin_amdgcn_rcpf(1.0f + __expf(-ga[e]));
;                                                   acc[ai][bj][m][1][e] *= (1.0f + __expf(-gb[4 + e])) * __builtin_amdgcn_rcpf(1.0f + __expf(-ga[4 + e])); } }
	v_lshlrev_b32_e32 v174, 16, v200
	v_lshlrev_b32_e32 v175, 16, v201
	v_lshlrev_b32_e32 v176, 16, v202
	v_lshlrev_b32_e32 v177, 16, v203
	v_and_b32_e32 v200, 0xffff0000, v200
	v_and_b32_e32 v201, 0xffff0000, v201
	v_and_b32_e32 v202, 0xffff0000, v202
	v_and_b32_e32 v203, 0xffff0000, v203
	v_lshlrev_b32_e32 v205, 16, v132
	v_lshlrev_b32_e32 v206, 16, v133
	v_lshlrev_b32_e32 v208, 16, v134
	v_lshlrev_b32_e32 v210, 16, v135
	v_and_b32_e32 v132, 0xffff0000, v132
	v_and_b32_e32 v133, 0xffff0000, v133
	v_and_b32_e32 v134, 0xffff0000, v134
	v_and_b32_e32 v135, 0xffff0000, v135
	v_mul_f32_e32 v174, 0xbfb8aa3b, v174
	v_mul_f32_e32 v200, 0xbfb8aa3b, v200
	v_mul_f32_e32 v175, 0xbfb8aa3b, v175
	v_mul_f32_e32 v201, 0xbfb8aa3b, v201
	v_mul_f32_e32 v176, 0xbfb8aa3b, v176
	v_mul_f32_e32 v202, 0xbfb8aa3b, v202
	v_mul_f32_e32 v177, 0xbfb8aa3b, v177
	v_mul_f32_e32 v203, 0xbfb8aa3b, v203
	v_mul_f32_e32 v205, 0xbfb8aa3b, v205
	v_mul_f32_e32 v132, 0xbfb8aa3b, v132
	v_mul_f32_e32 v206, 0xbfb8aa3b, v206
	v_mul_f32_e32 v133, 0xbfb8aa3b, v133
	v_mul_f32_e32 v208, 0xbfb8aa3b, v208
	v_mul_f32_e32 v134, 0xbfb8aa3b, v134
	v_mul_f32_e32 v210, 0xbfb8aa3b, v210
	v_mul_f32_e32 v135, 0xbfb8aa3b, v135
	v_exp_f32_e32 v174, v174
	v_exp_f32_e32 v200, v200
	v_exp_f32_e32 v175, v175
	v_exp_f32_e32 v201, v201
	v_exp_f32_e32 v176, v176
	v_exp_f32_e32 v202, v202
	v_exp_f32_e32 v177, v177
	v_exp_f32_e32 v203, v203
	v_exp_f32_e32 v205, v205
	v_exp_f32_e32 v132, v132
	v_exp_f32_e32 v206, v206
	v_exp_f32_e32 v133, v133
	v_exp_f32_e32 v208, v208
	v_exp_f32_e32 v134, v134
	v_exp_f32_e32 v210, v210
	v_exp_f32_e32 v135, v135
	v_add_f32_e32 v174, 1.0, v174
	v_add_f32_e32 v200, 1.0, v200
	v_add_f32_e32 v175, 1.0, v175
	v_add_f32_e32 v201, 1.0, v201
	v_add_f32_e32 v176, 1.0, v176
	v_add_f32_e32 v202, 1.0, v202
	v_add_f32_e32 v177, 1.0, v177
	v_add_f32_e32 v203, 1.0, v203
	v_add_f32_e32 v205, 1.0, v205
	v_add_f32_e32 v132, 1.0, v132
	v_add_f32_e32 v206, 1.0, v206
	v_add_f32_e32 v133, 1.0, v133
	v_add_f32_e32 v208, 1.0, v208
	v_add_f32_e32 v134, 1.0, v134
	v_add_f32_e32 v210, 1.0, v210
	v_add_f32_e32 v135, 1.0, v135
	v_rcp_f32_e32 v174, v174
	v_rcp_f32_e32 v200, v200
	v_rcp_f32_e32 v175, v175
	v_rcp_f32_e32 v201, v201
	v_rcp_f32_e32 v176, v176
	v_rcp_f32_e32 v202, v202
	v_rcp_f32_e32 v177, v177
	v_rcp_f32_e32 v203, v203
	v_mul_f32_e32 v205, v205, v174
	v_mul_f32_e32 v132, v132, v200
	v_mul_f32_e32 v206, v206, v175
	v_mul_f32_e32 v133, v133, v201
	v_mul_f32_e32 v208, v208, v176
	v_mul_f32_e32 v134, v134, v202
	v_mul_f32_e32 v210, v210, v177
	v_mul_f32_e32 v135, v135, v203
	v_mul_f32_e32 v16, v16, v205
	v_mul_f32_e32 v17, v17, v132
	v_mul_f32_e32 v18, v18, v206
	v_mul_f32_e32 v19, v19, v133
	v_mul_f32_e32 v12, v12, v208
	v_mul_f32_e32 v13, v13, v134
	v_mul_f32_e32 v14, v14, v210
	v_mul_f32_e32 v15, v15, v135
	s_waitcnt vmcnt(2)
	v_lshlrev_b32_e32 v174, 16, v224
	v_lshlrev_b32_e32 v175, 16, v225
	v_lshlrev_b32_e32 v176, 16, v226
	v_lshlrev_b32_e32 v177, 16, v227
	v_and_b32_e32 v224, 0xffff0000, v224
	v_and_b32_e32 v225, 0xffff0000, v225
	v_and_b32_e32 v226, 0xffff0000, v226
	v_and_b32_e32 v227, 0xffff0000, v227
	v_lshlrev_b32_e32 v205, 16, v136
	v_lshlrev_b32_e32 v206, 16, v137
	v_lshlrev_b32_e32 v208, 16, v138
	v_lshlrev_b32_e32 v210, 16, v139
	v_and_b32_e32 v136, 0xffff0000, v136
	v_and_b32_e32 v137, 0xffff0000, v137
	v_and_b32_e32 v138, 0xffff0000, v138
	v_and_b32_e32 v139, 0xffff0000, v139
	v_mul_f32_e32 v174, 0xbfb8aa3b, v174
	v_mul_f32_e32 v224, 0xbfb8aa3b, v224
	v_mul_f32_e32 v175, 0xbfb8aa3b, v175
	v_mul_f32_e32 v225, 0xbfb8aa3b, v225
	v_mul_f32_e32 v176, 0xbfb8aa3b, v176
	v_mul_f32_e32 v226, 0xbfb8aa3b, v226
	v_mul_f32_e32 v177, 0xbfb8aa3b, v177
	v_mul_f32_e32 v227, 0xbfb8aa3b, v227
	v_mul_f32_e32 v205, 0xbfb8aa3b, v205
	v_mul_f32_e32 v136, 0xbfb8aa3b, v136
	v_mul_f32_e32 v206, 0xbfb8aa3b, v206
	v_mul_f32_e32 v137, 0xbfb8aa3b, v137
	v_mul_f32_e32 v208, 0xbfb8aa3b, v208
	v_mul_f32_e32 v138, 0xbfb8aa3b, v138
	v_mul_f32_e32 v210, 0xbfb8aa3b, v210
	v_mul_f32_e32 v139, 0xbfb8aa3b, v139
	v_exp_f32_e32 v174, v174
	v_exp_f32_e32 v224, v224
	v_exp_f32_e32 v175, v175
	v_exp_f32_e32 v225, v225
	v_exp_f32_e32 v176, v176
	v_exp_f32_e32 v226, v226
	v_exp_f32_e32 v177, v177
	v_exp_f32_e32 v227, v227
	v_exp_f32_e32 v205, v205
	v_exp_f32_e32 v136, v136
	v_exp_f32_e32 v206, v206
	v_exp_f32_e32 v137, v137
	v_exp_f32_e32 v208, v208
	v_exp_f32_e32 v138, v138
	v_exp_f32_e32 v210, v210
	v_exp_f32_e32 v139, v139
	v_add_f32_e32 v174, 1.0, v174
	v_add_f32_e32 v224, 1.0, v224
	v_add_f32_e32 v175, 1.0, v175
	v_add_f32_e32 v225, 1.0, v225
	v_add_f32_e32 v176, 1.0, v176
	v_add_f32_e32 v226, 1.0, v226
	v_add_f32_e32 v177, 1.0, v177
	v_add_f32_e32 v227, 1.0, v227
	v_add_f32_e32 v205, 1.0, v205
	v_add_f32_e32 v136, 1.0, v136
	v_add_f32_e32 v206, 1.0, v206
	v_add_f32_e32 v137, 1.0, v137
	v_add_f32_e32 v208, 1.0, v208
	v_add_f32_e32 v138, 1.0, v138
	v_add_f32_e32 v210, 1.0, v210
	v_add_f32_e32 v139, 1.0, v139
	v_rcp_f32_e32 v174, v174
	v_rcp_f32_e32 v224, v224
	v_rcp_f32_e32 v175, v175
	v_rcp_f32_e32 v225, v225
	v_rcp_f32_e32 v176, v176
	v_rcp_f32_e32 v226, v226
	v_rcp_f32_e32 v177, v177
	v_rcp_f32_e32 v227, v227
	v_mul_f32_e32 v205, v205, v174
	v_mul_f32_e32 v136, v136, v224
	v_mul_f32_e32 v206, v206, v175
	v_mul_f32_e32 v137, v137, v225
	v_mul_f32_e32 v208, v208, v176
	v_mul_f32_e32 v138, v138, v226
	v_mul_f32_e32 v210, v210, v177
	v_mul_f32_e32 v139, v139, v227
	v_mul_f32_e32 v40, v40, v205
	v_mul_f32_e32 v41, v41, v136
	v_mul_f32_e32 v42, v42, v206
	v_mul_f32_e32 v43, v43, v137
	v_mul_f32_e32 v36, v36, v208
	v_mul_f32_e32 v37, v37, v138
	v_mul_f32_e32 v38, v38, v210
	v_mul_f32_e32 v39, v39, v139
	s_waitcnt vmcnt(0)
;     __device__ __forceinline__ void mid(f32x4 (&acc)[2][2][4][2], const Unit& u, int wr, int wc, int fr, int fq) const {
;         const int row0 = u.pm * BM + wr * 64 + fr, col0 = u.pn * BM + wc * 32 + 8 * fq;
; #pragma unroll
;         for (int ai = 0; ai < 2; ++ai)
; #pragma unroll
;             for (int m = 0; m < 4; ++m) { const bf16_t* prow = P + (size_t)(row0 + ai * HALF + m * 16) * DP;
; #pragma unroll
;                 for (int bj = 0; bj < 2; ++bj) { const int c = col0 + bj * HALF;
;                     float ga[8], gb[8]; unpack8(__builtin_nontemporal_load((const u32x4*)(prow + C_MA + c)), ga); unpack8(*(const u32x4*)(prow + C_MB + c), gb);
; #pragma unroll
;                     for (int e = 0; e < 4; ++e) { acc[ai][bj][m][0][e] *= (1.0f + __expf(-gb[e])) * __builtin_amdgcn_rcpf(1.0f + __expf(-ga[e]));
;                                                   acc[ai][bj][m][1][e] *= (1.0f + __expf(-gb[4 + e])) * __builtin_amdgcn_rcpf(1.0f + __expf(-ga[4 + e])); } }
;                 asm volatile("" ::: "memory"); }
; template <class Epi, bool ALIGN_EPI = true, bool SP2 = true>
; __device__ __forceinline__ void gemm_phase(LAS unsigned char* lds, const Gemm g, const Order& S, const Epi& E) {
;     ...
;         if (!chained) {
; #pragma unroll
;         for (int a = 0; a < 2; ++a)
; #pragma unroll
;             for (int b = 0; b < 2; ++b)
; #pragma unroll
;                 for (int m = 0; m < 4; ++m)
; #pragma unroll
;                     for (int n = 0; n < 2; ++n) acc[a][b][m][n] = (f32x4){0.f, 0.f, 0.f, 0.f};
	v_lshlrev_b32_e32 v174, 16, v228
	v_lshlrev_b32_e32 v175, 16, v229
	v_lshlrev_b32_e32 v176, 16, v230
	v_lshlrev_b32_e32 v177, 16, v231
	v_and_b32_e32 v228, 0xffff0000, v228
	v_and_b32_e32 v229, 0xffff0000, v229
	v_and_b32_e32 v230, 0xffff0000, v230
	v_and_b32_e32 v231, 0xffff0000, v231
	v_lshlrev_b32_e32 v205, 16, v170
	v_lshlrev_b32_e32 v206, 16, v171
	v_lshlrev_b32_e32 v208, 16, v172
	v_lshlrev_b32_e32 v210, 16, v173
	v_and_b32_e32 v170, 0xffff0000, v170
	v_and_b32_e32 v171, 0xffff0000, v171
	v_and_b32_e32 v172, 0xffff0000, v172
	v_and_b32_e32 v173, 0xffff0000, v173
	v_mul_f32_e32 v174, 0xbfb8aa3b, v174
	v_mul_f32_e32 v228, 0xbfb8aa3b, v228
	v_mul_f32_e32 v175, 0xbfb8aa3b, v175
	v_mul_f32_e32 v229, 0xbfb8aa3b, v229
	v_mul_f32_e32 v176, 0xbfb8aa3b, v176
	v_mul_f32_e32 v230, 0xbfb8aa3b, v230
	v_mul_f32_e32 v177, 0xbfb8aa3b, v177
	v_mul_f32_e32 v231, 0xbfb8aa3b, v231
	v_mul_f32_e32 v205, 0xbfb8aa3b, v205
	v_mul_f32_e32 v170, 0xbfb8aa3b, v170
	v_mul_f32_e32 v206, 0xbfb8aa3b, v206
	v_mul_f32_e32 v171, 0xbfb8aa3b, v171
	v_mul_f32_e32 v208, 0xbfb8aa3b, v208
	v_mul_f32_e32 v172, 0xbfb8aa3b, v172
	v_mul_f32_e32 v210, 0xbfb8aa3b, v210
	v_mul_f32_e32 v173, 0xbfb8aa3b, v173
	v_exp_f32_e32 v174, v174
	v_exp_f32_e32 v228, v228
	v_exp_f32_e32 v175, v175
	v_exp_f32_e32 v229, v229
	v_exp_f32_e32 v176, v176
	v_exp_f32_e32 v230, v230
	v_exp_f32_e32 v177, v177
	v_exp_f32_e32 v231, v231
	v_exp_f32_e32 v205, v205
	v_exp_f32_e32 v170, v170
	v_exp_f32_e32 v206, v206
	v_exp_f32_e32 v171, v171
	v_exp_f32_e32 v208, v208
	v_exp_f32_e32 v172, v172
	v_exp_f32_e32 v210, v210
	v_exp_f32_e32 v173, v173
	v_add_f32_e32 v174, 1.0, v174
	v_add_f32_e32 v228, 1.0, v228
	v_add_f32_e32 v175, 1.0, v175
	v_add_f32_e32 v229, 1.0, v229
	v_add_f32_e32 v176, 1.0, v176
	v_add_f32_e32 v230, 1.0, v230
	v_add_f32_e32 v177, 1.0, v177
	v_add_f32_e32 v231, 1.0, v231
	v_add_f32_e32 v205, 1.0, v205
	v_add_f32_e32 v170, 1.0, v170
	v_add_f32_e32 v206, 1.0, v206
	v_add_f32_e32 v171, 1.0, v171
	v_add_f32_e32 v208, 1.0, v208
	v_add_f32_e32 v172, 1.0, v172
	v_add_f32_e32 v210, 1.0, v210
	v_add_f32_e32 v173, 1.0, v173
	v_rcp_f32_e32 v174, v174
	v_rcp_f32_e32 v228, v228
	v_rcp_f32_e32 v175, v175
	v_rcp_f32_e32 v229, v229
	v_rcp_f32_e32 v176, v176
	v_rcp_f32_e32 v230, v230
	v_rcp_f32_e32 v177, v177
	v_rcp_f32_e32 v231, v231
	v_mul_f32_e32 v205, v205, v174
	v_mul_f32_e32 v170, v170, v228
	v_mul_f32_e32 v206, v206, v175
	v_mul_f32_e32 v171, v171, v229
	v_mul_f32_e32 v208, v208, v176
	v_mul_f32_e32 v172, v172, v230
	v_mul_f32_e32 v210, v210, v177
	v_mul_f32_e32 v173, v173, v231
	v_mul_f32_e32 v8, v8, v205
	v_mul_f32_e32 v9, v9, v170
	v_mul_f32_e32 v10, v10, v206
	v_mul_f32_e32 v11, v11, v171
	v_mul_f32_e32 v4, v4, v208
	v_mul_f32_e32 v5, v5, v172
	v_mul_f32_e32 v6, v6, v210
	v_mul_f32_e32 v7, v7, v173
	s_branch .LBB0_579
.LBB0_579:
	s_and_b64 vcc, exec, s[6:7]
	s_mov_b64 s[4:5], -1
	s_cbranch_vccnz .LBB0_494
	s_branch .LBB0_582
.LBB0_582:
	s_andn2_b64 vcc, exec, s[64:65]
	s_cbranch_vccnz .LBB0_584
	v_mov_b32_e32 v2, v1
	v_mov_b32_e32 v3, v1
	v_mov_b32_e32 v0, v1
	v_mov_b64_e32 v[6:7], v[2:3]
	v_mov_b64_e32 v[10:11], v[2:3]
	v_mov_b64_e32 v[14:15], v[2:3]
	v_mov_b64_e32 v[18:19], v[2:3]
	v_mov_b64_e32 v[22:23], v[2:3]
	v_mov_b64_e32 v[26:27], v[2:3]
	v_mov_b64_e32 v[30:31], v[2:3]
	v_mov_b64_e32 v[34:35], v[2:3]
	v_mov_b64_e32 v[38:39], v[2:3]
	v_mov_b64_e32 v[42:43], v[2:3]
	v_mov_b64_e32 v[46:47], v[2:3]
	v_mov_b64_e32 v[50:51], v[2:3]
	v_mov_b64_e32 v[54:55], v[2:3]
	v_mov_b64_e32 v[58:59], v[2:3]
	v_mov_b64_e32 v[62:63], v[2:3]
	v_mov_b64_e32 v[66:67], v[2:3]
	v_mov_b64_e32 v[70:71], v[2:3]
	v_mov_b64_e32 v[74:75], v[2:3]
	v_mov_b64_e32 v[78:79], v[2:3]
	v_mov_b64_e32 v[82:83], v[2:3]
	v_mov_b64_e32 v[86:87], v[2:3]
	v_mov_b64_e32 v[90:91], v[2:3]
	v_mov_b64_e32 v[94:95], v[2:3]
	v_mov_b64_e32 v[98:99], v[2:3]
	v_mov_b64_e32 v[102:103], v[2:3]
	v_mov_b64_e32 v[106:107], v[2:3]
	v_mov_b64_e32 v[110:111], v[2:3]
	v_mov_b64_e32 v[114:115], v[2:3]
	v_mov_b64_e32 v[118:119], v[2:3]
	v_mov_b64_e32 v[122:123], v[2:3]
	v_mov_b64_e32 v[126:127], v[2:3]
	v_mov_b64_e32 v[130:131], v[2:3]
	v_mov_b64_e32 v[4:5], v[0:1]
	v_mov_b64_e32 v[8:9], v[0:1]
	v_mov_b64_e32 v[12:13], v[0:1]
	v_mov_b64_e32 v[16:17], v[0:1]
	v_mov_b64_e32 v[20:21], v[0:1]
	v_mov_b64_e32 v[24:25], v[0:1]
	v_mov_b64_e32 v[28:29], v[0:1]
	v_mov_b64_e32 v[32:33], v[0:1]
	v_mov_b64_e32 v[36:37], v[0:1]
	v_mov_b64_e32 v[40:41], v[0:1]
	v_mov_b64_e32 v[44:45], v[0:1]
	v_mov_b64_e32 v[48:49], v[0:1]
	v_mov_b64_e32 v[52:53], v[0:1]
	v_mov_b64_e32 v[56:57], v[0:1]
	v_mov_b64_e32 v[60:61], v[0:1]
	v_mov_b64_e32 v[64:65], v[0:1]
	v_mov_b64_e32 v[68:69], v[0:1]
	v_mov_b64_e32 v[72:73], v[0:1]
	v_mov_b64_e32 v[76:77], v[0:1]
	v_mov_b64_e32 v[80:81], v[0:1]
	v_mov_b64_e32 v[84:85], v[0:1]
	v_mov_b64_e32 v[88:89], v[0:1]
	v_mov_b64_e32 v[92:93], v[0:1]
	v_mov_b64_e32 v[96:97], v[0:1]
	v_mov_b64_e32 v[100:101], v[0:1]
	v_mov_b64_e32 v[104:105], v[0:1]
	v_mov_b64_e32 v[108:109], v[0:1]
	v_mov_b64_e32 v[112:113], v[0:1]
	v_mov_b64_e32 v[116:117], v[0:1]
	v_mov_b64_e32 v[120:121], v[0:1]
	v_mov_b64_e32 v[124:125], v[0:1]
	v_mov_b64_e32 v[128:129], v[0:1]
